# scan waves load decay vector w from global DEC via 8-deep VGPR ring instead of LDS (on top of conversion move)
# speedup vs baseline: 1.0039x; 1.0010x over previous
.LBB0_831:
	v_readlane_b32 s28, v255, 5
	s_and_b64 vcc, exec, s[8:9]
	v_readlane_b32 s31, v255, 8
	v_readlane_b32 s29, v255, 6
	v_readlane_b32 s30, v255, 7
	s_cbranch_vccz .LBB0_834
	s_bfe_u32 s4, s44, 0x20006
	s_lshl_b32 s5, s4, 5
	s_add_i32 s5, s5, 0
	s_mul_i32 s6, s4, 0x1e0
	s_lshl_b32 s4, s4, 9
	v_lshl_add_u32 v110, v165, 2, s5
	s_add_i32 s5, s5, s6
	v_lshlrev_b32_e32 v2, 2, v166
	s_add_i32 s4, s4, 0
	v_add_u32_e32 v111, s5, v2
	s_add_i32 s4, s4, 0x13000
	s_waitcnt vmcnt(8)
	v_mov_b32_e32 v24, 0
	v_add_u32_e32 v112, 0xb000, v111
	v_add_u32_e32 v113, s4, v2
	s_mov_b32 s4, -4
	v_mov_b32_e32 v25, v24
	v_mov_b32_e32 v22, v24
	v_mov_b32_e32 v23, v24
	v_mov_b32_e32 v6, v24
	v_mov_b32_e32 v7, v24
	v_mov_b32_e32 v8, v24
	v_mov_b32_e32 v9, v24
	s_lshr_b32 s58, s10, 2
	s_lshl_b32 s58, s58, 8
	s_add_u32 s56, s92, s58
	s_addc_u32 s57, s93, 0
	s_add_u32 s56, s56, 0x37800000
	s_addc_u32 s57, s57, 0
	s_movk_i32 s58, 0x2000
	s_mov_b32 s59, 0
	s_bitcmp1_b32 s10, 1
	s_cbranch_scc0 .Lw_fwd
	s_add_u32 s56, s56, 0x7ffe000
	s_addc_u32 s57, s57, 0
	s_mov_b32 s58, 0xffffe000
	s_mov_b32 s59, -1
.Lw_fwd:
	global_load_dwordx4 v[192:195], v118, s[56:57]
	s_add_u32 s56, s56, s58
	s_addc_u32 s57, s57, s59
	global_load_dwordx4 v[196:199], v118, s[56:57]
	s_add_u32 s56, s56, s58
	s_addc_u32 s57, s57, s59
	global_load_dwordx4 v[200:203], v118, s[56:57]
	s_add_u32 s56, s56, s58
	s_addc_u32 s57, s57, s59
	global_load_dwordx4 v[204:207], v118, s[56:57]
	s_add_u32 s56, s56, s58
	s_addc_u32 s57, s57, s59
.LBB0_833:
	ds_read_b128 v[34:37], v118
	global_load_dwordx4 v[208:211], v118, s[56:57]
	s_add_u32 s56, s56, s58
	s_addc_u32 s57, s57, s59
	ds_read_b128 v[42:45], v118 offset:512
	ds_read_b128 v[54:57], v118 offset:768
	ds_read_b128 v[58:61], v118 offset:1024
	s_waitcnt lgkmcnt(3)
	v_pk_mul_f32 v[64:65], v[22:23], v[36:37]
	v_pk_mul_f32 v[36:37], v[8:9], v[36:37]
	v_pk_fma_f32 v[64:65], v[24:25], v[34:35], v[64:65]
	v_pk_fma_f32 v[34:35], v[6:7], v[34:35], v[36:37]
	v_add_f32_e32 v36, v64, v65
	v_add_f32_e32 v34, v34, v35
	v_add_u32_e32 v121, 0xa000, v110
	v_add_f32_dpp v36, v36, v36 row_ror:8 row_mask:0xf bank_mask:0xf bound_ctrl:1
	v_add_f32_dpp v34, v34, v34 row_ror:8 row_mask:0xf bank_mask:0xf bound_ctrl:1
	ds_read2_b32 v[62:63], v121 offset1:4
	ds_read_b128 v[66:69], v118 offset:1280
	global_load_dwordx4 v[212:215], v118, s[56:57]
	s_add_u32 s56, s56, s58
	s_addc_u32 s57, s57, s59
	ds_read_b128 v[90:93], v118 offset:1792
	ds_read_b128 v[94:97], v118 offset:2048
	ds_read_b128 v[102:105], v118 offset:2304
	ds_read2_b32 v[98:99], v121 offset0:32 offset1:36
	ds_read_b128 v[78:81], v118 offset:2560
	global_load_dwordx4 v[216:219], v118, s[56:57]
	s_add_u32 s56, s56, s58
	s_addc_u32 s57, s57, s59
	ds_read_b128 v[46:49], v118 offset:3072
	ds_read_b128 v[50:53], v118 offset:3328
	ds_read_b128 v[10:13], v118 offset:3584
	ds_read2_b32 v[84:85], v121 offset0:64 offset1:68
	ds_read_b128 v[70:73], v118 offset:3840
	global_load_dwordx4 v[220:223], v118, s[56:57]
	s_add_u32 s56, s56, s58
	s_addc_u32 s57, s57, s59
	ds_read_b128 v[26:29], v118 offset:4352
	ds_read_b128 v[30:33], v118 offset:4608
	ds_read_b128 v[2:5], v118 offset:4864
	ds_read2_b32 v[82:83], v121 offset0:96 offset1:100
	v_add_f32_dpp v36, v36, v36 row_ror:4 row_mask:0xf bank_mask:0xf bound_ctrl:1
	v_add_f32_dpp v34, v34, v34 row_ror:4 row_mask:0xf bank_mask:0xf bound_ctrl:1
	s_waitcnt lgkmcnt(12)
	v_mov_b32_e32 v64, v63
	v_add_f32_dpp v36, v36, v36 row_ror:2 row_mask:0xf bank_mask:0xf bound_ctrl:1
	v_add_f32_dpp v34, v34, v34 row_ror:2 row_mask:0xf bank_mask:0xf bound_ctrl:1
	v_add_u32_e32 v117, 0xa400, v110
	v_add_f32_dpp v36, v36, v36 row_ror:1 row_mask:0xf bank_mask:0xf bound_ctrl:1
	v_pk_mul_f32 v[74:75], v[42:43], v[36:37] op_sel_hi:[1,0]
	v_add_f32_dpp v34, v34, v34 row_ror:1 row_mask:0xf bank_mask:0xf bound_ctrl:1
	v_pk_fma_f32 v[74:75], v[54:55], v[62:63], v[74:75] op_sel_hi:[1,0,1]
	v_add_u32_e32 v120, 0xa800, v110
	s_waitcnt vmcnt(7)
	v_pk_fma_f32 v[106:107], v[24:25], v[192:193], v[74:75]
	v_pk_mul_f32 v[24:25], v[44:45], v[36:37] op_sel_hi:[1,0]
	v_add_u32_e32 v114, 0xac00, v110
	v_pk_fma_f32 v[24:25], v[56:57], v[62:63], v[24:25] op_sel_hi:[1,0,1]
	s_add_i32 s4, s4, 4
	v_pk_fma_f32 v[36:37], v[22:23], v[194:195], v[24:25]
	v_pk_mul_f32 v[22:23], v[42:43], v[34:35] op_sel_hi:[1,0]
	s_cmpk_gt_u32 s4, 0x1fb
	v_pk_fma_f32 v[22:23], v[54:55], v[64:65], v[22:23] op_sel_hi:[1,0,1]
	s_nop 0
	v_pk_fma_f32 v[42:43], v[6:7], v[192:193], v[22:23]
	v_pk_mul_f32 v[6:7], v[44:45], v[34:35] op_sel_hi:[1,0]
	v_pk_mul_f32 v[44:45], v[68:69], v[36:37]
	v_pk_fma_f32 v[6:7], v[56:57], v[64:65], v[6:7] op_sel_hi:[1,0,1]
	v_pk_fma_f32 v[44:45], v[66:67], v[106:107], v[44:45]
	v_pk_fma_f32 v[34:35], v[8:9], v[194:195], v[6:7]
	v_add_f32_e32 v44, v44, v45
	v_pk_mul_f32 v[54:55], v[68:69], v[34:35]
	v_pk_mul_f32 v[6:7], v[60:61], v[36:37]
	v_pk_fma_f32 v[54:55], v[66:67], v[42:43], v[54:55]
	v_add_f32_dpp v44, v44, v44 row_ror:8 row_mask:0xf bank_mask:0xf bound_ctrl:1
	v_add_f32_e32 v45, v54, v55
	v_pk_mul_f32 v[8:9], v[60:61], v[34:35]
	v_add_f32_dpp v44, v44, v44 row_ror:4 row_mask:0xf bank_mask:0xf bound_ctrl:1
	v_add_f32_dpp v45, v45, v45 row_ror:8 row_mask:0xf bank_mask:0xf bound_ctrl:1
	v_pk_fma_f32 v[6:7], v[58:59], v[106:107], v[6:7]
	v_add_f32_dpp v44, v44, v44 row_ror:2 row_mask:0xf bank_mask:0xf bound_ctrl:1
	v_add_f32_dpp v45, v45, v45 row_ror:4 row_mask:0xf bank_mask:0xf bound_ctrl:1
	v_pk_fma_f32 v[8:9], v[58:59], v[42:43], v[8:9]
	v_add_f32_dpp v44, v44, v44 row_ror:1 row_mask:0xf bank_mask:0xf bound_ctrl:1
	v_add_f32_dpp v45, v45, v45 row_ror:2 row_mask:0xf bank_mask:0xf bound_ctrl:1
	v_pk_mul_f32 v[58:59], v[90:91], v[44:45] op_sel_hi:[1,0]
	s_waitcnt lgkmcnt(10)
	v_mov_b32_e32 v56, v99
	v_add_f32_dpp v54, v45, v45 row_ror:1 row_mask:0xf bank_mask:0xf bound_ctrl:1
	v_pk_mul_f32 v[44:45], v[92:93], v[44:45] op_sel_hi:[1,0]
	v_pk_fma_f32 v[58:59], v[94:95], v[98:99], v[58:59] op_sel_hi:[1,0,1]
	v_pk_fma_f32 v[44:45], v[96:97], v[98:99], v[44:45] op_sel_hi:[1,0,1]
	s_waitcnt vmcnt(6)
	v_pk_fma_f32 v[106:107], v[196:197], v[106:107], v[58:59]
	v_pk_fma_f32 v[108:109], v[198:199], v[36:37], v[44:45]
	v_pk_mul_f32 v[36:37], v[90:91], v[54:55] op_sel_hi:[1,0]
	s_waitcnt lgkmcnt(9)
	v_pk_mul_f32 v[90:91], v[80:81], v[108:109]
	v_pk_fma_f32 v[36:37], v[94:95], v[56:57], v[36:37] op_sel_hi:[1,0,1]
	v_pk_fma_f32 v[90:91], v[78:79], v[106:107], v[90:91]
	v_pk_fma_f32 v[86:87], v[196:197], v[42:43], v[36:37]
	v_pk_mul_f32 v[36:37], v[92:93], v[54:55] op_sel_hi:[1,0]
	v_add_f32_e32 v6, v6, v7
	v_pk_fma_f32 v[36:37], v[96:97], v[56:57], v[36:37] op_sel_hi:[1,0,1]
	v_add_f32_e32 v7, v8, v9
	v_pk_fma_f32 v[88:89], v[198:199], v[34:35], v[36:37]
	v_pk_mul_f32 v[34:35], v[104:105], v[108:109]
	v_pk_mul_f32 v[80:81], v[80:81], v[88:89]
	v_pk_mul_f32 v[36:37], v[104:105], v[88:89]
	v_pk_fma_f32 v[78:79], v[78:79], v[86:87], v[80:81]
	v_add_f32_e32 v80, v90, v91
	v_add_f32_e32 v78, v78, v79
	s_waitcnt lgkmcnt(5)
	v_mov_b32_e32 v90, v85
	v_add_f32_dpp v80, v80, v80 row_ror:8 row_mask:0xf bank_mask:0xf bound_ctrl:1
	v_add_f32_dpp v78, v78, v78 row_ror:8 row_mask:0xf bank_mask:0xf bound_ctrl:1
	v_pk_fma_f32 v[36:37], v[102:103], v[86:87], v[36:37]
	v_add_f32_dpp v80, v80, v80 row_ror:4 row_mask:0xf bank_mask:0xf bound_ctrl:1
	v_add_f32_dpp v78, v78, v78 row_ror:4 row_mask:0xf bank_mask:0xf bound_ctrl:1
	v_pk_fma_f32 v[34:35], v[102:103], v[106:107], v[34:35]
	v_add_f32_dpp v80, v80, v80 row_ror:2 row_mask:0xf bank_mask:0xf bound_ctrl:1
	v_add_f32_dpp v78, v78, v78 row_ror:2 row_mask:0xf bank_mask:0xf bound_ctrl:1
	ds_write2st64_b32 v111, v6, v7 offset0:176 offset1:177
	v_add_f32_dpp v80, v80, v80 row_ror:1 row_mask:0xf bank_mask:0xf bound_ctrl:1
	v_add_f32_dpp v78, v78, v78 row_ror:1 row_mask:0xf bank_mask:0xf bound_ctrl:1
	v_pk_mul_f32 v[92:93], v[46:47], v[80:81] op_sel_hi:[1,0]
	v_pk_mul_f32 v[46:47], v[46:47], v[78:79] op_sel_hi:[1,0]
	v_pk_fma_f32 v[92:93], v[50:51], v[84:85], v[92:93] op_sel_hi:[1,0,1]
	v_pk_mul_f32 v[80:81], v[48:49], v[80:81] op_sel_hi:[1,0]
	v_pk_fma_f32 v[46:47], v[50:51], v[90:91], v[46:47] op_sel_hi:[1,0,1]
	s_waitcnt vmcnt(5)
	v_pk_fma_f32 v[94:95], v[200:201], v[106:107], v[92:93]
	v_pk_fma_f32 v[80:81], v[52:53], v[84:85], v[80:81] op_sel_hi:[1,0,1]
	v_pk_fma_f32 v[84:85], v[200:201], v[86:87], v[46:47]
	v_pk_mul_f32 v[18:19], v[48:49], v[78:79] op_sel_hi:[1,0]
	v_pk_fma_f32 v[80:81], v[202:203], v[108:109], v[80:81]
	v_pk_fma_f32 v[18:19], v[52:53], v[90:91], v[18:19] op_sel_hi:[1,0,1]
	s_waitcnt lgkmcnt(5)
	v_pk_mul_f32 v[86:87], v[72:73], v[80:81]
	v_pk_fma_f32 v[78:79], v[202:203], v[88:89], v[18:19]
	v_pk_fma_f32 v[86:87], v[70:71], v[94:95], v[86:87]
	v_pk_mul_f32 v[72:73], v[72:73], v[78:79]
	v_pk_mul_f32 v[18:19], v[12:13], v[80:81]
	v_pk_fma_f32 v[70:71], v[70:71], v[84:85], v[72:73]
	v_add_f32_e32 v72, v86, v87
	v_add_f32_e32 v70, v70, v71
	s_waitcnt lgkmcnt(1)
	v_mov_b32_e32 v86, v83
	v_add_f32_dpp v72, v72, v72 row_ror:8 row_mask:0xf bank_mask:0xf bound_ctrl:1
	v_add_f32_dpp v70, v70, v70 row_ror:8 row_mask:0xf bank_mask:0xf bound_ctrl:1
	v_pk_mul_f32 v[12:13], v[12:13], v[78:79]
	v_add_f32_dpp v72, v72, v72 row_ror:4 row_mask:0xf bank_mask:0xf bound_ctrl:1
	v_add_f32_dpp v70, v70, v70 row_ror:4 row_mask:0xf bank_mask:0xf bound_ctrl:1
	v_add_f32_e32 v34, v34, v35
	v_add_f32_dpp v72, v72, v72 row_ror:2 row_mask:0xf bank_mask:0xf bound_ctrl:1
	v_add_f32_dpp v70, v70, v70 row_ror:2 row_mask:0xf bank_mask:0xf bound_ctrl:1
	v_add_f32_e32 v35, v36, v37
	v_add_f32_dpp v72, v72, v72 row_ror:1 row_mask:0xf bank_mask:0xf bound_ctrl:1
	v_add_f32_dpp v70, v70, v70 row_ror:1 row_mask:0xf bank_mask:0xf bound_ctrl:1
	v_pk_mul_f32 v[88:89], v[26:27], v[72:73] op_sel_hi:[1,0]
	v_pk_mul_f32 v[26:27], v[26:27], v[70:71] op_sel_hi:[1,0]
	v_pk_fma_f32 v[88:89], v[30:31], v[82:83], v[88:89] op_sel_hi:[1,0,1]
	v_pk_fma_f32 v[26:27], v[30:31], v[86:87], v[26:27] op_sel_hi:[1,0,1]
	s_waitcnt vmcnt(4)
	v_pk_fma_f32 v[106:107], v[204:205], v[94:95], v[88:89]
	v_pk_mul_f32 v[72:73], v[28:29], v[72:73] op_sel_hi:[1,0]
	v_pk_fma_f32 v[26:27], v[204:205], v[84:85], v[26:27]
	v_pk_mul_f32 v[14:15], v[28:29], v[70:71] op_sel_hi:[1,0]
	v_pk_fma_f32 v[72:73], v[32:33], v[82:83], v[72:73] op_sel_hi:[1,0,1]
	v_pk_fma_f32 v[14:15], v[32:33], v[86:87], v[14:15] op_sel_hi:[1,0,1]
	v_pk_fma_f32 v[72:73], v[206:207], v[80:81], v[72:73]
	v_pk_fma_f32 v[28:29], v[206:207], v[78:79], v[14:15]
	v_pk_fma_f32 v[18:19], v[10:11], v[94:95], v[18:19]
	v_pk_fma_f32 v[10:11], v[10:11], v[84:85], v[12:13]
	v_pk_mul_f32 v[14:15], v[4:5], v[72:73]
	v_pk_mul_f32 v[4:5], v[4:5], v[28:29]
	ds_read_b128 v[74:77], v118 offset:5120
	global_load_dwordx4 v[192:195], v118, s[56:57]
	s_add_u32 s56, s56, s58
	s_addc_u32 s57, s57, s59
	ds_read_b128 v[38:41], v118 offset:5632
	ds_read_b128 v[62:65], v118 offset:5888
	ds_read_b128 v[6:9], v118 offset:6144
	ds_read2_b32 v[100:101], v121 offset0:128 offset1:132
	ds_write2st64_b32 v111, v34, v35 offset0:184 offset1:185
	v_add_f32_e32 v12, v18, v19
	v_add_f32_e32 v10, v10, v11
	v_pk_fma_f32 v[14:15], v[2:3], v[106:107], v[14:15]
	v_pk_fma_f32 v[2:3], v[2:3], v[26:27], v[4:5]
	ds_read_b128 v[66:69], v118 offset:6400
	global_load_dwordx4 v[196:199], v118, s[56:57]
	s_add_u32 s56, s56, s58
	s_addc_u32 s57, s57, s59
	ds_read_b128 v[54:57], v118 offset:6912
	ds_read_b128 v[58:61], v118 offset:7168
	ds_read_b128 v[34:37], v118 offset:7424
	ds_read2_b32 v[98:99], v121 offset0:160 offset1:164
	ds_write2st64_b32 v111, v12, v10 offset0:192 offset1:193
	v_add_f32_e32 v4, v14, v15
	v_add_f32_e32 v2, v2, v3
	ds_read_b128 v[90:93], v118 offset:7680
	global_load_dwordx4 v[200:203], v118, s[56:57]
	s_add_u32 s56, s56, s58
	s_addc_u32 s57, s57, s59
	ds_read_b128 v[46:49], v118 offset:8192
	ds_read_b128 v[50:53], v118 offset:8448
	ds_read_b128 v[10:13], v118 offset:8704
	ds_read2_b32 v[102:103], v121 offset0:192 offset1:196
	ds_write2st64_b32 v111, v4, v2 offset0:200 offset1:201
	s_waitcnt lgkmcnt(12)
	v_pk_mul_f32 v[2:3], v[76:77], v[72:73]
	v_pk_mul_f32 v[4:5], v[76:77], v[28:29]
	v_pk_fma_f32 v[2:3], v[74:75], v[106:107], v[2:3]
	v_pk_fma_f32 v[4:5], v[74:75], v[26:27], v[4:5]
	v_add_f32_e32 v2, v2, v3
	v_add_f32_e32 v3, v4, v5
	v_mov_b32_e32 v70, v101
	v_add_f32_dpp v2, v2, v2 row_ror:8 row_mask:0xf bank_mask:0xf bound_ctrl:1
	v_add_f32_dpp v3, v3, v3 row_ror:8 row_mask:0xf bank_mask:0xf bound_ctrl:1
	ds_read_b128 v[94:97], v118 offset:8960
	global_load_dwordx4 v[204:207], v118, s[56:57]
	s_add_u32 s56, s56, s58
	s_addc_u32 s57, s57, s59
	ds_read_b128 v[82:85], v118 offset:9472
	ds_read_b128 v[86:89], v118 offset:9728
	ds_read_b128 v[14:17], v118 offset:9984
	ds_read2_b32 v[104:105], v121 offset0:224 offset1:228
	v_add_f32_dpp v2, v2, v2 row_ror:4 row_mask:0xf bank_mask:0xf bound_ctrl:1
	v_add_f32_dpp v3, v3, v3 row_ror:4 row_mask:0xf bank_mask:0xf bound_ctrl:1
	s_nop 0
	v_add_f32_dpp v2, v2, v2 row_ror:2 row_mask:0xf bank_mask:0xf bound_ctrl:1
	v_add_f32_dpp v3, v3, v3 row_ror:2 row_mask:0xf bank_mask:0xf bound_ctrl:1
	s_nop 0
	v_add_f32_dpp v2, v2, v2 row_ror:1 row_mask:0xf bank_mask:0xf bound_ctrl:1
	v_add_f32_dpp v4, v3, v3 row_ror:1 row_mask:0xf bank_mask:0xf bound_ctrl:1
	v_pk_mul_f32 v[74:75], v[38:39], v[2:3] op_sel_hi:[1,0]
	v_pk_mul_f32 v[2:3], v[40:41], v[2:3] op_sel_hi:[1,0]
	v_pk_fma_f32 v[74:75], v[62:63], v[100:101], v[74:75] op_sel_hi:[1,0,1]
	v_pk_fma_f32 v[2:3], v[64:65], v[100:101], v[2:3] op_sel_hi:[1,0,1]
	s_waitcnt vmcnt(7)
	v_pk_fma_f32 v[74:75], v[208:209], v[106:107], v[74:75]
	v_pk_fma_f32 v[72:73], v[210:211], v[72:73], v[2:3]
	v_pk_mul_f32 v[2:3], v[38:39], v[4:5] op_sel_hi:[1,0]
	s_nop 0
	v_pk_fma_f32 v[2:3], v[62:63], v[70:71], v[2:3] op_sel_hi:[1,0,1]
	s_nop 0
	v_pk_fma_f32 v[62:63], v[208:209], v[26:27], v[2:3]
	v_pk_mul_f32 v[2:3], v[40:41], v[4:5] op_sel_hi:[1,0]
	s_nop 0
	v_pk_fma_f32 v[2:3], v[64:65], v[70:71], v[2:3] op_sel_hi:[1,0,1]
	s_waitcnt lgkmcnt(12)
	v_pk_mul_f32 v[70:71], v[68:69], v[72:73]
	v_pk_fma_f32 v[64:65], v[210:211], v[28:29], v[2:3]
	v_pk_fma_f32 v[70:71], v[66:67], v[74:75], v[70:71]
	v_pk_mul_f32 v[68:69], v[68:69], v[64:65]
	v_pk_mul_f32 v[2:3], v[8:9], v[72:73]
	v_pk_fma_f32 v[66:67], v[66:67], v[62:63], v[68:69]
	v_add_f32_e32 v68, v70, v71
	v_add_f32_e32 v66, v66, v67
	v_mov_b32_e32 v70, v99
	v_add_f32_dpp v68, v68, v68 row_ror:8 row_mask:0xf bank_mask:0xf bound_ctrl:1
	v_add_f32_dpp v66, v66, v66 row_ror:8 row_mask:0xf bank_mask:0xf bound_ctrl:1
	v_pk_mul_f32 v[4:5], v[8:9], v[64:65]
	v_add_f32_dpp v68, v68, v68 row_ror:4 row_mask:0xf bank_mask:0xf bound_ctrl:1
	v_add_f32_dpp v66, v66, v66 row_ror:4 row_mask:0xf bank_mask:0xf bound_ctrl:1
	v_pk_fma_f32 v[2:3], v[6:7], v[74:75], v[2:3]
	v_add_f32_dpp v68, v68, v68 row_ror:2 row_mask:0xf bank_mask:0xf bound_ctrl:1
	v_add_f32_dpp v66, v66, v66 row_ror:2 row_mask:0xf bank_mask:0xf bound_ctrl:1
	v_pk_fma_f32 v[4:5], v[6:7], v[62:63], v[4:5]
	v_add_f32_dpp v68, v68, v68 row_ror:1 row_mask:0xf bank_mask:0xf bound_ctrl:1
	v_add_f32_dpp v66, v66, v66 row_ror:1 row_mask:0xf bank_mask:0xf bound_ctrl:1
	v_pk_mul_f32 v[76:77], v[54:55], v[68:69] op_sel_hi:[1,0]
	v_pk_mul_f32 v[54:55], v[54:55], v[66:67] op_sel_hi:[1,0]
	v_pk_fma_f32 v[76:77], v[58:59], v[98:99], v[76:77] op_sel_hi:[1,0,1]
	v_pk_fma_f32 v[54:55], v[58:59], v[70:71], v[54:55] op_sel_hi:[1,0,1]
	s_waitcnt vmcnt(6)
	v_pk_fma_f32 v[106:107], v[212:213], v[74:75], v[76:77]
	v_pk_mul_f32 v[68:69], v[56:57], v[68:69] op_sel_hi:[1,0]
	v_pk_fma_f32 v[42:43], v[212:213], v[62:63], v[54:55]
	v_pk_mul_f32 v[54:55], v[56:57], v[66:67] op_sel_hi:[1,0]
	v_pk_fma_f32 v[68:69], v[60:61], v[98:99], v[68:69] op_sel_hi:[1,0,1]
	v_pk_fma_f32 v[54:55], v[60:61], v[70:71], v[54:55] op_sel_hi:[1,0,1]
	v_pk_fma_f32 v[108:109], v[214:215], v[72:73], v[68:69]
	v_pk_fma_f32 v[44:45], v[214:215], v[64:65], v[54:55]
	v_pk_mul_f32 v[54:55], v[36:37], v[108:109]
	v_pk_mul_f32 v[36:37], v[36:37], v[44:45]
	v_add_f32_e32 v2, v2, v3
	v_add_f32_e32 v3, v4, v5
	v_pk_fma_f32 v[54:55], v[34:35], v[106:107], v[54:55]
	v_pk_fma_f32 v[34:35], v[34:35], v[42:43], v[36:37]
	ds_write2st64_b32 v111, v2, v3 offset0:208 offset1:209
	v_add_f32_e32 v36, v54, v55
	v_add_f32_e32 v34, v34, v35
	ds_read_b128 v[38:41], v118 offset:10240
	global_load_dwordx4 v[208:211], v118, s[56:57]
	s_add_u32 s56, s56, s58
	s_addc_u32 s57, s57, s59
	ds_read_b128 v[22:25], v118 offset:10752
	ds_read_b128 v[26:29], v118 offset:11008
	ds_read_b128 v[2:5], v118 offset:11264
	ds_write2st64_b32 v111, v36, v34 offset0:216 offset1:217
	s_waitcnt lgkmcnt(12)
	v_pk_mul_f32 v[34:35], v[92:93], v[108:109]
	v_pk_mul_f32 v[36:37], v[92:93], v[44:45]
	v_pk_fma_f32 v[34:35], v[90:91], v[106:107], v[34:35]
	v_pk_fma_f32 v[36:37], v[90:91], v[42:43], v[36:37]
	v_add_f32_e32 v34, v34, v35
	v_add_f32_e32 v35, v36, v37
	v_mov_b32_e32 v54, v103
	v_add_f32_dpp v34, v34, v34 row_ror:8 row_mask:0xf bank_mask:0xf bound_ctrl:1
	v_add_f32_dpp v35, v35, v35 row_ror:8 row_mask:0xf bank_mask:0xf bound_ctrl:1
	ds_read2_b32 v[100:101], v117 offset1:4
	v_add_f32_dpp v34, v34, v34 row_ror:4 row_mask:0xf bank_mask:0xf bound_ctrl:1
	v_add_f32_dpp v35, v35, v35 row_ror:4 row_mask:0xf bank_mask:0xf bound_ctrl:1
	ds_read_b128 v[78:81], v118 offset:11520
	global_load_dwordx4 v[212:215], v118, s[56:57]
	s_add_u32 s56, s56, s58
	s_addc_u32 s57, s57, s59
	ds_read_b128 v[70:73], v118 offset:12032
	ds_read_b128 v[74:77], v118 offset:12288
	ds_read_b128 v[62:65], v118 offset:12544
	ds_read2_b32 v[98:99], v117 offset0:32 offset1:36
	v_add_f32_dpp v34, v34, v34 row_ror:2 row_mask:0xf bank_mask:0xf bound_ctrl:1
	v_add_f32_dpp v35, v35, v35 row_ror:2 row_mask:0xf bank_mask:0xf bound_ctrl:1
	s_nop 0
	v_add_f32_dpp v34, v34, v34 row_ror:1 row_mask:0xf bank_mask:0xf bound_ctrl:1
	v_add_f32_dpp v36, v35, v35 row_ror:1 row_mask:0xf bank_mask:0xf bound_ctrl:1
	v_pk_mul_f32 v[56:57], v[46:47], v[34:35] op_sel_hi:[1,0]
	v_pk_mul_f32 v[34:35], v[48:49], v[34:35] op_sel_hi:[1,0]
	v_pk_mul_f32 v[46:47], v[46:47], v[36:37] op_sel_hi:[1,0]
	v_pk_mul_f32 v[36:37], v[48:49], v[36:37] op_sel_hi:[1,0]
	v_pk_fma_f32 v[34:35], v[52:53], v[102:103], v[34:35] op_sel_hi:[1,0,1]
	v_pk_fma_f32 v[36:37], v[52:53], v[54:55], v[36:37] op_sel_hi:[1,0,1]
	v_pk_fma_f32 v[56:57], v[50:51], v[102:103], v[56:57] op_sel_hi:[1,0,1]
	s_waitcnt vmcnt(7)
	v_pk_fma_f32 v[34:35], v[218:219], v[108:109], v[34:35]
	v_pk_fma_f32 v[46:47], v[50:51], v[54:55], v[46:47] op_sel_hi:[1,0,1]
	v_pk_fma_f32 v[20:21], v[218:219], v[44:45], v[36:37]
	v_pk_fma_f32 v[92:93], v[216:217], v[106:107], v[56:57]
	v_pk_fma_f32 v[18:19], v[216:217], v[42:43], v[46:47]
	v_pk_mul_f32 v[36:37], v[12:13], v[34:35]
	v_pk_mul_f32 v[12:13], v[12:13], v[20:21]
	v_pk_fma_f32 v[36:37], v[10:11], v[92:93], v[36:37]
	v_pk_fma_f32 v[10:11], v[10:11], v[18:19], v[12:13]
	v_add_f32_e32 v12, v36, v37
	v_add_f32_e32 v10, v10, v11
	ds_write2st64_b32 v111, v12, v10 offset0:224 offset1:225
	s_waitcnt lgkmcnt(12)
	v_pk_mul_f32 v[10:11], v[96:97], v[34:35]
	v_pk_mul_f32 v[12:13], v[96:97], v[20:21]
	v_pk_fma_f32 v[10:11], v[94:95], v[92:93], v[10:11]
	v_pk_fma_f32 v[12:13], v[94:95], v[18:19], v[12:13]
	v_add_f32_e32 v10, v10, v11
	v_add_f32_e32 v11, v12, v13
	v_mov_b32_e32 v36, v105
	v_add_f32_dpp v10, v10, v10 row_ror:8 row_mask:0xf bank_mask:0xf bound_ctrl:1
	v_add_f32_dpp v11, v11, v11 row_ror:8 row_mask:0xf bank_mask:0xf bound_ctrl:1
	s_waitcnt lgkmcnt(6)
	v_mov_b32_e32 v102, v101
	v_add_f32_dpp v10, v10, v10 row_ror:4 row_mask:0xf bank_mask:0xf bound_ctrl:1
	v_add_f32_dpp v11, v11, v11 row_ror:4 row_mask:0xf bank_mask:0xf bound_ctrl:1
	ds_read_b128 v[58:61], v118 offset:12800
	global_load_dwordx4 v[216:219], v118, s[56:57]
	s_add_u32 s56, s56, s58
	s_addc_u32 s57, s57, s59
	ds_read_b128 v[50:53], v118 offset:13312
	ds_read_b128 v[54:57], v118 offset:13568
	ds_read_b128 v[42:45], v118 offset:13824
	ds_read2_b32 v[90:91], v117 offset0:64 offset1:68
	v_add_f32_dpp v10, v10, v10 row_ror:2 row_mask:0xf bank_mask:0xf bound_ctrl:1
	v_add_f32_dpp v11, v11, v11 row_ror:2 row_mask:0xf bank_mask:0xf bound_ctrl:1
	s_nop 0
	v_add_f32_dpp v10, v10, v10 row_ror:1 row_mask:0xf bank_mask:0xf bound_ctrl:1
	v_add_f32_dpp v12, v11, v11 row_ror:1 row_mask:0xf bank_mask:0xf bound_ctrl:1
	v_pk_mul_f32 v[94:95], v[82:83], v[10:11] op_sel_hi:[1,0]
	v_pk_mul_f32 v[10:11], v[84:85], v[10:11] op_sel_hi:[1,0]
	v_pk_fma_f32 v[94:95], v[86:87], v[104:105], v[94:95] op_sel_hi:[1,0,1]
	v_pk_fma_f32 v[10:11], v[88:89], v[104:105], v[10:11] op_sel_hi:[1,0,1]
	s_waitcnt vmcnt(7)
	v_pk_fma_f32 v[92:93], v[220:221], v[92:93], v[94:95]
	v_pk_fma_f32 v[94:95], v[222:223], v[34:35], v[10:11]
	v_pk_mul_f32 v[10:11], v[82:83], v[12:13] op_sel_hi:[1,0]
	s_nop 0
	v_pk_fma_f32 v[10:11], v[86:87], v[36:37], v[10:11] op_sel_hi:[1,0,1]
	v_pk_mul_f32 v[86:87], v[40:41], v[94:95]
	v_pk_fma_f32 v[96:97], v[220:221], v[18:19], v[10:11]
	v_pk_mul_f32 v[10:11], v[84:85], v[12:13] op_sel_hi:[1,0]
	v_pk_fma_f32 v[86:87], v[38:39], v[92:93], v[86:87]
	v_pk_fma_f32 v[10:11], v[88:89], v[36:37], v[10:11] op_sel_hi:[1,0,1]
	s_nop 0
	v_pk_fma_f32 v[84:85], v[222:223], v[20:21], v[10:11]
	v_pk_mul_f32 v[10:11], v[16:17], v[94:95]
	v_pk_mul_f32 v[40:41], v[40:41], v[84:85]
	v_pk_fma_f32 v[10:11], v[14:15], v[92:93], v[10:11]
	v_pk_fma_f32 v[38:39], v[38:39], v[96:97], v[40:41]
	v_add_f32_e32 v40, v86, v87
	v_add_f32_e32 v38, v38, v39
	v_pk_mul_f32 v[12:13], v[16:17], v[84:85]
	v_add_f32_dpp v40, v40, v40 row_ror:8 row_mask:0xf bank_mask:0xf bound_ctrl:1
	v_add_f32_dpp v38, v38, v38 row_ror:8 row_mask:0xf bank_mask:0xf bound_ctrl:1
	v_pk_fma_f32 v[12:13], v[14:15], v[96:97], v[12:13]
	v_add_f32_dpp v40, v40, v40 row_ror:4 row_mask:0xf bank_mask:0xf bound_ctrl:1
	v_add_f32_dpp v38, v38, v38 row_ror:4 row_mask:0xf bank_mask:0xf bound_ctrl:1
	v_add_f32_e32 v10, v10, v11
	v_add_f32_dpp v40, v40, v40 row_ror:2 row_mask:0xf bank_mask:0xf bound_ctrl:1
	v_add_f32_dpp v38, v38, v38 row_ror:2 row_mask:0xf bank_mask:0xf bound_ctrl:1
	v_add_f32_e32 v11, v12, v13
	v_add_f32_dpp v40, v40, v40 row_ror:1 row_mask:0xf bank_mask:0xf bound_ctrl:1
	v_add_f32_dpp v38, v38, v38 row_ror:1 row_mask:0xf bank_mask:0xf bound_ctrl:1
	v_pk_mul_f32 v[86:87], v[22:23], v[40:41] op_sel_hi:[1,0]
	v_pk_mul_f32 v[22:23], v[22:23], v[38:39] op_sel_hi:[1,0]
	v_pk_fma_f32 v[86:87], v[26:27], v[100:101], v[86:87] op_sel_hi:[1,0,1]
	v_pk_fma_f32 v[22:23], v[26:27], v[102:103], v[22:23] op_sel_hi:[1,0,1]
	s_waitcnt vmcnt(6)
	v_pk_fma_f32 v[86:87], v[192:193], v[92:93], v[86:87]
	v_pk_mul_f32 v[40:41], v[24:25], v[40:41] op_sel_hi:[1,0]
	v_pk_fma_f32 v[92:93], v[192:193], v[96:97], v[22:23]
	v_pk_mul_f32 v[6:7], v[24:25], v[38:39] op_sel_hi:[1,0]
	v_pk_fma_f32 v[40:41], v[28:29], v[100:101], v[40:41] op_sel_hi:[1,0,1]
	v_pk_fma_f32 v[6:7], v[28:29], v[102:103], v[6:7] op_sel_hi:[1,0,1]
	v_pk_fma_f32 v[88:89], v[194:195], v[94:95], v[40:41]
	v_pk_fma_f32 v[94:95], v[194:195], v[84:85], v[6:7]
	s_waitcnt lgkmcnt(10)
	v_pk_mul_f32 v[96:97], v[80:81], v[88:89]
	v_pk_mul_f32 v[80:81], v[80:81], v[94:95]
	v_pk_fma_f32 v[96:97], v[78:79], v[86:87], v[96:97]
	v_pk_fma_f32 v[78:79], v[78:79], v[92:93], v[80:81]
	v_add_f32_e32 v80, v96, v97
	v_add_f32_e32 v78, v78, v79
	s_waitcnt lgkmcnt(6)
	v_mov_b32_e32 v100, v99
	v_add_f32_dpp v80, v80, v80 row_ror:8 row_mask:0xf bank_mask:0xf bound_ctrl:1
	v_add_f32_dpp v78, v78, v78 row_ror:8 row_mask:0xf bank_mask:0xf bound_ctrl:1
	v_pk_mul_f32 v[6:7], v[4:5], v[88:89]
	v_add_f32_dpp v80, v80, v80 row_ror:4 row_mask:0xf bank_mask:0xf bound_ctrl:1
	v_add_f32_dpp v78, v78, v78 row_ror:4 row_mask:0xf bank_mask:0xf bound_ctrl:1
	v_pk_mul_f32 v[4:5], v[4:5], v[94:95]
	v_add_f32_dpp v80, v80, v80 row_ror:2 row_mask:0xf bank_mask:0xf bound_ctrl:1
	v_add_f32_dpp v78, v78, v78 row_ror:2 row_mask:0xf bank_mask:0xf bound_ctrl:1
	v_pk_fma_f32 v[6:7], v[2:3], v[86:87], v[6:7]
	v_add_f32_dpp v80, v80, v80 row_ror:1 row_mask:0xf bank_mask:0xf bound_ctrl:1
	v_add_f32_dpp v78, v78, v78 row_ror:1 row_mask:0xf bank_mask:0xf bound_ctrl:1
	v_pk_mul_f32 v[96:97], v[70:71], v[80:81] op_sel_hi:[1,0]
	v_pk_mul_f32 v[70:71], v[70:71], v[78:79] op_sel_hi:[1,0]
	v_pk_fma_f32 v[96:97], v[74:75], v[98:99], v[96:97] op_sel_hi:[1,0,1]
	v_pk_mul_f32 v[80:81], v[72:73], v[80:81] op_sel_hi:[1,0]
	v_pk_fma_f32 v[70:71], v[74:75], v[100:101], v[70:71] op_sel_hi:[1,0,1]
	s_waitcnt vmcnt(5)
	v_pk_fma_f32 v[96:97], v[196:197], v[86:87], v[96:97]
	v_pk_fma_f32 v[80:81], v[76:77], v[98:99], v[80:81] op_sel_hi:[1,0,1]
	v_pk_fma_f32 v[98:99], v[196:197], v[92:93], v[70:71]
	v_pk_mul_f32 v[66:67], v[72:73], v[78:79] op_sel_hi:[1,0]
	v_pk_fma_f32 v[88:89], v[198:199], v[88:89], v[80:81]
	v_pk_fma_f32 v[66:67], v[76:77], v[100:101], v[66:67] op_sel_hi:[1,0,1]
	v_pk_fma_f32 v[2:3], v[2:3], v[92:93], v[4:5]
	v_pk_fma_f32 v[100:101], v[198:199], v[94:95], v[66:67]
	s_waitcnt lgkmcnt(4)
	v_pk_mul_f32 v[92:93], v[60:61], v[88:89]
	v_pk_mul_f32 v[60:61], v[60:61], v[100:101]
	v_pk_fma_f32 v[92:93], v[58:59], v[96:97], v[92:93]
	v_pk_fma_f32 v[58:59], v[58:59], v[98:99], v[60:61]
	v_add_f32_e32 v60, v92, v93
	v_add_f32_e32 v58, v58, v59
	s_waitcnt lgkmcnt(0)
	v_mov_b32_e32 v102, v91
	v_add_f32_dpp v60, v60, v60 row_ror:8 row_mask:0xf bank_mask:0xf bound_ctrl:1
	v_add_f32_dpp v58, v58, v58 row_ror:8 row_mask:0xf bank_mask:0xf bound_ctrl:1
	ds_write2st64_b32 v111, v10, v11 offset0:232 offset1:233
	v_add_f32_dpp v60, v60, v60 row_ror:4 row_mask:0xf bank_mask:0xf bound_ctrl:1
	v_add_f32_dpp v58, v58, v58 row_ror:4 row_mask:0xf bank_mask:0xf bound_ctrl:1
	v_pk_mul_f32 v[66:67], v[64:65], v[88:89]
	v_add_f32_dpp v60, v60, v60 row_ror:2 row_mask:0xf bank_mask:0xf bound_ctrl:1
	v_add_f32_dpp v58, v58, v58 row_ror:2 row_mask:0xf bank_mask:0xf bound_ctrl:1
	ds_read_b128 v[10:13], v118 offset:14080
	global_load_dwordx4 v[220:223], v118, s[56:57]
	s_add_u32 s56, s56, s58
	s_addc_u32 s57, s57, s59
	ds_read_b128 v[18:21], v118 offset:14592
	ds_read_b128 v[34:37], v118 offset:14848
	ds_read_b128 v[30:33], v118 offset:15104
	ds_read2_b32 v[82:83], v117 offset0:96 offset1:100
	v_add_f32_dpp v60, v60, v60 row_ror:1 row_mask:0xf bank_mask:0xf bound_ctrl:1
	v_add_f32_dpp v58, v58, v58 row_ror:1 row_mask:0xf bank_mask:0xf bound_ctrl:1
	v_pk_mul_f32 v[92:93], v[50:51], v[60:61] op_sel_hi:[1,0]
	v_pk_mul_f32 v[50:51], v[50:51], v[58:59] op_sel_hi:[1,0]
	v_pk_fma_f32 v[92:93], v[54:55], v[90:91], v[92:93] op_sel_hi:[1,0,1]
	v_pk_fma_f32 v[50:51], v[54:55], v[102:103], v[50:51] op_sel_hi:[1,0,1]
	s_waitcnt vmcnt(5)
	v_pk_fma_f32 v[92:93], v[200:201], v[96:97], v[92:93]
	v_pk_mul_f32 v[60:61], v[52:53], v[60:61] op_sel_hi:[1,0]
	v_pk_fma_f32 v[94:95], v[200:201], v[98:99], v[50:51]
	v_pk_mul_f32 v[46:47], v[52:53], v[58:59] op_sel_hi:[1,0]
	v_pk_fma_f32 v[60:61], v[56:57], v[90:91], v[60:61] op_sel_hi:[1,0,1]
	v_pk_fma_f32 v[46:47], v[56:57], v[102:103], v[46:47] op_sel_hi:[1,0,1]
	v_pk_fma_f32 v[66:67], v[62:63], v[96:97], v[66:67]
	v_pk_mul_f32 v[64:65], v[64:65], v[100:101]
	v_pk_fma_f32 v[90:91], v[202:203], v[88:89], v[60:61]
	v_pk_fma_f32 v[96:97], v[202:203], v[100:101], v[46:47]
	v_pk_fma_f32 v[62:63], v[62:63], v[98:99], v[64:65]
	s_waitcnt lgkmcnt(4)
	v_pk_mul_f32 v[98:99], v[12:13], v[90:91]
	v_pk_mul_f32 v[12:13], v[12:13], v[96:97]
	v_pk_fma_f32 v[98:99], v[10:11], v[92:93], v[98:99]
	v_pk_fma_f32 v[10:11], v[10:11], v[94:95], v[12:13]
	v_add_f32_e32 v12, v98, v99
	v_add_f32_e32 v10, v10, v11
	s_waitcnt lgkmcnt(0)
	v_mov_b32_e32 v100, v83
	v_add_f32_dpp v12, v12, v12 row_ror:8 row_mask:0xf bank_mask:0xf bound_ctrl:1
	v_add_f32_dpp v10, v10, v10 row_ror:8 row_mask:0xf bank_mask:0xf bound_ctrl:1
	v_add_f32_e32 v4, v6, v7
	v_add_f32_dpp v12, v12, v12 row_ror:4 row_mask:0xf bank_mask:0xf bound_ctrl:1
	v_add_f32_dpp v10, v10, v10 row_ror:4 row_mask:0xf bank_mask:0xf bound_ctrl:1
	v_add_f32_e32 v2, v2, v3
	v_add_f32_dpp v12, v12, v12 row_ror:2 row_mask:0xf bank_mask:0xf bound_ctrl:1
	v_add_f32_dpp v10, v10, v10 row_ror:2 row_mask:0xf bank_mask:0xf bound_ctrl:1
	ds_write2st64_b32 v111, v4, v2 offset0:240 offset1:241
	v_add_f32_dpp v12, v12, v12 row_ror:1 row_mask:0xf bank_mask:0xf bound_ctrl:1
	v_add_f32_dpp v98, v10, v10 row_ror:1 row_mask:0xf bank_mask:0xf bound_ctrl:1
	v_pk_mul_f32 v[10:11], v[18:19], v[12:13] op_sel_hi:[1,0]
	v_pk_mul_f32 v[18:19], v[18:19], v[98:99] op_sel_hi:[1,0]
	v_pk_fma_f32 v[10:11], v[34:35], v[82:83], v[10:11] op_sel_hi:[1,0,1]
	v_pk_mul_f32 v[12:13], v[20:21], v[12:13] op_sel_hi:[1,0]
	v_pk_fma_f32 v[18:19], v[34:35], v[100:101], v[18:19] op_sel_hi:[1,0,1]
	s_waitcnt vmcnt(4)
	v_pk_fma_f32 v[10:11], v[204:205], v[92:93], v[10:11]
	v_pk_fma_f32 v[12:13], v[36:37], v[82:83], v[12:13] op_sel_hi:[1,0,1]
	v_pk_fma_f32 v[14:15], v[204:205], v[94:95], v[18:19]
	v_pk_mul_f32 v[18:19], v[20:21], v[98:99] op_sel_hi:[1,0]
	v_pk_fma_f32 v[12:13], v[206:207], v[90:91], v[12:13]
	v_pk_fma_f32 v[18:19], v[36:37], v[100:101], v[18:19] op_sel_hi:[1,0,1]
	ds_read_b128 v[6:9], v118 offset:15360
	global_load_dwordx4 v[192:195], v118, s[56:57]
	s_add_u32 s56, s56, s58
	s_addc_u32 s57, s57, s59
	ds_read_b128 v[22:25], v118 offset:15872
	ds_read_b128 v[26:29], v118 offset:16128
	ds_read_b128 v[38:41], v118 offset:16384
	ds_read2_b32 v[84:85], v117 offset0:128 offset1:132
	v_pk_fma_f32 v[16:17], v[206:207], v[96:97], v[18:19]
	s_waitcnt lgkmcnt(4)
	v_pk_mul_f32 v[98:99], v[8:9], v[12:13]
	v_pk_mul_f32 v[8:9], v[8:9], v[16:17]
	v_pk_fma_f32 v[98:99], v[6:7], v[10:11], v[98:99]
	v_pk_fma_f32 v[6:7], v[6:7], v[14:15], v[8:9]
	v_add_f32_e32 v8, v98, v99
	v_add_f32_e32 v6, v6, v7
	v_pk_mul_f32 v[18:19], v[32:33], v[12:13]
	v_add_f32_dpp v8, v8, v8 row_ror:8 row_mask:0xf bank_mask:0xf bound_ctrl:1
	v_add_f32_dpp v6, v6, v6 row_ror:8 row_mask:0xf bank_mask:0xf bound_ctrl:1
	s_waitcnt lgkmcnt(0)
	v_mov_b32_e32 v98, v85
	v_add_f32_dpp v8, v8, v8 row_ror:4 row_mask:0xf bank_mask:0xf bound_ctrl:1
	v_add_f32_dpp v6, v6, v6 row_ror:4 row_mask:0xf bank_mask:0xf bound_ctrl:1
	v_pk_mul_f32 v[46:47], v[44:45], v[90:91]
	v_add_f32_dpp v8, v8, v8 row_ror:2 row_mask:0xf bank_mask:0xf bound_ctrl:1
	v_add_f32_dpp v6, v6, v6 row_ror:2 row_mask:0xf bank_mask:0xf bound_ctrl:1
	v_pk_mul_f32 v[44:45], v[44:45], v[96:97]
	v_add_f32_dpp v8, v8, v8 row_ror:1 row_mask:0xf bank_mask:0xf bound_ctrl:1
	v_pk_mul_f32 v[100:101], v[22:23], v[8:9] op_sel_hi:[1,0]
	v_pk_mul_f32 v[8:9], v[24:25], v[8:9] op_sel_hi:[1,0]
	v_add_f32_dpp v6, v6, v6 row_ror:1 row_mask:0xf bank_mask:0xf bound_ctrl:1
	v_pk_fma_f32 v[8:9], v[28:29], v[84:85], v[8:9] op_sel_hi:[1,0,1]
	v_add_f32_e32 v64, v66, v67
	s_waitcnt vmcnt(4)
	v_pk_fma_f32 v[8:9], v[210:211], v[12:13], v[8:9]
	v_pk_mul_f32 v[12:13], v[22:23], v[6:7] op_sel_hi:[1,0]
	v_pk_mul_f32 v[6:7], v[24:25], v[6:7] op_sel_hi:[1,0]
	v_add_f32_e32 v62, v62, v63
	v_pk_fma_f32 v[6:7], v[28:29], v[98:99], v[6:7] op_sel_hi:[1,0,1]
	v_pk_fma_f32 v[46:47], v[42:43], v[92:93], v[46:47]
	v_pk_fma_f32 v[42:43], v[42:43], v[94:95], v[44:45]
	v_pk_mul_f32 v[20:21], v[32:33], v[16:17]
	v_pk_fma_f32 v[100:101], v[26:27], v[84:85], v[100:101] op_sel_hi:[1,0,1]
	v_pk_fma_f32 v[12:13], v[26:27], v[98:99], v[12:13] op_sel_hi:[1,0,1]
	v_pk_fma_f32 v[4:5], v[210:211], v[16:17], v[6:7]
	ds_write2st64_b32 v111, v64, v62 offset0:248 offset1:249
	v_add_f32_e32 v44, v46, v47
	v_add_f32_e32 v42, v42, v43
	v_pk_fma_f32 v[18:19], v[30:31], v[10:11], v[18:19]
	v_pk_fma_f32 v[20:21], v[30:31], v[14:15], v[20:21]
	v_pk_fma_f32 v[10:11], v[208:209], v[10:11], v[100:101]
	v_pk_fma_f32 v[2:3], v[208:209], v[14:15], v[12:13]
	v_pk_mul_f32 v[6:7], v[40:41], v[8:9]
	v_pk_mul_f32 v[12:13], v[40:41], v[4:5]
	ds_read_b128 v[62:65], v118 offset:16640
	global_load_dwordx4 v[196:199], v118, s[56:57]
	s_add_u32 s56, s56, s58
	s_addc_u32 s57, s57, s59
	ds_read_b128 v[70:73], v118 offset:17152
	ds_read_b128 v[74:77], v118 offset:17408
	ds_read_b128 v[78:81], v118 offset:17664
	ds_read2_b32 v[86:87], v117 offset0:160 offset1:164
	ds_write2st64_b32 v112, v44, v42 offset0:80 offset1:81
	v_add_f32_e32 v18, v18, v19
	v_add_f32_e32 v19, v20, v21
	v_pk_fma_f32 v[6:7], v[38:39], v[10:11], v[6:7]
	v_pk_fma_f32 v[12:13], v[38:39], v[2:3], v[12:13]
	ds_read_b128 v[46:49], v118 offset:17920
	global_load_dwordx4 v[200:203], v118, s[56:57]
	s_add_u32 s56, s56, s58
	s_addc_u32 s57, s57, s59
	ds_read_b128 v[50:53], v118 offset:18432
	ds_read_b128 v[54:57], v118 offset:18688
	ds_read_b128 v[58:61], v118 offset:18944
	ds_read2_b32 v[88:89], v117 offset0:192 offset1:196
	ds_write2st64_b32 v112, v18, v19 offset0:88 offset1:89
	v_add_f32_e32 v6, v6, v7
	v_add_f32_e32 v7, v12, v13
	ds_read_b128 v[18:21], v118 offset:19200
	global_load_dwordx4 v[204:207], v118, s[56:57]
	s_add_u32 s56, s56, s58
	s_addc_u32 s57, s57, s59
	ds_read_b128 v[34:37], v118 offset:19712
	ds_read_b128 v[90:93], v118 offset:19968
	ds_read_b128 v[94:97], v118 offset:20224
	ds_read2_b32 v[82:83], v117 offset0:224 offset1:228
	ds_write2st64_b32 v112, v6, v7 offset0:96 offset1:97
	s_waitcnt lgkmcnt(12)
	v_pk_mul_f32 v[6:7], v[64:65], v[8:9]
	v_pk_mul_f32 v[12:13], v[64:65], v[4:5]
	v_pk_fma_f32 v[6:7], v[62:63], v[10:11], v[6:7]
	v_pk_fma_f32 v[12:13], v[62:63], v[2:3], v[12:13]
	v_add_f32_e32 v6, v6, v7
	v_add_f32_e32 v7, v12, v13
	v_mov_b32_e32 v14, v87
	v_add_f32_dpp v6, v6, v6 row_ror:8 row_mask:0xf bank_mask:0xf bound_ctrl:1
	v_add_f32_dpp v7, v7, v7 row_ror:8 row_mask:0xf bank_mask:0xf bound_ctrl:1
	s_nop 0
	v_add_f32_dpp v6, v6, v6 row_ror:4 row_mask:0xf bank_mask:0xf bound_ctrl:1
	v_add_f32_dpp v7, v7, v7 row_ror:4 row_mask:0xf bank_mask:0xf bound_ctrl:1
	s_nop 0
	v_add_f32_dpp v6, v6, v6 row_ror:2 row_mask:0xf bank_mask:0xf bound_ctrl:1
	v_add_f32_dpp v7, v7, v7 row_ror:2 row_mask:0xf bank_mask:0xf bound_ctrl:1
	s_nop 0
	v_add_f32_dpp v6, v6, v6 row_ror:1 row_mask:0xf bank_mask:0xf bound_ctrl:1
	v_add_f32_dpp v12, v7, v7 row_ror:1 row_mask:0xf bank_mask:0xf bound_ctrl:1
	v_pk_mul_f32 v[16:17], v[70:71], v[6:7] op_sel_hi:[1,0]
	v_pk_mul_f32 v[6:7], v[72:73], v[6:7] op_sel_hi:[1,0]
	v_pk_fma_f32 v[16:17], v[74:75], v[86:87], v[16:17] op_sel_hi:[1,0,1]
	v_pk_fma_f32 v[6:7], v[76:77], v[86:87], v[6:7] op_sel_hi:[1,0,1]
	s_waitcnt vmcnt(6)
	v_pk_fma_f32 v[10:11], v[212:213], v[10:11], v[16:17]
	v_pk_fma_f32 v[6:7], v[214:215], v[8:9], v[6:7]
	v_pk_mul_f32 v[8:9], v[70:71], v[12:13] op_sel_hi:[1,0]
	s_nop 0
	v_pk_fma_f32 v[8:9], v[74:75], v[14:15], v[8:9] op_sel_hi:[1,0,1]
	s_nop 0
	v_pk_fma_f32 v[2:3], v[212:213], v[2:3], v[8:9]
	v_pk_mul_f32 v[8:9], v[72:73], v[12:13] op_sel_hi:[1,0]
	s_nop 0
	v_pk_fma_f32 v[8:9], v[76:77], v[14:15], v[8:9] op_sel_hi:[1,0,1]
	s_waitcnt lgkmcnt(7)
	v_mov_b32_e32 v14, v89
	v_pk_fma_f32 v[4:5], v[214:215], v[4:5], v[8:9]
	v_pk_mul_f32 v[8:9], v[80:81], v[6:7]
	v_pk_mul_f32 v[12:13], v[80:81], v[4:5]
	v_pk_fma_f32 v[8:9], v[78:79], v[10:11], v[8:9]
	v_pk_fma_f32 v[12:13], v[78:79], v[2:3], v[12:13]
	v_add_f32_e32 v8, v8, v9
	v_add_f32_e32 v9, v12, v13
	ds_write2st64_b32 v112, v8, v9 offset0:104 offset1:105
	v_pk_mul_f32 v[8:9], v[48:49], v[6:7]
	v_pk_mul_f32 v[12:13], v[48:49], v[4:5]
	v_pk_fma_f32 v[8:9], v[46:47], v[10:11], v[8:9]
	v_pk_fma_f32 v[12:13], v[46:47], v[2:3], v[12:13]
	v_add_f32_e32 v8, v8, v9
	v_add_f32_e32 v9, v12, v13
	s_nop 0
	v_add_f32_dpp v8, v8, v8 row_ror:8 row_mask:0xf bank_mask:0xf bound_ctrl:1
	v_add_f32_dpp v9, v9, v9 row_ror:8 row_mask:0xf bank_mask:0xf bound_ctrl:1
	s_nop 0
	v_add_f32_dpp v8, v8, v8 row_ror:4 row_mask:0xf bank_mask:0xf bound_ctrl:1
	v_add_f32_dpp v9, v9, v9 row_ror:4 row_mask:0xf bank_mask:0xf bound_ctrl:1
	s_nop 0
	v_add_f32_dpp v8, v8, v8 row_ror:2 row_mask:0xf bank_mask:0xf bound_ctrl:1
	v_add_f32_dpp v9, v9, v9 row_ror:2 row_mask:0xf bank_mask:0xf bound_ctrl:1
	s_nop 0
	v_add_f32_dpp v8, v8, v8 row_ror:1 row_mask:0xf bank_mask:0xf bound_ctrl:1
	v_add_f32_dpp v12, v9, v9 row_ror:1 row_mask:0xf bank_mask:0xf bound_ctrl:1
	v_pk_mul_f32 v[16:17], v[50:51], v[8:9] op_sel_hi:[1,0]
	v_pk_mul_f32 v[8:9], v[52:53], v[8:9] op_sel_hi:[1,0]
	v_pk_fma_f32 v[16:17], v[54:55], v[88:89], v[16:17] op_sel_hi:[1,0,1]
	v_pk_fma_f32 v[8:9], v[56:57], v[88:89], v[8:9] op_sel_hi:[1,0,1]
	s_waitcnt vmcnt(5)
	v_pk_fma_f32 v[10:11], v[216:217], v[10:11], v[16:17]
	v_pk_fma_f32 v[6:7], v[218:219], v[6:7], v[8:9]
	v_pk_mul_f32 v[8:9], v[50:51], v[12:13] op_sel_hi:[1,0]
	s_nop 0
	v_pk_fma_f32 v[8:9], v[54:55], v[14:15], v[8:9] op_sel_hi:[1,0,1]
	s_nop 0
	v_pk_fma_f32 v[2:3], v[216:217], v[2:3], v[8:9]
	v_pk_mul_f32 v[8:9], v[52:53], v[12:13] op_sel_hi:[1,0]
	s_nop 0
	v_pk_fma_f32 v[8:9], v[56:57], v[14:15], v[8:9] op_sel_hi:[1,0,1]
	s_waitcnt lgkmcnt(2)
	v_mov_b32_e32 v14, v83
	v_pk_fma_f32 v[4:5], v[218:219], v[4:5], v[8:9]
	v_pk_mul_f32 v[8:9], v[60:61], v[6:7]
	v_pk_mul_f32 v[12:13], v[60:61], v[4:5]
	v_pk_fma_f32 v[8:9], v[58:59], v[10:11], v[8:9]
	v_pk_fma_f32 v[12:13], v[58:59], v[2:3], v[12:13]
	v_add_f32_e32 v8, v8, v9
	v_add_f32_e32 v9, v12, v13
	ds_write2st64_b32 v112, v8, v9 offset0:112 offset1:113
	v_pk_mul_f32 v[8:9], v[20:21], v[6:7]
	v_pk_mul_f32 v[12:13], v[20:21], v[4:5]
	v_pk_fma_f32 v[8:9], v[18:19], v[10:11], v[8:9]
	v_pk_fma_f32 v[12:13], v[18:19], v[2:3], v[12:13]
	v_add_f32_e32 v8, v8, v9
	v_add_f32_e32 v9, v12, v13
	s_nop 0
	v_add_f32_dpp v8, v8, v8 row_ror:8 row_mask:0xf bank_mask:0xf bound_ctrl:1
	v_add_f32_dpp v9, v9, v9 row_ror:8 row_mask:0xf bank_mask:0xf bound_ctrl:1
	s_nop 0
	v_add_f32_dpp v8, v8, v8 row_ror:4 row_mask:0xf bank_mask:0xf bound_ctrl:1
	v_add_f32_dpp v9, v9, v9 row_ror:4 row_mask:0xf bank_mask:0xf bound_ctrl:1
	s_nop 0
	v_add_f32_dpp v8, v8, v8 row_ror:2 row_mask:0xf bank_mask:0xf bound_ctrl:1
	v_add_f32_dpp v9, v9, v9 row_ror:2 row_mask:0xf bank_mask:0xf bound_ctrl:1
	s_nop 0
	v_add_f32_dpp v8, v8, v8 row_ror:1 row_mask:0xf bank_mask:0xf bound_ctrl:1
	v_add_f32_dpp v12, v9, v9 row_ror:1 row_mask:0xf bank_mask:0xf bound_ctrl:1
	v_pk_mul_f32 v[16:17], v[34:35], v[8:9] op_sel_hi:[1,0]
	v_pk_mul_f32 v[8:9], v[36:37], v[8:9] op_sel_hi:[1,0]
	v_pk_fma_f32 v[16:17], v[90:91], v[82:83], v[16:17] op_sel_hi:[1,0,1]
	v_pk_fma_f32 v[8:9], v[92:93], v[82:83], v[8:9] op_sel_hi:[1,0,1]
	s_waitcnt vmcnt(4)
	v_pk_fma_f32 v[22:23], v[220:221], v[10:11], v[16:17]
	v_pk_fma_f32 v[24:25], v[222:223], v[6:7], v[8:9]
	v_pk_mul_f32 v[6:7], v[34:35], v[12:13] op_sel_hi:[1,0]
	s_nop 0
	v_pk_fma_f32 v[6:7], v[90:91], v[14:15], v[6:7] op_sel_hi:[1,0,1]
	s_nop 0
	v_pk_fma_f32 v[26:27], v[220:221], v[2:3], v[6:7]
	v_pk_mul_f32 v[2:3], v[36:37], v[12:13] op_sel_hi:[1,0]
	s_nop 0
	v_pk_fma_f32 v[2:3], v[92:93], v[14:15], v[2:3] op_sel_hi:[1,0,1]
	s_nop 0
	v_pk_fma_f32 v[28:29], v[222:223], v[4:5], v[2:3]
	v_pk_mul_f32 v[2:3], v[96:97], v[24:25]
	v_pk_mul_f32 v[4:5], v[96:97], v[28:29]
	v_pk_fma_f32 v[2:3], v[94:95], v[22:23], v[2:3]
	v_pk_fma_f32 v[4:5], v[94:95], v[26:27], v[4:5]
	v_add_f32_e32 v2, v2, v3
	v_add_f32_e32 v3, v4, v5
	ds_write2st64_b32 v112, v2, v3 offset0:120 offset1:121
	s_waitcnt lgkmcnt(0)
	s_barrier
	ds_read_b128 v[18:21], v118 offset:20480
	global_load_dwordx4 v[208:211], v118, s[56:57]
	s_add_u32 s56, s56, s58
	s_addc_u32 s57, s57, s59
	ds_read_b128 v[10:13], v118 offset:20992
	ds_read_b128 v[14:17], v118 offset:21248
	ds_read_b128 v[2:5], v118 offset:21504
	s_waitcnt lgkmcnt(3)
	v_pk_mul_f32 v[66:67], v[20:21], v[24:25]
	v_pk_mul_f32 v[20:21], v[20:21], v[28:29]
	v_pk_fma_f32 v[66:67], v[18:19], v[22:23], v[66:67]
	v_pk_fma_f32 v[18:19], v[18:19], v[26:27], v[20:21]
	v_add_f32_e32 v20, v66, v67
	v_add_f32_e32 v18, v18, v19
	ds_read2_b32 v[62:63], v120 offset1:4
	ds_read_b128 v[30:33], v118 offset:21760
	global_load_dwordx4 v[212:215], v118, s[56:57]
	s_add_u32 s56, s56, s58
	s_addc_u32 s57, s57, s59
	ds_read_b128 v[38:41], v118 offset:22272
	ds_read_b128 v[42:45], v118 offset:22528
	ds_read_b128 v[46:49], v118 offset:22784
	ds_read2_b32 v[64:65], v120 offset0:32 offset1:36
	ds_read_b128 v[50:53], v118 offset:23040
	global_load_dwordx4 v[216:219], v118, s[56:57]
	s_add_u32 s56, s56, s58
	s_addc_u32 s57, s57, s59
	ds_read_b128 v[58:61], v118 offset:23552
	ds_read_b128 v[82:85], v118 offset:23808
	ds_read_b128 v[88:91], v118 offset:24064
	ds_read2_b32 v[108:109], v120 offset0:64 offset1:68
	ds_read_b128 v[92:95], v118 offset:24320
	global_load_dwordx4 v[220:223], v118, s[56:57]
	s_add_u32 s56, s56, s58
	s_addc_u32 s57, s57, s59
	ds_read_b128 v[100:103], v118 offset:24832
	ds_read_b128 v[104:107], v118 offset:25088
	ds_read_b128 v[124:127], v118 offset:25344
	ds_read2_b32 v[130:131], v120 offset0:96 offset1:100
	v_add_f32_dpp v20, v20, v20 row_ror:8 row_mask:0xf bank_mask:0xf bound_ctrl:1
	v_add_f32_dpp v18, v18, v18 row_ror:8 row_mask:0xf bank_mask:0xf bound_ctrl:1
	s_waitcnt lgkmcnt(12)
	v_mov_b32_e32 v66, v63
	v_add_f32_dpp v20, v20, v20 row_ror:4 row_mask:0xf bank_mask:0xf bound_ctrl:1
	v_add_f32_dpp v18, v18, v18 row_ror:4 row_mask:0xf bank_mask:0xf bound_ctrl:1
	s_nop 0
	v_add_f32_dpp v20, v20, v20 row_ror:2 row_mask:0xf bank_mask:0xf bound_ctrl:1
	v_add_f32_dpp v18, v18, v18 row_ror:2 row_mask:0xf bank_mask:0xf bound_ctrl:1
	s_nop 0
	v_add_f32_dpp v20, v20, v20 row_ror:1 row_mask:0xf bank_mask:0xf bound_ctrl:1
	v_add_f32_dpp v18, v18, v18 row_ror:1 row_mask:0xf bank_mask:0xf bound_ctrl:1
	v_pk_mul_f32 v[68:69], v[10:11], v[20:21] op_sel_hi:[1,0]
	v_pk_mul_f32 v[10:11], v[10:11], v[18:19] op_sel_hi:[1,0]
	v_pk_fma_f32 v[68:69], v[14:15], v[62:63], v[68:69] op_sel_hi:[1,0,1]
	v_pk_mul_f32 v[20:21], v[12:13], v[20:21] op_sel_hi:[1,0]
	v_pk_fma_f32 v[10:11], v[14:15], v[66:67], v[10:11] op_sel_hi:[1,0,1]
	s_waitcnt vmcnt(7)
	v_pk_fma_f32 v[22:23], v[192:193], v[22:23], v[68:69]
	v_pk_fma_f32 v[20:21], v[16:17], v[62:63], v[20:21] op_sel_hi:[1,0,1]
	v_pk_fma_f32 v[26:27], v[192:193], v[26:27], v[10:11]
	v_pk_mul_f32 v[6:7], v[12:13], v[18:19] op_sel_hi:[1,0]
	v_pk_fma_f32 v[24:25], v[194:195], v[24:25], v[20:21]
	v_pk_fma_f32 v[6:7], v[16:17], v[66:67], v[6:7] op_sel_hi:[1,0,1]
	v_pk_mul_f32 v[62:63], v[32:33], v[24:25]
	v_pk_fma_f32 v[28:29], v[194:195], v[28:29], v[6:7]
	v_pk_fma_f32 v[62:63], v[30:31], v[22:23], v[62:63]
	v_pk_mul_f32 v[32:33], v[32:33], v[28:29]
	v_pk_mul_f32 v[6:7], v[4:5], v[24:25]
	v_pk_fma_f32 v[30:31], v[30:31], v[26:27], v[32:33]
	v_add_f32_e32 v32, v62, v63
	v_add_f32_e32 v30, v30, v31
	s_waitcnt lgkmcnt(10)
	v_mov_b32_e32 v62, v65
	v_add_f32_dpp v32, v32, v32 row_ror:8 row_mask:0xf bank_mask:0xf bound_ctrl:1
	v_add_f32_dpp v30, v30, v30 row_ror:8 row_mask:0xf bank_mask:0xf bound_ctrl:1
	v_pk_mul_f32 v[4:5], v[4:5], v[28:29]
	v_add_f32_dpp v32, v32, v32 row_ror:4 row_mask:0xf bank_mask:0xf bound_ctrl:1
	v_add_f32_dpp v30, v30, v30 row_ror:4 row_mask:0xf bank_mask:0xf bound_ctrl:1
	v_pk_fma_f32 v[6:7], v[2:3], v[22:23], v[6:7]
	v_add_f32_dpp v32, v32, v32 row_ror:2 row_mask:0xf bank_mask:0xf bound_ctrl:1
	v_add_f32_dpp v30, v30, v30 row_ror:2 row_mask:0xf bank_mask:0xf bound_ctrl:1
	v_pk_fma_f32 v[2:3], v[2:3], v[26:27], v[4:5]
	v_add_f32_dpp v32, v32, v32 row_ror:1 row_mask:0xf bank_mask:0xf bound_ctrl:1
	v_pk_mul_f32 v[66:67], v[38:39], v[32:33] op_sel_hi:[1,0]
	v_pk_mul_f32 v[32:33], v[40:41], v[32:33] op_sel_hi:[1,0]
	v_add_f32_dpp v30, v30, v30 row_ror:1 row_mask:0xf bank_mask:0xf bound_ctrl:1
	v_pk_fma_f32 v[32:33], v[44:45], v[64:65], v[32:33] op_sel_hi:[1,0,1]
	v_pk_fma_f32 v[66:67], v[42:43], v[64:65], v[66:67] op_sel_hi:[1,0,1]
	s_waitcnt vmcnt(6)
	v_pk_fma_f32 v[24:25], v[198:199], v[24:25], v[32:33]
	v_pk_mul_f32 v[32:33], v[38:39], v[30:31] op_sel_hi:[1,0]
	v_pk_mul_f32 v[30:31], v[40:41], v[30:31] op_sel_hi:[1,0]
	v_pk_fma_f32 v[32:33], v[42:43], v[62:63], v[32:33] op_sel_hi:[1,0,1]
	v_pk_fma_f32 v[30:31], v[44:45], v[62:63], v[30:31] op_sel_hi:[1,0,1]
	v_pk_fma_f32 v[22:23], v[196:197], v[22:23], v[66:67]
	v_pk_fma_f32 v[28:29], v[198:199], v[28:29], v[30:31]
	v_pk_fma_f32 v[26:27], v[196:197], v[26:27], v[32:33]
	v_pk_mul_f32 v[30:31], v[48:49], v[24:25]
	v_pk_mul_f32 v[32:33], v[48:49], v[28:29]
	v_add_f32_e32 v4, v6, v7
	v_add_f32_e32 v2, v2, v3
	v_pk_fma_f32 v[30:31], v[46:47], v[22:23], v[30:31]
	v_pk_fma_f32 v[32:33], v[46:47], v[26:27], v[32:33]
	ds_write2st64_b32 v113, v4, v2 offset1:1
	v_add_f32_e32 v30, v30, v31
	v_add_f32_e32 v31, v32, v33
	ds_read_b128 v[2:5], v118 offset:25600
	global_load_dwordx4 v[192:195], v118, s[56:57]
	s_add_u32 s56, s56, s58
	s_addc_u32 s57, s57, s59
	ds_read_b128 v[10:13], v118 offset:26112
	ds_read_b128 v[14:17], v118 offset:26368
	ds_read_b128 v[18:21], v118 offset:26624
	ds_read2_b32 v[132:133], v120 offset0:128 offset1:132
	ds_write2st64_b32 v113, v30, v31 offset0:8 offset1:9
	s_waitcnt lgkmcnt(12)
	v_pk_mul_f32 v[30:31], v[52:53], v[24:25]
	v_pk_mul_f32 v[32:33], v[52:53], v[28:29]
	v_pk_fma_f32 v[30:31], v[50:51], v[22:23], v[30:31]
	v_pk_fma_f32 v[32:33], v[50:51], v[26:27], v[32:33]
	v_add_f32_e32 v30, v30, v31
	v_add_f32_e32 v31, v32, v33
	v_mov_b32_e32 v34, v109
	v_add_f32_dpp v30, v30, v30 row_ror:8 row_mask:0xf bank_mask:0xf bound_ctrl:1
	v_add_f32_dpp v31, v31, v31 row_ror:8 row_mask:0xf bank_mask:0xf bound_ctrl:1
	ds_read_b128 v[78:81], v118 offset:26880
	global_load_dwordx4 v[196:199], v118, s[56:57]
	s_add_u32 s56, s56, s58
	s_addc_u32 s57, s57, s59
	ds_read_b128 v[70:73], v118 offset:27392
	ds_read_b128 v[74:77], v118 offset:27648
	ds_read_b128 v[62:65], v118 offset:27904
	ds_read2_b32 v[86:87], v120 offset0:160 offset1:164
	v_add_f32_dpp v30, v30, v30 row_ror:4 row_mask:0xf bank_mask:0xf bound_ctrl:1
	v_add_f32_dpp v31, v31, v31 row_ror:4 row_mask:0xf bank_mask:0xf bound_ctrl:1
	s_nop 0
	v_add_f32_dpp v30, v30, v30 row_ror:2 row_mask:0xf bank_mask:0xf bound_ctrl:1
	v_add_f32_dpp v31, v31, v31 row_ror:2 row_mask:0xf bank_mask:0xf bound_ctrl:1
	s_nop 0
	v_add_f32_dpp v30, v30, v30 row_ror:1 row_mask:0xf bank_mask:0xf bound_ctrl:1
	v_add_f32_dpp v32, v31, v31 row_ror:1 row_mask:0xf bank_mask:0xf bound_ctrl:1
	v_pk_mul_f32 v[36:37], v[58:59], v[30:31] op_sel_hi:[1,0]
	v_pk_mul_f32 v[30:31], v[60:61], v[30:31] op_sel_hi:[1,0]
	v_pk_fma_f32 v[36:37], v[82:83], v[108:109], v[36:37] op_sel_hi:[1,0,1]
	v_pk_fma_f32 v[30:31], v[84:85], v[108:109], v[30:31] op_sel_hi:[1,0,1]
	s_waitcnt vmcnt(7)
	v_pk_fma_f32 v[22:23], v[200:201], v[22:23], v[36:37]
	v_pk_fma_f32 v[24:25], v[202:203], v[24:25], v[30:31]
	v_pk_mul_f32 v[30:31], v[58:59], v[32:33] op_sel_hi:[1,0]
	s_nop 0
	v_pk_fma_f32 v[30:31], v[82:83], v[34:35], v[30:31] op_sel_hi:[1,0,1]
	s_nop 0
	v_pk_fma_f32 v[26:27], v[200:201], v[26:27], v[30:31]
	v_pk_mul_f32 v[30:31], v[60:61], v[32:33] op_sel_hi:[1,0]
	s_nop 0
	v_pk_fma_f32 v[30:31], v[84:85], v[34:35], v[30:31] op_sel_hi:[1,0,1]
	s_waitcnt lgkmcnt(12)
	v_mov_b32_e32 v34, v131
	v_pk_fma_f32 v[28:29], v[202:203], v[28:29], v[30:31]
	v_pk_mul_f32 v[30:31], v[90:91], v[24:25]
	v_pk_mul_f32 v[32:33], v[90:91], v[28:29]
	v_pk_fma_f32 v[30:31], v[88:89], v[22:23], v[30:31]
	v_pk_fma_f32 v[32:33], v[88:89], v[26:27], v[32:33]
	v_add_f32_e32 v30, v30, v31
	v_add_f32_e32 v31, v32, v33
	ds_write2st64_b32 v113, v30, v31 offset0:16 offset1:17
	v_pk_mul_f32 v[30:31], v[94:95], v[24:25]
	v_pk_mul_f32 v[32:33], v[94:95], v[28:29]
	v_pk_fma_f32 v[30:31], v[92:93], v[22:23], v[30:31]
	v_pk_fma_f32 v[32:33], v[92:93], v[26:27], v[32:33]
	v_add_f32_e32 v30, v30, v31
	v_add_f32_e32 v31, v32, v33
	ds_read_b128 v[58:61], v118 offset:28160
	global_load_dwordx4 v[200:203], v118, s[56:57]
	s_add_u32 s56, s56, s58
	s_addc_u32 s57, s57, s59
	ds_read_b128 v[50:53], v118 offset:28672
	ds_read_b128 v[54:57], v118 offset:28928
	ds_read_b128 v[42:45], v118 offset:29184
	ds_read2_b32 v[84:85], v120 offset0:192 offset1:196
	v_add_f32_dpp v30, v30, v30 row_ror:8 row_mask:0xf bank_mask:0xf bound_ctrl:1
	v_add_f32_dpp v31, v31, v31 row_ror:8 row_mask:0xf bank_mask:0xf bound_ctrl:1
	s_nop 0
	v_add_f32_dpp v30, v30, v30 row_ror:4 row_mask:0xf bank_mask:0xf bound_ctrl:1
	v_add_f32_dpp v31, v31, v31 row_ror:4 row_mask:0xf bank_mask:0xf bound_ctrl:1
	s_nop 0
	v_add_f32_dpp v30, v30, v30 row_ror:2 row_mask:0xf bank_mask:0xf bound_ctrl:1
	v_add_f32_dpp v31, v31, v31 row_ror:2 row_mask:0xf bank_mask:0xf bound_ctrl:1
	s_nop 0
	v_add_f32_dpp v30, v30, v30 row_ror:1 row_mask:0xf bank_mask:0xf bound_ctrl:1
	v_pk_mul_f32 v[36:37], v[100:101], v[30:31] op_sel_hi:[1,0]
	v_add_f32_dpp v32, v31, v31 row_ror:1 row_mask:0xf bank_mask:0xf bound_ctrl:1
	v_pk_fma_f32 v[36:37], v[104:105], v[130:131], v[36:37] op_sel_hi:[1,0,1]
	s_nop 0
	s_waitcnt vmcnt(7)
	v_pk_fma_f32 v[88:89], v[204:205], v[22:23], v[36:37]
	v_pk_mul_f32 v[22:23], v[102:103], v[30:31] op_sel_hi:[1,0]
	s_nop 0
	v_pk_fma_f32 v[22:23], v[106:107], v[130:131], v[22:23] op_sel_hi:[1,0,1]
	s_nop 0
	v_pk_fma_f32 v[90:91], v[206:207], v[24:25], v[22:23]
	v_pk_mul_f32 v[22:23], v[100:101], v[32:33] op_sel_hi:[1,0]
	s_nop 0
	v_pk_fma_f32 v[22:23], v[104:105], v[34:35], v[22:23] op_sel_hi:[1,0,1]
	s_nop 0
	v_pk_fma_f32 v[92:93], v[204:205], v[26:27], v[22:23]
	v_pk_mul_f32 v[22:23], v[102:103], v[32:33] op_sel_hi:[1,0]
	s_waitcnt lgkmcnt(12)
	v_pk_mul_f32 v[96:97], v[4:5], v[90:91]
	v_pk_fma_f32 v[22:23], v[106:107], v[34:35], v[22:23] op_sel_hi:[1,0,1]
	v_pk_fma_f32 v[96:97], v[2:3], v[88:89], v[96:97]
	v_pk_fma_f32 v[94:95], v[206:207], v[28:29], v[22:23]
	v_pk_mul_f32 v[22:23], v[126:127], v[90:91]
	v_pk_mul_f32 v[4:5], v[4:5], v[94:95]
	v_pk_mul_f32 v[24:25], v[126:127], v[94:95]
	v_pk_fma_f32 v[2:3], v[2:3], v[92:93], v[4:5]
	v_add_f32_e32 v4, v96, v97
	v_add_f32_e32 v2, v2, v3
	v_mov_b32_e32 v96, v133
	v_add_f32_dpp v4, v4, v4 row_ror:8 row_mask:0xf bank_mask:0xf bound_ctrl:1
	v_add_f32_dpp v2, v2, v2 row_ror:8 row_mask:0xf bank_mask:0xf bound_ctrl:1
	v_pk_fma_f32 v[22:23], v[124:125], v[88:89], v[22:23]
	v_add_f32_dpp v4, v4, v4 row_ror:4 row_mask:0xf bank_mask:0xf bound_ctrl:1
	v_add_f32_dpp v2, v2, v2 row_ror:4 row_mask:0xf bank_mask:0xf bound_ctrl:1
	v_pk_fma_f32 v[24:25], v[124:125], v[92:93], v[24:25]
	v_add_f32_dpp v4, v4, v4 row_ror:2 row_mask:0xf bank_mask:0xf bound_ctrl:1
	v_add_f32_dpp v2, v2, v2 row_ror:2 row_mask:0xf bank_mask:0xf bound_ctrl:1
	v_add_f32_e32 v22, v22, v23
	v_add_f32_dpp v4, v4, v4 row_ror:1 row_mask:0xf bank_mask:0xf bound_ctrl:1
	v_pk_mul_f32 v[98:99], v[10:11], v[4:5] op_sel_hi:[1,0]
	v_pk_mul_f32 v[4:5], v[12:13], v[4:5] op_sel_hi:[1,0]
	v_add_f32_dpp v2, v2, v2 row_ror:1 row_mask:0xf bank_mask:0xf bound_ctrl:1
	v_pk_fma_f32 v[4:5], v[16:17], v[132:133], v[4:5] op_sel_hi:[1,0,1]
	v_pk_fma_f32 v[98:99], v[14:15], v[132:133], v[98:99] op_sel_hi:[1,0,1]
	s_waitcnt vmcnt(6)
	v_pk_fma_f32 v[90:91], v[210:211], v[90:91], v[4:5]
	v_pk_mul_f32 v[4:5], v[10:11], v[2:3] op_sel_hi:[1,0]
	v_pk_mul_f32 v[2:3], v[12:13], v[2:3] op_sel_hi:[1,0]
	v_pk_fma_f32 v[4:5], v[14:15], v[96:97], v[4:5] op_sel_hi:[1,0,1]
	v_pk_fma_f32 v[2:3], v[16:17], v[96:97], v[2:3] op_sel_hi:[1,0,1]
	v_pk_fma_f32 v[88:89], v[208:209], v[88:89], v[98:99]
	v_pk_fma_f32 v[94:95], v[210:211], v[94:95], v[2:3]
	v_pk_fma_f32 v[92:93], v[208:209], v[92:93], v[4:5]
	s_waitcnt lgkmcnt(10)
	v_pk_mul_f32 v[96:97], v[80:81], v[90:91]
	v_pk_mul_f32 v[80:81], v[80:81], v[94:95]
	v_pk_fma_f32 v[96:97], v[78:79], v[88:89], v[96:97]
	v_pk_fma_f32 v[78:79], v[78:79], v[92:93], v[80:81]
	v_add_f32_e32 v80, v96, v97
	v_add_f32_e32 v78, v78, v79
	s_waitcnt lgkmcnt(6)
	v_mov_b32_e32 v96, v87
	v_add_f32_dpp v80, v80, v80 row_ror:8 row_mask:0xf bank_mask:0xf bound_ctrl:1
	v_add_f32_dpp v78, v78, v78 row_ror:8 row_mask:0xf bank_mask:0xf bound_ctrl:1
	v_pk_mul_f32 v[2:3], v[20:21], v[90:91]
	v_add_f32_dpp v80, v80, v80 row_ror:4 row_mask:0xf bank_mask:0xf bound_ctrl:1
	v_add_f32_dpp v78, v78, v78 row_ror:4 row_mask:0xf bank_mask:0xf bound_ctrl:1
	v_pk_mul_f32 v[4:5], v[20:21], v[94:95]
	v_add_f32_dpp v80, v80, v80 row_ror:2 row_mask:0xf bank_mask:0xf bound_ctrl:1
	v_add_f32_dpp v78, v78, v78 row_ror:2 row_mask:0xf bank_mask:0xf bound_ctrl:1
	v_add_f32_e32 v23, v24, v25
	v_add_f32_dpp v80, v80, v80 row_ror:1 row_mask:0xf bank_mask:0xf bound_ctrl:1
	v_add_f32_dpp v78, v78, v78 row_ror:1 row_mask:0xf bank_mask:0xf bound_ctrl:1
	v_pk_mul_f32 v[98:99], v[70:71], v[80:81] op_sel_hi:[1,0]
	v_pk_mul_f32 v[70:71], v[70:71], v[78:79] op_sel_hi:[1,0]
	v_pk_fma_f32 v[98:99], v[74:75], v[86:87], v[98:99] op_sel_hi:[1,0,1]
	v_pk_fma_f32 v[70:71], v[74:75], v[96:97], v[70:71] op_sel_hi:[1,0,1]
	s_waitcnt vmcnt(5)
	v_pk_fma_f32 v[104:105], v[212:213], v[88:89], v[98:99]
	v_pk_mul_f32 v[80:81], v[72:73], v[80:81] op_sel_hi:[1,0]
	v_pk_fma_f32 v[66:67], v[212:213], v[92:93], v[70:71]
	v_pk_mul_f32 v[70:71], v[72:73], v[78:79] op_sel_hi:[1,0]
	v_pk_fma_f32 v[80:81], v[76:77], v[86:87], v[80:81] op_sel_hi:[1,0,1]
	v_pk_fma_f32 v[70:71], v[76:77], v[96:97], v[70:71] op_sel_hi:[1,0,1]
	v_pk_fma_f32 v[106:107], v[214:215], v[90:91], v[80:81]
	v_pk_fma_f32 v[68:69], v[214:215], v[94:95], v[70:71]
	v_pk_fma_f32 v[2:3], v[18:19], v[88:89], v[2:3]
	v_pk_fma_f32 v[4:5], v[18:19], v[92:93], v[4:5]
	v_pk_mul_f32 v[70:71], v[64:65], v[106:107]
	v_pk_mul_f32 v[64:65], v[64:65], v[68:69]
	ds_write2st64_b32 v113, v22, v23 offset0:24 offset1:25
	v_add_f32_e32 v2, v2, v3
	v_add_f32_e32 v3, v4, v5
	v_pk_fma_f32 v[70:71], v[62:63], v[104:105], v[70:71]
	v_pk_fma_f32 v[62:63], v[62:63], v[66:67], v[64:65]
	ds_read_b128 v[38:41], v118 offset:29440
	global_load_dwordx4 v[204:207], v118, s[56:57]
	s_add_u32 s56, s56, s58
	s_addc_u32 s57, s57, s59
	ds_read_b128 v[30:33], v118 offset:29952
	ds_read_b128 v[34:37], v118 offset:30208
	ds_read_b128 v[22:25], v118 offset:30464
	ds_read2_b32 v[82:83], v120 offset0:224 offset1:228
	ds_write2st64_b32 v113, v2, v3 offset0:32 offset1:33
	v_add_f32_e32 v64, v70, v71
	v_add_f32_e32 v62, v62, v63
	ds_read_b128 v[18:21], v118 offset:30720
	global_load_dwordx4 v[208:211], v118, s[56:57]
	s_add_u32 s56, s56, s58
	s_addc_u32 s57, s57, s59
	ds_read_b128 v[10:13], v118 offset:31232
	ds_read_b128 v[14:17], v118 offset:31488
	ds_read_b128 v[2:5], v118 offset:31744
	ds_write2st64_b32 v113, v64, v62 offset0:40 offset1:41
	s_waitcnt lgkmcnt(12)
	v_pk_mul_f32 v[62:63], v[60:61], v[106:107]
	v_pk_mul_f32 v[60:61], v[60:61], v[68:69]
	v_pk_fma_f32 v[62:63], v[58:59], v[104:105], v[62:63]
	v_pk_fma_f32 v[58:59], v[58:59], v[66:67], v[60:61]
	v_add_f32_e32 v60, v62, v63
	v_add_f32_e32 v58, v58, v59
	v_mov_b32_e32 v62, v85
	v_add_f32_dpp v60, v60, v60 row_ror:8 row_mask:0xf bank_mask:0xf bound_ctrl:1
	v_add_f32_dpp v58, v58, v58 row_ror:8 row_mask:0xf bank_mask:0xf bound_ctrl:1
	ds_read2_b32 v[102:103], v114 offset1:4
	v_add_f32_dpp v60, v60, v60 row_ror:4 row_mask:0xf bank_mask:0xf bound_ctrl:1
	v_add_f32_dpp v58, v58, v58 row_ror:4 row_mask:0xf bank_mask:0xf bound_ctrl:1
	ds_read_b128 v[98:101], v118 offset:32000
	global_load_dwordx4 v[212:215], v118, s[56:57]
	s_add_u32 s56, s56, s58
	s_addc_u32 s57, s57, s59
	ds_read_b128 v[90:93], v118 offset:32512
	ds_read_b128 v[94:97], v118 offset:32768
	ds_read_b128 v[78:81], v118 offset:33024
	ds_read2_b32 v[108:109], v114 offset0:32 offset1:36
	v_add_f32_dpp v60, v60, v60 row_ror:2 row_mask:0xf bank_mask:0xf bound_ctrl:1
	v_add_f32_dpp v58, v58, v58 row_ror:2 row_mask:0xf bank_mask:0xf bound_ctrl:1
	s_nop 0
	v_add_f32_dpp v60, v60, v60 row_ror:1 row_mask:0xf bank_mask:0xf bound_ctrl:1
	v_add_f32_dpp v58, v58, v58 row_ror:1 row_mask:0xf bank_mask:0xf bound_ctrl:1
	v_pk_mul_f32 v[64:65], v[50:51], v[60:61] op_sel_hi:[1,0]
	v_pk_mul_f32 v[50:51], v[50:51], v[58:59] op_sel_hi:[1,0]
	v_pk_fma_f32 v[64:65], v[54:55], v[84:85], v[64:65] op_sel_hi:[1,0,1]
	v_pk_fma_f32 v[50:51], v[54:55], v[62:63], v[50:51] op_sel_hi:[1,0,1]
	s_waitcnt vmcnt(7)
	v_pk_fma_f32 v[104:105], v[216:217], v[104:105], v[64:65]
	v_pk_mul_f32 v[60:61], v[52:53], v[60:61] op_sel_hi:[1,0]
	v_pk_fma_f32 v[54:55], v[216:217], v[66:67], v[50:51]
	v_pk_mul_f32 v[46:47], v[52:53], v[58:59] op_sel_hi:[1,0]
	v_pk_fma_f32 v[60:61], v[56:57], v[84:85], v[60:61] op_sel_hi:[1,0,1]
	v_pk_fma_f32 v[46:47], v[56:57], v[62:63], v[46:47] op_sel_hi:[1,0,1]
	v_pk_fma_f32 v[60:61], v[218:219], v[106:107], v[60:61]
	v_pk_fma_f32 v[56:57], v[218:219], v[68:69], v[46:47]
	s_waitcnt lgkmcnt(12)
	v_pk_mul_f32 v[50:51], v[40:41], v[60:61]
	v_pk_mul_f32 v[40:41], v[40:41], v[56:57]
	v_pk_fma_f32 v[50:51], v[38:39], v[104:105], v[50:51]
	v_pk_fma_f32 v[38:39], v[38:39], v[54:55], v[40:41]
	v_add_f32_e32 v40, v50, v51
	v_add_f32_e32 v38, v38, v39
	v_mov_b32_e32 v58, v83
	v_add_f32_dpp v40, v40, v40 row_ror:8 row_mask:0xf bank_mask:0xf bound_ctrl:1
	v_add_f32_dpp v38, v38, v38 row_ror:8 row_mask:0xf bank_mask:0xf bound_ctrl:1
	v_pk_mul_f32 v[46:47], v[44:45], v[60:61]
	v_add_f32_dpp v40, v40, v40 row_ror:4 row_mask:0xf bank_mask:0xf bound_ctrl:1
	v_add_f32_dpp v38, v38, v38 row_ror:4 row_mask:0xf bank_mask:0xf bound_ctrl:1
	v_pk_mul_f32 v[44:45], v[44:45], v[56:57]
	v_add_f32_dpp v40, v40, v40 row_ror:2 row_mask:0xf bank_mask:0xf bound_ctrl:1
	v_add_f32_dpp v38, v38, v38 row_ror:2 row_mask:0xf bank_mask:0xf bound_ctrl:1
	v_pk_fma_f32 v[46:47], v[42:43], v[104:105], v[46:47]
	v_add_f32_dpp v40, v40, v40 row_ror:1 row_mask:0xf bank_mask:0xf bound_ctrl:1
	v_add_f32_dpp v38, v38, v38 row_ror:1 row_mask:0xf bank_mask:0xf bound_ctrl:1
	v_pk_mul_f32 v[50:51], v[30:31], v[40:41] op_sel_hi:[1,0]
	v_pk_mul_f32 v[30:31], v[30:31], v[38:39] op_sel_hi:[1,0]
	v_pk_fma_f32 v[50:51], v[34:35], v[82:83], v[50:51] op_sel_hi:[1,0,1]
	v_pk_fma_f32 v[30:31], v[34:35], v[58:59], v[30:31] op_sel_hi:[1,0,1]
	s_waitcnt vmcnt(6)
	v_pk_fma_f32 v[50:51], v[220:221], v[104:105], v[50:51]
	v_pk_mul_f32 v[40:41], v[32:33], v[40:41] op_sel_hi:[1,0]
	v_pk_fma_f32 v[26:27], v[220:221], v[54:55], v[30:31]
	v_pk_mul_f32 v[30:31], v[32:33], v[38:39] op_sel_hi:[1,0]
	v_pk_fma_f32 v[40:41], v[36:37], v[82:83], v[40:41] op_sel_hi:[1,0,1]
	v_pk_fma_f32 v[30:31], v[36:37], v[58:59], v[30:31] op_sel_hi:[1,0,1]
	v_pk_fma_f32 v[52:53], v[222:223], v[60:61], v[40:41]
	v_pk_fma_f32 v[28:29], v[222:223], v[56:57], v[30:31]
	v_pk_fma_f32 v[42:43], v[42:43], v[54:55], v[44:45]
	v_pk_mul_f32 v[30:31], v[24:25], v[52:53]
	v_pk_mul_f32 v[24:25], v[24:25], v[28:29]
	v_add_f32_e32 v44, v46, v47
	v_add_f32_e32 v42, v42, v43
	v_pk_fma_f32 v[30:31], v[22:23], v[50:51], v[30:31]
	v_pk_fma_f32 v[22:23], v[22:23], v[26:27], v[24:25]
	ds_write2st64_b32 v113, v44, v42 offset0:48 offset1:49
	v_add_f32_e32 v24, v30, v31
	v_add_f32_e32 v22, v22, v23
	ds_read_b128 v[46:49], v118 offset:33280
	global_load_dwordx4 v[216:219], v118, s[56:57]
	s_add_u32 s56, s56, s58
	s_addc_u32 s57, s57, s59
	ds_read_b128 v[62:65], v118 offset:33792
	ds_read_b128 v[74:77], v118 offset:34048
	ds_read_b128 v[70:73], v118 offset:34304
	ds_read2_b32 v[106:107], v114 offset0:64 offset1:68
	ds_write2st64_b32 v113, v24, v22 offset0:56 offset1:57
	s_waitcnt lgkmcnt(12)
	v_pk_mul_f32 v[22:23], v[20:21], v[52:53]
	v_pk_mul_f32 v[20:21], v[20:21], v[28:29]
	v_pk_fma_f32 v[22:23], v[18:19], v[50:51], v[22:23]
	v_pk_fma_f32 v[18:19], v[18:19], v[26:27], v[20:21]
	v_add_f32_e32 v20, v22, v23
	v_add_f32_e32 v18, v18, v19
	v_mov_b32_e32 v22, v103
	v_add_f32_dpp v20, v20, v20 row_ror:8 row_mask:0xf bank_mask:0xf bound_ctrl:1
	v_add_f32_dpp v18, v18, v18 row_ror:8 row_mask:0xf bank_mask:0xf bound_ctrl:1
	ds_read_b128 v[34:37], v118 offset:34560
	global_load_dwordx4 v[220:223], v118, s[56:57]
	s_add_u32 s56, s56, s58
	s_addc_u32 s57, s57, s59
	ds_read_b128 v[58:61], v118 offset:35072
	ds_read_b128 v[66:69], v118 offset:35328
	ds_read_b128 v[82:85], v118 offset:35584
	ds_read2_b32 v[104:105], v114 offset0:96 offset1:100
	v_add_f32_dpp v20, v20, v20 row_ror:4 row_mask:0xf bank_mask:0xf bound_ctrl:1
	v_add_f32_dpp v18, v18, v18 row_ror:4 row_mask:0xf bank_mask:0xf bound_ctrl:1
	s_nop 0
	v_add_f32_dpp v20, v20, v20 row_ror:2 row_mask:0xf bank_mask:0xf bound_ctrl:1
	v_add_f32_dpp v18, v18, v18 row_ror:2 row_mask:0xf bank_mask:0xf bound_ctrl:1
	s_nop 0
	v_add_f32_dpp v20, v20, v20 row_ror:1 row_mask:0xf bank_mask:0xf bound_ctrl:1
	v_add_f32_dpp v18, v18, v18 row_ror:1 row_mask:0xf bank_mask:0xf bound_ctrl:1
	v_pk_mul_f32 v[24:25], v[10:11], v[20:21] op_sel_hi:[1,0]
	v_pk_mul_f32 v[10:11], v[10:11], v[18:19] op_sel_hi:[1,0]
	v_pk_fma_f32 v[24:25], v[14:15], v[102:103], v[24:25] op_sel_hi:[1,0,1]
	v_pk_fma_f32 v[10:11], v[14:15], v[22:23], v[10:11] op_sel_hi:[1,0,1]
	s_waitcnt vmcnt(7)
	v_pk_fma_f32 v[54:55], v[192:193], v[50:51], v[24:25]
	v_pk_mul_f32 v[20:21], v[12:13], v[20:21] op_sel_hi:[1,0]
	v_pk_fma_f32 v[6:7], v[192:193], v[26:27], v[10:11]
	v_pk_mul_f32 v[10:11], v[12:13], v[18:19] op_sel_hi:[1,0]
	v_pk_fma_f32 v[20:21], v[16:17], v[102:103], v[20:21] op_sel_hi:[1,0,1]
	v_pk_fma_f32 v[10:11], v[16:17], v[22:23], v[10:11] op_sel_hi:[1,0,1]
	v_pk_fma_f32 v[56:57], v[194:195], v[52:53], v[20:21]
	v_pk_fma_f32 v[8:9], v[194:195], v[28:29], v[10:11]
	v_pk_mul_f32 v[10:11], v[4:5], v[56:57]
	v_pk_mul_f32 v[4:5], v[4:5], v[8:9]
	v_pk_fma_f32 v[10:11], v[2:3], v[54:55], v[10:11]
	v_pk_fma_f32 v[2:3], v[2:3], v[6:7], v[4:5]
	v_add_f32_e32 v4, v10, v11
	v_add_f32_e32 v2, v2, v3
	ds_write2st64_b32 v113, v4, v2 offset0:64 offset1:65
	s_waitcnt lgkmcnt(12)
	v_pk_mul_f32 v[2:3], v[100:101], v[56:57]
	v_pk_mul_f32 v[4:5], v[100:101], v[8:9]
	v_pk_fma_f32 v[2:3], v[98:99], v[54:55], v[2:3]
	v_pk_fma_f32 v[4:5], v[98:99], v[6:7], v[4:5]
	v_add_f32_e32 v2, v2, v3
	v_mov_b32_e32 v14, v109
	ds_read_b128 v[50:53], v118 offset:35840
	global_load_dwordx4 v[192:195], v118, s[56:57]
	s_add_u32 s56, s56, s58
	s_addc_u32 s57, s57, s59
	ds_read_b128 v[22:25], v118 offset:36352
	ds_read_b128 v[26:29], v118 offset:36608
	ds_read_b128 v[30:33], v118 offset:36864
	ds_read2_b32 v[102:103], v114 offset0:128 offset1:132
	v_add_f32_dpp v2, v2, v2 row_ror:8 row_mask:0xf bank_mask:0xf bound_ctrl:1
	s_nop 1
	v_add_f32_dpp v2, v2, v2 row_ror:4 row_mask:0xf bank_mask:0xf bound_ctrl:1
	s_nop 1
	v_add_f32_dpp v2, v2, v2 row_ror:2 row_mask:0xf bank_mask:0xf bound_ctrl:1
	s_nop 1
	v_add_f32_dpp v10, v2, v2 row_ror:1 row_mask:0xf bank_mask:0xf bound_ctrl:1
	v_add_f32_e32 v2, v4, v5
	v_pk_mul_f32 v[4:5], v[92:93], v[10:11] op_sel_hi:[1,0]
	s_nop 0
	v_add_f32_dpp v2, v2, v2 row_ror:8 row_mask:0xf bank_mask:0xf bound_ctrl:1
	v_pk_fma_f32 v[4:5], v[96:97], v[108:109], v[4:5] op_sel_hi:[1,0,1]
	s_nop 0
	v_add_f32_dpp v2, v2, v2 row_ror:4 row_mask:0xf bank_mask:0xf bound_ctrl:1
	s_waitcnt vmcnt(7)
	v_pk_fma_f32 v[4:5], v[198:199], v[56:57], v[4:5]
	s_nop 0
	v_add_f32_dpp v2, v2, v2 row_ror:2 row_mask:0xf bank_mask:0xf bound_ctrl:1
	s_nop 1
	v_add_f32_dpp v12, v2, v2 row_ror:1 row_mask:0xf bank_mask:0xf bound_ctrl:1
	v_pk_mul_f32 v[2:3], v[90:91], v[10:11] op_sel_hi:[1,0]
	v_pk_mul_f32 v[10:11], v[90:91], v[12:13] op_sel_hi:[1,0]
	v_pk_fma_f32 v[2:3], v[94:95], v[108:109], v[2:3] op_sel_hi:[1,0,1]
	v_pk_fma_f32 v[10:11], v[94:95], v[14:15], v[10:11] op_sel_hi:[1,0,1]
	v_pk_fma_f32 v[2:3], v[196:197], v[54:55], v[2:3]
	v_pk_fma_f32 v[6:7], v[196:197], v[6:7], v[10:11]
	v_pk_mul_f32 v[10:11], v[92:93], v[12:13] op_sel_hi:[1,0]
	s_nop 0
	v_pk_fma_f32 v[10:11], v[96:97], v[14:15], v[10:11] op_sel_hi:[1,0,1]
	s_waitcnt lgkmcnt(12)
	v_mov_b32_e32 v14, v107
	v_pk_fma_f32 v[8:9], v[198:199], v[8:9], v[10:11]
	v_pk_mul_f32 v[10:11], v[80:81], v[4:5]
	v_pk_mul_f32 v[12:13], v[80:81], v[8:9]
	v_pk_fma_f32 v[10:11], v[78:79], v[2:3], v[10:11]
	v_pk_fma_f32 v[12:13], v[78:79], v[6:7], v[12:13]
	v_add_f32_e32 v10, v10, v11
	v_add_f32_e32 v11, v12, v13
	ds_write2st64_b32 v113, v10, v11 offset0:72 offset1:73
	v_pk_mul_f32 v[10:11], v[48:49], v[4:5]
	v_pk_mul_f32 v[12:13], v[48:49], v[8:9]
	v_pk_fma_f32 v[10:11], v[46:47], v[2:3], v[10:11]
	v_pk_fma_f32 v[12:13], v[46:47], v[6:7], v[12:13]
	v_add_f32_e32 v10, v10, v11
	v_add_f32_e32 v11, v12, v13
	ds_read_b128 v[94:97], v118 offset:37120
	global_load_dwordx4 v[196:199], v118, s[56:57]
	s_add_u32 s56, s56, s58
	s_addc_u32 s57, s57, s59
	ds_read_b128 v[78:81], v118 offset:37632
	ds_read_b128 v[86:89], v118 offset:37888
	ds_read_b128 v[90:93], v118 offset:38144
	ds_read2_b32 v[98:99], v114 offset0:160 offset1:164
	v_add_f32_dpp v10, v10, v10 row_ror:8 row_mask:0xf bank_mask:0xf bound_ctrl:1
	v_add_f32_dpp v11, v11, v11 row_ror:8 row_mask:0xf bank_mask:0xf bound_ctrl:1
	s_nop 0
	v_add_f32_dpp v10, v10, v10 row_ror:4 row_mask:0xf bank_mask:0xf bound_ctrl:1
	v_add_f32_dpp v11, v11, v11 row_ror:4 row_mask:0xf bank_mask:0xf bound_ctrl:1
	s_nop 0
	v_add_f32_dpp v10, v10, v10 row_ror:2 row_mask:0xf bank_mask:0xf bound_ctrl:1
	v_add_f32_dpp v11, v11, v11 row_ror:2 row_mask:0xf bank_mask:0xf bound_ctrl:1
	s_nop 0
	v_add_f32_dpp v10, v10, v10 row_ror:1 row_mask:0xf bank_mask:0xf bound_ctrl:1
	v_add_f32_dpp v12, v11, v11 row_ror:1 row_mask:0xf bank_mask:0xf bound_ctrl:1
	v_pk_mul_f32 v[16:17], v[62:63], v[10:11] op_sel_hi:[1,0]
	v_pk_mul_f32 v[10:11], v[64:65], v[10:11] op_sel_hi:[1,0]
	v_pk_fma_f32 v[16:17], v[74:75], v[106:107], v[16:17] op_sel_hi:[1,0,1]
	v_pk_fma_f32 v[10:11], v[76:77], v[106:107], v[10:11] op_sel_hi:[1,0,1]
	s_waitcnt vmcnt(7)
	v_pk_fma_f32 v[2:3], v[200:201], v[2:3], v[16:17]
	v_pk_fma_f32 v[4:5], v[202:203], v[4:5], v[10:11]
	v_pk_mul_f32 v[10:11], v[62:63], v[12:13] op_sel_hi:[1,0]
	s_nop 0
	v_pk_fma_f32 v[10:11], v[74:75], v[14:15], v[10:11] op_sel_hi:[1,0,1]
	s_nop 0
	v_pk_fma_f32 v[6:7], v[200:201], v[6:7], v[10:11]
	v_pk_mul_f32 v[10:11], v[64:65], v[12:13] op_sel_hi:[1,0]
	s_nop 0
	v_pk_fma_f32 v[10:11], v[76:77], v[14:15], v[10:11] op_sel_hi:[1,0,1]
	s_waitcnt lgkmcnt(12)
	v_mov_b32_e32 v14, v105
	v_pk_fma_f32 v[8:9], v[202:203], v[8:9], v[10:11]
	v_pk_mul_f32 v[10:11], v[72:73], v[4:5]
	v_pk_mul_f32 v[12:13], v[72:73], v[8:9]
	v_pk_fma_f32 v[10:11], v[70:71], v[2:3], v[10:11]
	v_pk_fma_f32 v[12:13], v[70:71], v[6:7], v[12:13]
	v_add_f32_e32 v10, v10, v11
	v_add_f32_e32 v11, v12, v13
	ds_write2st64_b32 v113, v10, v11 offset0:80 offset1:81
	v_pk_mul_f32 v[10:11], v[36:37], v[4:5]
	v_pk_mul_f32 v[12:13], v[36:37], v[8:9]
	v_pk_fma_f32 v[10:11], v[34:35], v[2:3], v[10:11]
	v_pk_fma_f32 v[12:13], v[34:35], v[6:7], v[12:13]
	v_add_f32_e32 v10, v10, v11
	v_add_f32_e32 v11, v12, v13
	ds_read_b128 v[74:77], v118 offset:38400
	global_load_dwordx4 v[200:203], v118, s[56:57]
	s_add_u32 s56, s56, s58
	s_addc_u32 s57, s57, s59
	ds_read_b128 v[46:49], v118 offset:38912
	ds_read_b128 v[62:65], v118 offset:39168
	ds_read_b128 v[70:73], v118 offset:39424
	ds_read2_b32 v[100:101], v114 offset0:192 offset1:196
	v_add_f32_dpp v10, v10, v10 row_ror:8 row_mask:0xf bank_mask:0xf bound_ctrl:1
	v_add_f32_dpp v11, v11, v11 row_ror:8 row_mask:0xf bank_mask:0xf bound_ctrl:1
	s_nop 0
	v_add_f32_dpp v10, v10, v10 row_ror:4 row_mask:0xf bank_mask:0xf bound_ctrl:1
	v_add_f32_dpp v11, v11, v11 row_ror:4 row_mask:0xf bank_mask:0xf bound_ctrl:1
	s_nop 0
	v_add_f32_dpp v10, v10, v10 row_ror:2 row_mask:0xf bank_mask:0xf bound_ctrl:1
	v_add_f32_dpp v11, v11, v11 row_ror:2 row_mask:0xf bank_mask:0xf bound_ctrl:1
	s_nop 0
	v_add_f32_dpp v10, v10, v10 row_ror:1 row_mask:0xf bank_mask:0xf bound_ctrl:1
	v_pk_mul_f32 v[16:17], v[58:59], v[10:11] op_sel_hi:[1,0]
	v_add_f32_dpp v12, v11, v11 row_ror:1 row_mask:0xf bank_mask:0xf bound_ctrl:1
	v_pk_fma_f32 v[16:17], v[66:67], v[104:105], v[16:17] op_sel_hi:[1,0,1]
	s_nop 0
	s_waitcnt vmcnt(7)
	v_pk_fma_f32 v[106:107], v[204:205], v[2:3], v[16:17]
	v_pk_mul_f32 v[2:3], v[60:61], v[10:11] op_sel_hi:[1,0]
	s_nop 0
	v_pk_fma_f32 v[2:3], v[68:69], v[104:105], v[2:3] op_sel_hi:[1,0,1]
	s_nop 0
	v_pk_fma_f32 v[104:105], v[206:207], v[4:5], v[2:3]
	v_pk_mul_f32 v[2:3], v[58:59], v[12:13] op_sel_hi:[1,0]
	s_nop 0
	v_pk_fma_f32 v[2:3], v[66:67], v[14:15], v[2:3] op_sel_hi:[1,0,1]
	s_nop 0
	v_pk_fma_f32 v[58:59], v[204:205], v[6:7], v[2:3]
	v_pk_mul_f32 v[2:3], v[60:61], v[12:13] op_sel_hi:[1,0]
	s_waitcnt lgkmcnt(12)
	v_pk_mul_f32 v[60:61], v[52:53], v[104:105]
	v_pk_fma_f32 v[2:3], v[68:69], v[14:15], v[2:3] op_sel_hi:[1,0,1]
	v_pk_fma_f32 v[60:61], v[50:51], v[106:107], v[60:61]
	v_pk_fma_f32 v[40:41], v[206:207], v[8:9], v[2:3]
	v_pk_mul_f32 v[2:3], v[84:85], v[104:105]
	v_pk_mul_f32 v[52:53], v[52:53], v[40:41]
	v_pk_mul_f32 v[4:5], v[84:85], v[40:41]
	v_pk_fma_f32 v[50:51], v[50:51], v[58:59], v[52:53]
	v_add_f32_e32 v52, v60, v61
	v_add_f32_e32 v50, v50, v51
	v_mov_b32_e32 v60, v103
	v_add_f32_dpp v52, v52, v52 row_ror:8 row_mask:0xf bank_mask:0xf bound_ctrl:1
	v_add_f32_dpp v50, v50, v50 row_ror:8 row_mask:0xf bank_mask:0xf bound_ctrl:1
	v_pk_fma_f32 v[2:3], v[82:83], v[106:107], v[2:3]
	v_add_f32_dpp v52, v52, v52 row_ror:4 row_mask:0xf bank_mask:0xf bound_ctrl:1
	v_add_f32_dpp v50, v50, v50 row_ror:4 row_mask:0xf bank_mask:0xf bound_ctrl:1
	v_pk_fma_f32 v[4:5], v[82:83], v[58:59], v[4:5]
	v_add_f32_dpp v52, v52, v52 row_ror:2 row_mask:0xf bank_mask:0xf bound_ctrl:1
	v_add_f32_dpp v50, v50, v50 row_ror:2 row_mask:0xf bank_mask:0xf bound_ctrl:1
	v_add_f32_e32 v2, v2, v3
	v_add_f32_dpp v52, v52, v52 row_ror:1 row_mask:0xf bank_mask:0xf bound_ctrl:1
	v_add_f32_dpp v50, v50, v50 row_ror:1 row_mask:0xf bank_mask:0xf bound_ctrl:1
	v_pk_mul_f32 v[66:67], v[22:23], v[52:53] op_sel_hi:[1,0]
	v_pk_mul_f32 v[22:23], v[22:23], v[50:51] op_sel_hi:[1,0]
	v_pk_fma_f32 v[66:67], v[26:27], v[102:103], v[66:67] op_sel_hi:[1,0,1]
	v_pk_fma_f32 v[22:23], v[26:27], v[60:61], v[22:23] op_sel_hi:[1,0,1]
	s_waitcnt vmcnt(6)
	v_pk_fma_f32 v[66:67], v[208:209], v[106:107], v[66:67]
	v_pk_mul_f32 v[52:53], v[24:25], v[52:53] op_sel_hi:[1,0]
	v_pk_fma_f32 v[18:19], v[208:209], v[58:59], v[22:23]
	v_pk_mul_f32 v[22:23], v[24:25], v[50:51] op_sel_hi:[1,0]
	v_pk_fma_f32 v[52:53], v[28:29], v[102:103], v[52:53] op_sel_hi:[1,0,1]
	v_pk_fma_f32 v[22:23], v[28:29], v[60:61], v[22:23] op_sel_hi:[1,0,1]
	v_pk_fma_f32 v[52:53], v[210:211], v[104:105], v[52:53]
	v_pk_fma_f32 v[20:21], v[210:211], v[40:41], v[22:23]
	v_pk_mul_f32 v[22:23], v[32:33], v[52:53]
	v_pk_mul_f32 v[24:25], v[32:33], v[20:21]
	v_add_f32_e32 v3, v4, v5
	v_pk_fma_f32 v[22:23], v[30:31], v[66:67], v[22:23]
	v_pk_fma_f32 v[24:25], v[30:31], v[18:19], v[24:25]
	ds_write2st64_b32 v113, v2, v3 offset0:88 offset1:89
	v_add_f32_e32 v22, v22, v23
	v_add_f32_e32 v23, v24, v25
	ds_read_b128 v[34:37], v118 offset:39680
	global_load_dwordx4 v[204:207], v118, s[56:57]
	s_add_u32 s56, s56, s58
	s_addc_u32 s57, s57, s59
	ds_read_b128 v[6:9], v118 offset:40192
	ds_read_b128 v[10:13], v118 offset:40448
	ds_read_b128 v[14:17], v118 offset:40704
	ds_read2_b32 v[38:39], v114 offset0:224 offset1:228
	ds_write2st64_b32 v113, v22, v23 offset0:96 offset1:97
	s_waitcnt lgkmcnt(12)
	v_pk_mul_f32 v[22:23], v[96:97], v[52:53]
	v_pk_mul_f32 v[24:25], v[96:97], v[20:21]
	v_pk_fma_f32 v[22:23], v[94:95], v[66:67], v[22:23]
	v_pk_fma_f32 v[24:25], v[94:95], v[18:19], v[24:25]
	v_add_f32_e32 v22, v22, v23
	v_add_f32_e32 v23, v24, v25
	v_mov_b32_e32 v26, v99
	v_add_f32_dpp v22, v22, v22 row_ror:8 row_mask:0xf bank_mask:0xf bound_ctrl:1
	v_add_f32_dpp v23, v23, v23 row_ror:8 row_mask:0xf bank_mask:0xf bound_ctrl:1
	s_waitcnt lgkmcnt(7)
	v_mov_b32_e32 v32, v101
	v_add_f32_dpp v22, v22, v22 row_ror:4 row_mask:0xf bank_mask:0xf bound_ctrl:1
	v_add_f32_dpp v23, v23, v23 row_ror:4 row_mask:0xf bank_mask:0xf bound_ctrl:1
	s_nop 0
	v_add_f32_dpp v22, v22, v22 row_ror:2 row_mask:0xf bank_mask:0xf bound_ctrl:1
	v_add_f32_dpp v23, v23, v23 row_ror:2 row_mask:0xf bank_mask:0xf bound_ctrl:1
	s_nop 0
	v_add_f32_dpp v22, v22, v22 row_ror:1 row_mask:0xf bank_mask:0xf bound_ctrl:1
	v_add_f32_dpp v24, v23, v23 row_ror:1 row_mask:0xf bank_mask:0xf bound_ctrl:1
	v_pk_mul_f32 v[28:29], v[78:79], v[22:23] op_sel_hi:[1,0]
	v_pk_mul_f32 v[22:23], v[80:81], v[22:23] op_sel_hi:[1,0]
	v_pk_mul_f32 v[30:31], v[78:79], v[24:25] op_sel_hi:[1,0]
	v_pk_mul_f32 v[24:25], v[80:81], v[24:25] op_sel_hi:[1,0]
	v_pk_fma_f32 v[22:23], v[88:89], v[98:99], v[22:23] op_sel_hi:[1,0,1]
	v_pk_fma_f32 v[24:25], v[88:89], v[26:27], v[24:25] op_sel_hi:[1,0,1]
	v_pk_fma_f32 v[28:29], v[86:87], v[98:99], v[28:29] op_sel_hi:[1,0,1]
	s_waitcnt vmcnt(6)
	v_pk_fma_f32 v[22:23], v[214:215], v[52:53], v[22:23]
	v_pk_fma_f32 v[30:31], v[86:87], v[26:27], v[30:31] op_sel_hi:[1,0,1]
	v_pk_fma_f32 v[26:27], v[214:215], v[20:21], v[24:25]
	v_pk_fma_f32 v[28:29], v[212:213], v[66:67], v[28:29]
	v_pk_fma_f32 v[18:19], v[212:213], v[18:19], v[30:31]
	v_pk_mul_f32 v[20:21], v[92:93], v[22:23]
	v_pk_mul_f32 v[24:25], v[92:93], v[26:27]
	v_pk_fma_f32 v[20:21], v[90:91], v[28:29], v[20:21]
	v_pk_fma_f32 v[24:25], v[90:91], v[18:19], v[24:25]
	v_add_f32_e32 v20, v20, v21
	v_add_f32_e32 v21, v24, v25
	ds_write2st64_b32 v113, v20, v21 offset0:104 offset1:105
	v_pk_mul_f32 v[20:21], v[76:77], v[22:23]
	v_pk_mul_f32 v[24:25], v[76:77], v[26:27]
	v_pk_fma_f32 v[20:21], v[74:75], v[28:29], v[20:21]
	v_pk_fma_f32 v[24:25], v[74:75], v[18:19], v[24:25]
	v_add_f32_e32 v20, v20, v21
	v_add_f32_e32 v21, v24, v25
	s_nop 0
	v_add_f32_dpp v20, v20, v20 row_ror:8 row_mask:0xf bank_mask:0xf bound_ctrl:1
	v_add_f32_dpp v21, v21, v21 row_ror:8 row_mask:0xf bank_mask:0xf bound_ctrl:1
	s_nop 0
	v_add_f32_dpp v20, v20, v20 row_ror:4 row_mask:0xf bank_mask:0xf bound_ctrl:1
	v_add_f32_dpp v21, v21, v21 row_ror:4 row_mask:0xf bank_mask:0xf bound_ctrl:1
	s_nop 0
	v_add_f32_dpp v20, v20, v20 row_ror:2 row_mask:0xf bank_mask:0xf bound_ctrl:1
	v_add_f32_dpp v21, v21, v21 row_ror:2 row_mask:0xf bank_mask:0xf bound_ctrl:1
	s_nop 0
	v_add_f32_dpp v20, v20, v20 row_ror:1 row_mask:0xf bank_mask:0xf bound_ctrl:1
	v_add_f32_dpp v30, v21, v21 row_ror:1 row_mask:0xf bank_mask:0xf bound_ctrl:1
	v_pk_mul_f32 v[24:25], v[46:47], v[20:21] op_sel_hi:[1,0]
	v_pk_mul_f32 v[20:21], v[48:49], v[20:21] op_sel_hi:[1,0]
	v_pk_fma_f32 v[24:25], v[62:63], v[100:101], v[24:25] op_sel_hi:[1,0,1]
	v_pk_fma_f32 v[20:21], v[64:65], v[100:101], v[20:21] op_sel_hi:[1,0,1]
	s_waitcnt vmcnt(5)
	v_pk_fma_f32 v[24:25], v[216:217], v[28:29], v[24:25]
	v_pk_fma_f32 v[22:23], v[218:219], v[22:23], v[20:21]
	v_pk_mul_f32 v[20:21], v[46:47], v[30:31] op_sel_hi:[1,0]
	s_nop 0
	v_pk_fma_f32 v[20:21], v[62:63], v[32:33], v[20:21] op_sel_hi:[1,0,1]
	s_nop 0
	v_pk_fma_f32 v[20:21], v[216:217], v[18:19], v[20:21]
	v_pk_mul_f32 v[18:19], v[48:49], v[30:31] op_sel_hi:[1,0]
	s_nop 0
	v_pk_fma_f32 v[18:19], v[64:65], v[32:33], v[18:19] op_sel_hi:[1,0,1]
	s_nop 0
	v_pk_fma_f32 v[18:19], v[218:219], v[26:27], v[18:19]
	v_pk_mul_f32 v[26:27], v[72:73], v[22:23]
	v_pk_mul_f32 v[28:29], v[72:73], v[18:19]
	v_pk_fma_f32 v[26:27], v[70:71], v[24:25], v[26:27]
	v_pk_fma_f32 v[28:29], v[70:71], v[20:21], v[28:29]
	v_add_f32_e32 v26, v26, v27
	v_add_f32_e32 v27, v28, v29
	ds_write2st64_b32 v113, v26, v27 offset0:112 offset1:113
	s_waitcnt lgkmcnt(7)
	v_pk_mul_f32 v[26:27], v[36:37], v[22:23]
	v_pk_mul_f32 v[28:29], v[36:37], v[18:19]
	v_pk_fma_f32 v[26:27], v[34:35], v[24:25], v[26:27]
	v_pk_fma_f32 v[30:31], v[34:35], v[20:21], v[28:29]
	v_add_f32_e32 v26, v26, v27
	s_nop 1
	v_add_f32_dpp v26, v26, v26 row_ror:8 row_mask:0xf bank_mask:0xf bound_ctrl:1
	s_nop 1
	v_add_f32_dpp v26, v26, v26 row_ror:4 row_mask:0xf bank_mask:0xf bound_ctrl:1
	s_nop 1
	v_add_f32_dpp v26, v26, v26 row_ror:2 row_mask:0xf bank_mask:0xf bound_ctrl:1
	s_nop 1
	v_add_f32_dpp v28, v26, v26 row_ror:1 row_mask:0xf bank_mask:0xf bound_ctrl:1
	v_add_f32_e32 v26, v30, v31
	s_waitcnt lgkmcnt(3)
	v_mov_b32_e32 v30, v39
	v_pk_mul_f32 v[32:33], v[6:7], v[28:29] op_sel_hi:[1,0]
	v_add_f32_dpp v26, v26, v26 row_ror:8 row_mask:0xf bank_mask:0xf bound_ctrl:1
	v_pk_fma_f32 v[32:33], v[10:11], v[38:39], v[32:33] op_sel_hi:[1,0,1]
	s_nop 0
	v_add_f32_dpp v26, v26, v26 row_ror:4 row_mask:0xf bank_mask:0xf bound_ctrl:1
	s_waitcnt vmcnt(4)
	v_pk_fma_f32 v[84:85], v[220:221], v[24:25], v[32:33]
	v_pk_mul_f32 v[24:25], v[8:9], v[28:29] op_sel_hi:[1,0]
	v_add_f32_dpp v26, v26, v26 row_ror:2 row_mask:0xf bank_mask:0xf bound_ctrl:1
	v_pk_fma_f32 v[24:25], v[12:13], v[38:39], v[24:25] op_sel_hi:[1,0,1]
	s_nop 0
	v_add_f32_dpp v26, v26, v26 row_ror:1 row_mask:0xf bank_mask:0xf bound_ctrl:1
	v_pk_mul_f32 v[6:7], v[6:7], v[26:27] op_sel_hi:[1,0]
	v_pk_fma_f32 v[86:87], v[222:223], v[22:23], v[24:25]
	v_pk_fma_f32 v[6:7], v[10:11], v[30:31], v[6:7] op_sel_hi:[1,0,1]
	s_nop 0
	v_pk_fma_f32 v[88:89], v[220:221], v[20:21], v[6:7]
	v_pk_mul_f32 v[2:3], v[8:9], v[26:27] op_sel_hi:[1,0]
	s_nop 0
	v_pk_fma_f32 v[2:3], v[12:13], v[30:31], v[2:3] op_sel_hi:[1,0,1]
	s_nop 0
	v_pk_fma_f32 v[92:93], v[222:223], v[18:19], v[2:3]
	v_pk_mul_f32 v[2:3], v[16:17], v[86:87]
	v_pk_mul_f32 v[4:5], v[16:17], v[92:93]
	v_pk_fma_f32 v[2:3], v[14:15], v[84:85], v[2:3]
	v_pk_fma_f32 v[4:5], v[14:15], v[88:89], v[4:5]
	v_add_f32_e32 v2, v2, v3
	v_add_f32_e32 v3, v4, v5
	ds_write2st64_b32 v113, v2, v3 offset0:120 offset1:121
	s_waitcnt lgkmcnt(0)
	s_barrier
	ds_read_b128 v[2:5], v118
	global_load_dwordx4 v[208:211], v118, s[56:57]
	s_add_u32 s56, s56, s58
	s_addc_u32 s57, s57, s59
	ds_read_b128 v[22:25], v118 offset:512
	ds_read_b128 v[26:29], v118 offset:768
	ds_read_b128 v[38:41], v118 offset:1024
	ds_read2_b32 v[94:95], v121 offset1:4
	ds_read_b128 v[42:45], v118 offset:1280
	global_load_dwordx4 v[212:215], v118, s[56:57]
	s_add_u32 s56, s56, s58
	s_addc_u32 s57, s57, s59
	ds_read_b128 v[62:65], v118 offset:1792
	ds_read_b128 v[70:73], v118 offset:2048
	ds_read_b128 v[74:77], v118 offset:2304
	ds_read2_b32 v[96:97], v121 offset0:32 offset1:36
	ds_read_b128 v[78:81], v118 offset:2560
	global_load_dwordx4 v[216:219], v118, s[56:57]
	s_add_u32 s56, s56, s58
	s_addc_u32 s57, s57, s59
	ds_read_b128 v[58:61], v118 offset:3072
	ds_read_b128 v[66:69], v118 offset:3328
	ds_read_b128 v[10:13], v118 offset:3584
	ds_read2_b32 v[82:83], v121 offset0:64 offset1:68
	ds_read_b128 v[50:53], v118 offset:3840
	global_load_dwordx4 v[220:223], v118, s[56:57]
	s_add_u32 s56, s56, s58
	s_addc_u32 s57, s57, s59
	ds_read_b128 v[30:33], v118 offset:4352
	ds_read_b128 v[34:37], v118 offset:4608
	ds_read_b128 v[6:9], v118 offset:4864
	ds_read2_b32 v[90:91], v121 offset0:96 offset1:100
	s_waitcnt lgkmcnt(12)
	v_pk_mul_f32 v[98:99], v[4:5], v[86:87]
	v_pk_mul_f32 v[4:5], v[4:5], v[92:93]
	v_pk_fma_f32 v[98:99], v[2:3], v[84:85], v[98:99]
	v_pk_fma_f32 v[2:3], v[2:3], v[88:89], v[4:5]
	v_add_f32_e32 v4, v98, v99
	v_add_f32_e32 v2, v2, v3
	v_mov_b32_e32 v98, v95
	v_add_f32_dpp v4, v4, v4 row_ror:8 row_mask:0xf bank_mask:0xf bound_ctrl:1
	v_add_f32_dpp v2, v2, v2 row_ror:8 row_mask:0xf bank_mask:0xf bound_ctrl:1
	s_nop 0
	v_add_f32_dpp v4, v4, v4 row_ror:4 row_mask:0xf bank_mask:0xf bound_ctrl:1
	v_add_f32_dpp v2, v2, v2 row_ror:4 row_mask:0xf bank_mask:0xf bound_ctrl:1
	s_nop 0
	v_add_f32_dpp v4, v4, v4 row_ror:2 row_mask:0xf bank_mask:0xf bound_ctrl:1
	v_add_f32_dpp v2, v2, v2 row_ror:2 row_mask:0xf bank_mask:0xf bound_ctrl:1
	s_nop 0
	v_add_f32_dpp v4, v4, v4 row_ror:1 row_mask:0xf bank_mask:0xf bound_ctrl:1
	v_pk_mul_f32 v[100:101], v[22:23], v[4:5] op_sel_hi:[1,0]
	v_pk_mul_f32 v[4:5], v[24:25], v[4:5] op_sel_hi:[1,0]
	v_add_f32_dpp v2, v2, v2 row_ror:1 row_mask:0xf bank_mask:0xf bound_ctrl:1
	v_pk_fma_f32 v[4:5], v[28:29], v[94:95], v[4:5] op_sel_hi:[1,0,1]
	v_pk_fma_f32 v[100:101], v[26:27], v[94:95], v[100:101] op_sel_hi:[1,0,1]
	s_waitcnt vmcnt(7)
	v_pk_fma_f32 v[86:87], v[194:195], v[86:87], v[4:5]
	v_pk_mul_f32 v[4:5], v[22:23], v[2:3] op_sel_hi:[1,0]
	v_pk_mul_f32 v[2:3], v[24:25], v[2:3] op_sel_hi:[1,0]
	v_pk_fma_f32 v[84:85], v[192:193], v[84:85], v[100:101]
	v_pk_fma_f32 v[2:3], v[28:29], v[98:99], v[2:3] op_sel_hi:[1,0,1]
	v_pk_fma_f32 v[4:5], v[26:27], v[98:99], v[4:5] op_sel_hi:[1,0,1]
	v_pk_fma_f32 v[92:93], v[194:195], v[92:93], v[2:3]
	v_pk_mul_f32 v[98:99], v[44:45], v[86:87]
	v_pk_fma_f32 v[88:89], v[192:193], v[88:89], v[4:5]
	v_pk_fma_f32 v[98:99], v[42:43], v[84:85], v[98:99]
	v_pk_mul_f32 v[44:45], v[44:45], v[92:93]
	v_pk_mul_f32 v[2:3], v[40:41], v[86:87]
	v_pk_fma_f32 v[42:43], v[42:43], v[88:89], v[44:45]
	v_add_f32_e32 v44, v98, v99
	v_add_f32_e32 v42, v42, v43
	s_waitcnt lgkmcnt(10)
	v_mov_b32_e32 v98, v97
	v_add_f32_dpp v44, v44, v44 row_ror:8 row_mask:0xf bank_mask:0xf bound_ctrl:1
	v_add_f32_dpp v42, v42, v42 row_ror:8 row_mask:0xf bank_mask:0xf bound_ctrl:1
	v_pk_mul_f32 v[4:5], v[40:41], v[92:93]
	v_add_f32_dpp v44, v44, v44 row_ror:4 row_mask:0xf bank_mask:0xf bound_ctrl:1
	v_add_f32_dpp v42, v42, v42 row_ror:4 row_mask:0xf bank_mask:0xf bound_ctrl:1
	v_pk_fma_f32 v[2:3], v[38:39], v[84:85], v[2:3]
	v_add_f32_dpp v44, v44, v44 row_ror:2 row_mask:0xf bank_mask:0xf bound_ctrl:1
	v_add_f32_dpp v42, v42, v42 row_ror:2 row_mask:0xf bank_mask:0xf bound_ctrl:1
	v_pk_fma_f32 v[4:5], v[38:39], v[88:89], v[4:5]
	v_add_f32_dpp v44, v44, v44 row_ror:1 row_mask:0xf bank_mask:0xf bound_ctrl:1
	v_pk_mul_f32 v[100:101], v[62:63], v[44:45] op_sel_hi:[1,0]
	v_pk_mul_f32 v[44:45], v[64:65], v[44:45] op_sel_hi:[1,0]
	v_add_f32_dpp v42, v42, v42 row_ror:1 row_mask:0xf bank_mask:0xf bound_ctrl:1
	v_pk_fma_f32 v[44:45], v[72:73], v[96:97], v[44:45] op_sel_hi:[1,0,1]
	v_pk_fma_f32 v[100:101], v[70:71], v[96:97], v[100:101] op_sel_hi:[1,0,1]
	s_waitcnt vmcnt(6)
	v_pk_fma_f32 v[86:87], v[198:199], v[86:87], v[44:45]
	v_pk_mul_f32 v[44:45], v[62:63], v[42:43] op_sel_hi:[1,0]
	v_pk_mul_f32 v[42:43], v[64:65], v[42:43] op_sel_hi:[1,0]
	v_pk_fma_f32 v[44:45], v[70:71], v[98:99], v[44:45] op_sel_hi:[1,0,1]
	v_pk_fma_f32 v[42:43], v[72:73], v[98:99], v[42:43] op_sel_hi:[1,0,1]
	v_pk_fma_f32 v[84:85], v[196:197], v[84:85], v[100:101]
	v_pk_fma_f32 v[92:93], v[198:199], v[92:93], v[42:43]
	v_pk_fma_f32 v[88:89], v[196:197], v[88:89], v[44:45]
	s_waitcnt lgkmcnt(9)
	v_pk_mul_f32 v[98:99], v[80:81], v[86:87]
	v_pk_mul_f32 v[80:81], v[80:81], v[92:93]
	v_pk_fma_f32 v[98:99], v[78:79], v[84:85], v[98:99]
	v_pk_fma_f32 v[78:79], v[78:79], v[88:89], v[80:81]
	v_add_f32_e32 v80, v98, v99
	v_add_f32_e32 v78, v78, v79
	s_waitcnt lgkmcnt(5)
	v_mov_b32_e32 v98, v83
	v_add_f32_dpp v80, v80, v80 row_ror:8 row_mask:0xf bank_mask:0xf bound_ctrl:1
	v_add_f32_dpp v78, v78, v78 row_ror:8 row_mask:0xf bank_mask:0xf bound_ctrl:1
	v_pk_mul_f32 v[44:45], v[76:77], v[92:93]
	v_add_f32_dpp v80, v80, v80 row_ror:4 row_mask:0xf bank_mask:0xf bound_ctrl:1
	v_add_f32_dpp v78, v78, v78 row_ror:4 row_mask:0xf bank_mask:0xf bound_ctrl:1
	v_add_f32_e32 v2, v2, v3
	v_add_f32_dpp v80, v80, v80 row_ror:2 row_mask:0xf bank_mask:0xf bound_ctrl:1
	v_add_f32_dpp v78, v78, v78 row_ror:2 row_mask:0xf bank_mask:0xf bound_ctrl:1
	v_add_f32_e32 v3, v4, v5
	v_add_f32_dpp v80, v80, v80 row_ror:1 row_mask:0xf bank_mask:0xf bound_ctrl:1
	v_add_f32_dpp v78, v78, v78 row_ror:1 row_mask:0xf bank_mask:0xf bound_ctrl:1
	v_pk_mul_f32 v[100:101], v[58:59], v[80:81] op_sel_hi:[1,0]
	v_pk_mul_f32 v[58:59], v[58:59], v[78:79] op_sel_hi:[1,0]
	v_pk_fma_f32 v[100:101], v[66:67], v[82:83], v[100:101] op_sel_hi:[1,0,1]
	v_pk_fma_f32 v[58:59], v[66:67], v[98:99], v[58:59] op_sel_hi:[1,0,1]
	s_waitcnt vmcnt(5)
	v_pk_fma_f32 v[100:101], v[200:201], v[84:85], v[100:101]
	v_pk_mul_f32 v[80:81], v[60:61], v[80:81] op_sel_hi:[1,0]
	v_pk_fma_f32 v[66:67], v[200:201], v[88:89], v[58:59]
	v_pk_mul_f32 v[46:47], v[60:61], v[78:79] op_sel_hi:[1,0]
	v_pk_fma_f32 v[80:81], v[68:69], v[82:83], v[80:81] op_sel_hi:[1,0,1]
	v_pk_fma_f32 v[46:47], v[68:69], v[98:99], v[46:47] op_sel_hi:[1,0,1]
	v_pk_fma_f32 v[80:81], v[202:203], v[86:87], v[80:81]
	v_pk_fma_f32 v[68:69], v[202:203], v[92:93], v[46:47]
	s_waitcnt lgkmcnt(4)
	v_pk_mul_f32 v[78:79], v[52:53], v[80:81]
	v_pk_mul_f32 v[52:53], v[52:53], v[68:69]
	v_pk_fma_f32 v[78:79], v[50:51], v[100:101], v[78:79]
	v_pk_fma_f32 v[50:51], v[50:51], v[66:67], v[52:53]
	v_add_f32_e32 v52, v78, v79
	v_add_f32_e32 v50, v50, v51
	s_waitcnt lgkmcnt(0)
	v_mov_b32_e32 v78, v91
	v_add_f32_dpp v52, v52, v52 row_ror:8 row_mask:0xf bank_mask:0xf bound_ctrl:1
	v_add_f32_dpp v50, v50, v50 row_ror:8 row_mask:0xf bank_mask:0xf bound_ctrl:1
	v_pk_mul_f32 v[46:47], v[12:13], v[80:81]
	v_add_f32_dpp v52, v52, v52 row_ror:4 row_mask:0xf bank_mask:0xf bound_ctrl:1
	v_add_f32_dpp v50, v50, v50 row_ror:4 row_mask:0xf bank_mask:0xf bound_ctrl:1
	v_pk_fma_f32 v[46:47], v[10:11], v[100:101], v[46:47]
	v_add_f32_dpp v52, v52, v52 row_ror:2 row_mask:0xf bank_mask:0xf bound_ctrl:1
	v_add_f32_dpp v50, v50, v50 row_ror:2 row_mask:0xf bank_mask:0xf bound_ctrl:1
	ds_write2st64_b32 v111, v2, v3 offset0:176 offset1:177
	v_add_f32_dpp v52, v52, v52 row_ror:1 row_mask:0xf bank_mask:0xf bound_ctrl:1
	v_add_f32_dpp v50, v50, v50 row_ror:1 row_mask:0xf bank_mask:0xf bound_ctrl:1
	v_pk_mul_f32 v[92:93], v[30:31], v[52:53] op_sel_hi:[1,0]
	v_pk_mul_f32 v[30:31], v[30:31], v[50:51] op_sel_hi:[1,0]
	v_pk_fma_f32 v[92:93], v[34:35], v[90:91], v[92:93] op_sel_hi:[1,0,1]
	v_pk_fma_f32 v[30:31], v[34:35], v[78:79], v[30:31] op_sel_hi:[1,0,1]
	s_waitcnt vmcnt(4)
	v_pk_fma_f32 v[100:101], v[204:205], v[100:101], v[92:93]
	v_pk_mul_f32 v[52:53], v[32:33], v[52:53] op_sel_hi:[1,0]
	v_pk_fma_f32 v[30:31], v[204:205], v[66:67], v[30:31]
	v_pk_mul_f32 v[14:15], v[32:33], v[50:51] op_sel_hi:[1,0]
	v_pk_fma_f32 v[52:53], v[36:37], v[90:91], v[52:53] op_sel_hi:[1,0,1]
	v_pk_fma_f32 v[14:15], v[36:37], v[78:79], v[14:15] op_sel_hi:[1,0,1]
	ds_read_b128 v[38:41], v118 offset:5120
	global_load_dwordx4 v[192:195], v118, s[56:57]
	s_add_u32 s56, s56, s58
	s_addc_u32 s57, s57, s59
	ds_read_b128 v[22:25], v118 offset:5632
	ds_read_b128 v[26:29], v118 offset:5888
	ds_read_b128 v[2:5], v118 offset:6144
	ds_read2_b32 v[94:95], v121 offset0:128 offset1:132
	v_pk_fma_f32 v[80:81], v[206:207], v[80:81], v[52:53]
	v_pk_fma_f32 v[32:33], v[206:207], v[68:69], v[14:15]
	s_waitcnt lgkmcnt(4)
	v_pk_mul_f32 v[78:79], v[40:41], v[80:81]
	v_pk_mul_f32 v[40:41], v[40:41], v[32:33]
	v_pk_fma_f32 v[78:79], v[38:39], v[100:101], v[78:79]
	v_pk_fma_f32 v[38:39], v[38:39], v[30:31], v[40:41]
	v_add_f32_e32 v40, v78, v79
	v_add_f32_e32 v38, v38, v39
	s_waitcnt lgkmcnt(0)
	v_mov_b32_e32 v78, v95
	v_add_f32_dpp v40, v40, v40 row_ror:8 row_mask:0xf bank_mask:0xf bound_ctrl:1
	v_add_f32_dpp v38, v38, v38 row_ror:8 row_mask:0xf bank_mask:0xf bound_ctrl:1
	v_pk_mul_f32 v[14:15], v[8:9], v[80:81]
	v_add_f32_dpp v40, v40, v40 row_ror:4 row_mask:0xf bank_mask:0xf bound_ctrl:1
	v_add_f32_dpp v38, v38, v38 row_ror:4 row_mask:0xf bank_mask:0xf bound_ctrl:1
	v_pk_mul_f32 v[42:43], v[76:77], v[86:87]
	v_add_f32_dpp v40, v40, v40 row_ror:2 row_mask:0xf bank_mask:0xf bound_ctrl:1
	v_add_f32_dpp v38, v38, v38 row_ror:2 row_mask:0xf bank_mask:0xf bound_ctrl:1
	v_pk_fma_f32 v[14:15], v[6:7], v[100:101], v[14:15]
	v_add_f32_dpp v40, v40, v40 row_ror:1 row_mask:0xf bank_mask:0xf bound_ctrl:1
	v_add_f32_dpp v38, v38, v38 row_ror:1 row_mask:0xf bank_mask:0xf bound_ctrl:1
	v_pk_mul_f32 v[90:91], v[22:23], v[40:41] op_sel_hi:[1,0]
	v_pk_mul_f32 v[22:23], v[22:23], v[38:39] op_sel_hi:[1,0]
	v_pk_fma_f32 v[90:91], v[26:27], v[94:95], v[90:91] op_sel_hi:[1,0,1]
	v_pk_mul_f32 v[40:41], v[24:25], v[40:41] op_sel_hi:[1,0]
	v_pk_fma_f32 v[22:23], v[26:27], v[78:79], v[22:23] op_sel_hi:[1,0,1]
	s_waitcnt vmcnt(4)
	v_pk_fma_f32 v[100:101], v[208:209], v[100:101], v[90:91]
	v_pk_fma_f32 v[40:41], v[28:29], v[94:95], v[40:41] op_sel_hi:[1,0,1]
	v_pk_fma_f32 v[94:95], v[208:209], v[30:31], v[22:23]
	v_pk_mul_f32 v[18:19], v[24:25], v[38:39] op_sel_hi:[1,0]
	v_pk_fma_f32 v[42:43], v[74:75], v[84:85], v[42:43]
	v_pk_fma_f32 v[44:45], v[74:75], v[88:89], v[44:45]
	v_pk_mul_f32 v[12:13], v[12:13], v[68:69]
	v_pk_fma_f32 v[18:19], v[28:29], v[78:79], v[18:19] op_sel_hi:[1,0,1]
	v_add_f32_e32 v42, v42, v43
	v_add_f32_e32 v43, v44, v45
	v_pk_fma_f32 v[10:11], v[10:11], v[66:67], v[12:13]
	v_pk_mul_f32 v[8:9], v[8:9], v[32:33]
	v_pk_fma_f32 v[80:81], v[210:211], v[80:81], v[40:41]
	v_pk_fma_f32 v[78:79], v[210:211], v[32:33], v[18:19]
	ds_write2st64_b32 v111, v42, v43 offset0:184 offset1:185
	v_add_f32_e32 v12, v46, v47
	v_add_f32_e32 v10, v10, v11
	v_pk_fma_f32 v[6:7], v[6:7], v[30:31], v[8:9]
	v_pk_mul_f32 v[18:19], v[4:5], v[80:81]
	v_pk_mul_f32 v[4:5], v[4:5], v[78:79]
	ds_read_b128 v[74:77], v118 offset:6400
	global_load_dwordx4 v[196:199], v118, s[56:57]
	s_add_u32 s56, s56, s58
	s_addc_u32 s57, s57, s59
	ds_read_b128 v[62:65], v118 offset:6912
	ds_read_b128 v[70:73], v118 offset:7168
	ds_read_b128 v[42:45], v118 offset:7424
	ds_read2_b32 v[96:97], v121 offset0:160 offset1:164
	ds_write2st64_b32 v111, v12, v10 offset0:192 offset1:193
	v_add_f32_e32 v8, v14, v15
	v_add_f32_e32 v6, v6, v7
	v_pk_fma_f32 v[18:19], v[2:3], v[100:101], v[18:19]
	v_pk_fma_f32 v[2:3], v[2:3], v[94:95], v[4:5]
	ds_read_b128 v[86:89], v118 offset:7680
	global_load_dwordx4 v[200:203], v118, s[56:57]
	s_add_u32 s56, s56, s58
	s_addc_u32 s57, s57, s59
	ds_read_b128 v[58:61], v118 offset:8192
	ds_read_b128 v[82:85], v118 offset:8448
	ds_read_b128 v[10:13], v118 offset:8704
	ds_read2_b32 v[98:99], v121 offset0:192 offset1:196
	ds_write2st64_b32 v111, v8, v6 offset0:200 offset1:201
	v_add_f32_e32 v4, v18, v19
	v_add_f32_e32 v2, v2, v3
	ds_read_b128 v[66:69], v118 offset:8960
	global_load_dwordx4 v[204:207], v118, s[56:57]
	s_add_u32 s56, s56, s58
	s_addc_u32 s57, s57, s59
	ds_read_b128 v[34:37], v118 offset:9472
	ds_read_b128 v[50:53], v118 offset:9728
	ds_read_b128 v[6:9], v118 offset:9984
	ds_read2_b32 v[92:93], v121 offset0:224 offset1:228
	ds_write2st64_b32 v111, v4, v2 offset0:208 offset1:209
	s_waitcnt lgkmcnt(12)
	v_pk_mul_f32 v[2:3], v[76:77], v[80:81]
	v_pk_mul_f32 v[4:5], v[76:77], v[78:79]
	v_pk_fma_f32 v[2:3], v[74:75], v[100:101], v[2:3]
	v_pk_fma_f32 v[4:5], v[74:75], v[94:95], v[4:5]
	v_add_f32_e32 v2, v2, v3
	v_add_f32_e32 v3, v4, v5
	v_mov_b32_e32 v74, v97
	v_add_f32_dpp v2, v2, v2 row_ror:8 row_mask:0xf bank_mask:0xf bound_ctrl:1
	v_add_f32_dpp v3, v3, v3 row_ror:8 row_mask:0xf bank_mask:0xf bound_ctrl:1
	s_waitcnt lgkmcnt(1)
	v_mov_b32_e32 v104, v93
	v_add_f32_dpp v2, v2, v2 row_ror:4 row_mask:0xf bank_mask:0xf bound_ctrl:1
	v_add_f32_dpp v3, v3, v3 row_ror:4 row_mask:0xf bank_mask:0xf bound_ctrl:1
	ds_read_b128 v[38:41], v118 offset:10240
	global_load_dwordx4 v[208:211], v118, s[56:57]
	s_add_u32 s56, s56, s58
	s_addc_u32 s57, s57, s59
	ds_read_b128 v[26:29], v118 offset:10752
	ds_read_b128 v[30:33], v118 offset:11008
	ds_read_b128 v[18:21], v118 offset:11264
	ds_read2_b32 v[90:91], v117 offset1:4
	v_add_f32_dpp v2, v2, v2 row_ror:2 row_mask:0xf bank_mask:0xf bound_ctrl:1
	v_add_f32_dpp v3, v3, v3 row_ror:2 row_mask:0xf bank_mask:0xf bound_ctrl:1
	s_nop 0
	v_add_f32_dpp v2, v2, v2 row_ror:1 row_mask:0xf bank_mask:0xf bound_ctrl:1
	v_add_f32_dpp v4, v3, v3 row_ror:1 row_mask:0xf bank_mask:0xf bound_ctrl:1
	v_pk_mul_f32 v[76:77], v[62:63], v[2:3] op_sel_hi:[1,0]
	v_pk_mul_f32 v[2:3], v[64:65], v[2:3] op_sel_hi:[1,0]
	v_pk_mul_f32 v[62:63], v[62:63], v[4:5] op_sel_hi:[1,0]
	v_pk_fma_f32 v[2:3], v[72:73], v[96:97], v[2:3] op_sel_hi:[1,0,1]
	v_pk_mul_f32 v[4:5], v[64:65], v[4:5] op_sel_hi:[1,0]
	v_pk_fma_f32 v[76:77], v[70:71], v[96:97], v[76:77] op_sel_hi:[1,0,1]
	s_waitcnt vmcnt(7)
	v_pk_fma_f32 v[2:3], v[214:215], v[80:81], v[2:3]
	v_pk_fma_f32 v[4:5], v[72:73], v[74:75], v[4:5] op_sel_hi:[1,0,1]
	v_pk_fma_f32 v[100:101], v[212:213], v[100:101], v[76:77]
	v_pk_fma_f32 v[62:63], v[70:71], v[74:75], v[62:63] op_sel_hi:[1,0,1]
	v_pk_fma_f32 v[4:5], v[214:215], v[78:79], v[4:5]
	v_pk_mul_f32 v[56:57], v[44:45], v[2:3]
	v_pk_fma_f32 v[54:55], v[212:213], v[94:95], v[62:63]
	v_pk_fma_f32 v[56:57], v[42:43], v[100:101], v[56:57]
	v_pk_mul_f32 v[44:45], v[44:45], v[4:5]
	s_nop 0
	v_pk_fma_f32 v[42:43], v[42:43], v[54:55], v[44:45]
	v_add_f32_e32 v44, v56, v57
	v_pk_mul_f32 v[56:57], v[88:89], v[2:3]
	v_pk_mul_f32 v[88:89], v[88:89], v[4:5]
	v_pk_fma_f32 v[56:57], v[86:87], v[100:101], v[56:57]
	v_pk_fma_f32 v[86:87], v[86:87], v[54:55], v[88:89]
	v_add_f32_e32 v56, v56, v57
	v_add_f32_e32 v57, v86, v87
	v_mov_b32_e32 v88, v99
	v_add_f32_dpp v56, v56, v56 row_ror:8 row_mask:0xf bank_mask:0xf bound_ctrl:1
	v_add_f32_dpp v57, v57, v57 row_ror:8 row_mask:0xf bank_mask:0xf bound_ctrl:1
	v_add_f32_e32 v42, v42, v43
	v_add_f32_dpp v56, v56, v56 row_ror:4 row_mask:0xf bank_mask:0xf bound_ctrl:1
	v_add_f32_dpp v57, v57, v57 row_ror:4 row_mask:0xf bank_mask:0xf bound_ctrl:1
	ds_write2st64_b32 v111, v44, v42 offset0:216 offset1:217
	v_add_f32_dpp v56, v56, v56 row_ror:2 row_mask:0xf bank_mask:0xf bound_ctrl:1
	v_add_f32_dpp v57, v57, v57 row_ror:2 row_mask:0xf bank_mask:0xf bound_ctrl:1
	ds_read_b128 v[78:81], v118 offset:11520
	global_load_dwordx4 v[212:215], v118, s[56:57]
	s_add_u32 s56, s56, s58
	s_addc_u32 s57, s57, s59
	ds_read_b128 v[70:73], v118 offset:12032
	ds_read_b128 v[74:77], v118 offset:12288
	ds_read_b128 v[42:45], v118 offset:12544
	ds_read2_b32 v[94:95], v117 offset0:32 offset1:36
	v_add_f32_dpp v56, v56, v56 row_ror:1 row_mask:0xf bank_mask:0xf bound_ctrl:1
	v_add_f32_dpp v86, v57, v57 row_ror:1 row_mask:0xf bank_mask:0xf bound_ctrl:1
	v_pk_mul_f32 v[96:97], v[58:59], v[56:57] op_sel_hi:[1,0]
	v_pk_mul_f32 v[56:57], v[60:61], v[56:57] op_sel_hi:[1,0]
	v_pk_fma_f32 v[96:97], v[82:83], v[98:99], v[96:97] op_sel_hi:[1,0,1]
	v_pk_fma_f32 v[56:57], v[84:85], v[98:99], v[56:57] op_sel_hi:[1,0,1]
	s_waitcnt vmcnt(7)
	v_pk_fma_f32 v[96:97], v[216:217], v[100:101], v[96:97]
	v_pk_fma_f32 v[98:99], v[218:219], v[2:3], v[56:57]
	v_pk_mul_f32 v[2:3], v[58:59], v[86:87] op_sel_hi:[1,0]
	s_nop 0
	v_pk_fma_f32 v[2:3], v[82:83], v[88:89], v[2:3] op_sel_hi:[1,0,1]
	s_nop 0
	v_pk_fma_f32 v[100:101], v[216:217], v[54:55], v[2:3]
	v_pk_mul_f32 v[2:3], v[60:61], v[86:87] op_sel_hi:[1,0]
	s_nop 0
	v_pk_fma_f32 v[2:3], v[84:85], v[88:89], v[2:3] op_sel_hi:[1,0,1]
	v_pk_mul_f32 v[84:85], v[68:69], v[98:99]
	v_pk_fma_f32 v[102:103], v[218:219], v[4:5], v[2:3]
	v_pk_fma_f32 v[84:85], v[66:67], v[96:97], v[84:85]
	v_pk_mul_f32 v[68:69], v[68:69], v[102:103]
	v_pk_mul_f32 v[2:3], v[12:13], v[98:99]
	v_pk_fma_f32 v[66:67], v[66:67], v[100:101], v[68:69]
	v_add_f32_e32 v68, v84, v85
	v_add_f32_e32 v66, v66, v67
	v_pk_fma_f32 v[2:3], v[10:11], v[96:97], v[2:3]
	v_add_f32_dpp v68, v68, v68 row_ror:8 row_mask:0xf bank_mask:0xf bound_ctrl:1
	v_add_f32_dpp v66, v66, v66 row_ror:8 row_mask:0xf bank_mask:0xf bound_ctrl:1
	v_pk_mul_f32 v[4:5], v[12:13], v[102:103]
	v_add_f32_dpp v68, v68, v68 row_ror:4 row_mask:0xf bank_mask:0xf bound_ctrl:1
	v_add_f32_dpp v66, v66, v66 row_ror:4 row_mask:0xf bank_mask:0xf bound_ctrl:1
	v_pk_fma_f32 v[4:5], v[10:11], v[100:101], v[4:5]
	v_add_f32_dpp v68, v68, v68 row_ror:2 row_mask:0xf bank_mask:0xf bound_ctrl:1
	v_add_f32_dpp v66, v66, v66 row_ror:2 row_mask:0xf bank_mask:0xf bound_ctrl:1
	v_add_f32_e32 v2, v2, v3
	v_add_f32_dpp v68, v68, v68 row_ror:1 row_mask:0xf bank_mask:0xf bound_ctrl:1
	v_add_f32_dpp v66, v66, v66 row_ror:1 row_mask:0xf bank_mask:0xf bound_ctrl:1
	v_pk_mul_f32 v[84:85], v[34:35], v[68:69] op_sel_hi:[1,0]
	v_pk_mul_f32 v[34:35], v[34:35], v[66:67] op_sel_hi:[1,0]
	v_pk_fma_f32 v[84:85], v[50:51], v[92:93], v[84:85] op_sel_hi:[1,0,1]
	v_pk_fma_f32 v[34:35], v[50:51], v[104:105], v[34:35] op_sel_hi:[1,0,1]
	s_waitcnt vmcnt(6)
	v_pk_fma_f32 v[84:85], v[220:221], v[96:97], v[84:85]
	v_pk_mul_f32 v[68:69], v[36:37], v[68:69] op_sel_hi:[1,0]
	v_pk_fma_f32 v[88:89], v[220:221], v[100:101], v[34:35]
	v_pk_mul_f32 v[14:15], v[36:37], v[66:67] op_sel_hi:[1,0]
	v_pk_fma_f32 v[68:69], v[52:53], v[92:93], v[68:69] op_sel_hi:[1,0,1]
	v_pk_fma_f32 v[14:15], v[52:53], v[104:105], v[14:15] op_sel_hi:[1,0,1]
	v_pk_fma_f32 v[86:87], v[222:223], v[98:99], v[68:69]
	v_pk_fma_f32 v[96:97], v[222:223], v[102:103], v[14:15]
	s_waitcnt lgkmcnt(10)
	v_pk_mul_f32 v[98:99], v[40:41], v[86:87]
	v_pk_mul_f32 v[40:41], v[40:41], v[96:97]
	v_pk_fma_f32 v[98:99], v[38:39], v[84:85], v[98:99]
	v_pk_fma_f32 v[38:39], v[38:39], v[88:89], v[40:41]
	v_add_f32_e32 v40, v98, v99
	v_add_f32_e32 v38, v38, v39
	s_waitcnt lgkmcnt(6)
	v_mov_b32_e32 v98, v91
	v_add_f32_dpp v40, v40, v40 row_ror:8 row_mask:0xf bank_mask:0xf bound_ctrl:1
	v_add_f32_dpp v38, v38, v38 row_ror:8 row_mask:0xf bank_mask:0xf bound_ctrl:1
	v_pk_mul_f32 v[14:15], v[8:9], v[86:87]
	v_add_f32_dpp v40, v40, v40 row_ror:4 row_mask:0xf bank_mask:0xf bound_ctrl:1
	v_add_f32_dpp v38, v38, v38 row_ror:4 row_mask:0xf bank_mask:0xf bound_ctrl:1
	v_pk_mul_f32 v[8:9], v[8:9], v[96:97]
	v_add_f32_dpp v40, v40, v40 row_ror:2 row_mask:0xf bank_mask:0xf bound_ctrl:1
	v_add_f32_dpp v38, v38, v38 row_ror:2 row_mask:0xf bank_mask:0xf bound_ctrl:1
	v_pk_fma_f32 v[14:15], v[6:7], v[84:85], v[14:15]
	v_add_f32_dpp v40, v40, v40 row_ror:1 row_mask:0xf bank_mask:0xf bound_ctrl:1
	v_add_f32_dpp v38, v38, v38 row_ror:1 row_mask:0xf bank_mask:0xf bound_ctrl:1
	v_pk_mul_f32 v[100:101], v[26:27], v[40:41] op_sel_hi:[1,0]
	v_pk_mul_f32 v[26:27], v[26:27], v[38:39] op_sel_hi:[1,0]
	v_pk_fma_f32 v[100:101], v[30:31], v[90:91], v[100:101] op_sel_hi:[1,0,1]
	v_pk_fma_f32 v[26:27], v[30:31], v[98:99], v[26:27] op_sel_hi:[1,0,1]
	v_pk_fma_f32 v[6:7], v[6:7], v[88:89], v[8:9]
	s_waitcnt vmcnt(5)
	v_pk_fma_f32 v[84:85], v[192:193], v[84:85], v[100:101]
	v_pk_mul_f32 v[40:41], v[28:29], v[40:41] op_sel_hi:[1,0]
	v_pk_fma_f32 v[88:89], v[192:193], v[88:89], v[26:27]
	v_pk_mul_f32 v[22:23], v[28:29], v[38:39] op_sel_hi:[1,0]
	v_pk_fma_f32 v[40:41], v[32:33], v[90:91], v[40:41] op_sel_hi:[1,0,1]
	v_pk_fma_f32 v[22:23], v[32:33], v[98:99], v[22:23] op_sel_hi:[1,0,1]
	v_pk_fma_f32 v[86:87], v[194:195], v[86:87], v[40:41]
	v_pk_fma_f32 v[96:97], v[194:195], v[96:97], v[22:23]
	s_waitcnt lgkmcnt(4)
	v_pk_mul_f32 v[98:99], v[80:81], v[86:87]
	v_pk_mul_f32 v[80:81], v[80:81], v[96:97]
	v_pk_fma_f32 v[98:99], v[78:79], v[84:85], v[98:99]
	v_pk_fma_f32 v[78:79], v[78:79], v[88:89], v[80:81]
	v_add_f32_e32 v80, v98, v99
	v_add_f32_e32 v78, v78, v79
	s_waitcnt lgkmcnt(0)
	v_mov_b32_e32 v98, v95
	v_add_f32_dpp v80, v80, v80 row_ror:8 row_mask:0xf bank_mask:0xf bound_ctrl:1
	v_add_f32_dpp v78, v78, v78 row_ror:8 row_mask:0xf bank_mask:0xf bound_ctrl:1
	v_pk_mul_f32 v[22:23], v[20:21], v[86:87]
	v_add_f32_dpp v80, v80, v80 row_ror:4 row_mask:0xf bank_mask:0xf bound_ctrl:1
	v_add_f32_dpp v78, v78, v78 row_ror:4 row_mask:0xf bank_mask:0xf bound_ctrl:1
	v_pk_mul_f32 v[20:21], v[20:21], v[96:97]
	v_add_f32_dpp v80, v80, v80 row_ror:2 row_mask:0xf bank_mask:0xf bound_ctrl:1
	v_add_f32_dpp v78, v78, v78 row_ror:2 row_mask:0xf bank_mask:0xf bound_ctrl:1
	v_add_f32_e32 v3, v4, v5
	v_add_f32_dpp v80, v80, v80 row_ror:1 row_mask:0xf bank_mask:0xf bound_ctrl:1
	v_add_f32_dpp v78, v78, v78 row_ror:1 row_mask:0xf bank_mask:0xf bound_ctrl:1
	v_pk_mul_f32 v[100:101], v[70:71], v[80:81] op_sel_hi:[1,0]
	v_pk_mul_f32 v[70:71], v[70:71], v[78:79] op_sel_hi:[1,0]
	v_pk_fma_f32 v[100:101], v[74:75], v[94:95], v[100:101] op_sel_hi:[1,0,1]
	v_pk_fma_f32 v[70:71], v[74:75], v[98:99], v[70:71] op_sel_hi:[1,0,1]
	v_pk_fma_f32 v[22:23], v[18:19], v[84:85], v[22:23]
	v_pk_fma_f32 v[18:19], v[18:19], v[88:89], v[20:21]
	s_waitcnt vmcnt(4)
	v_pk_fma_f32 v[84:85], v[196:197], v[84:85], v[100:101]
	v_pk_mul_f32 v[80:81], v[72:73], v[80:81] op_sel_hi:[1,0]
	v_pk_fma_f32 v[88:89], v[196:197], v[88:89], v[70:71]
	v_pk_mul_f32 v[62:63], v[72:73], v[78:79] op_sel_hi:[1,0]
	ds_write2st64_b32 v111, v2, v3 offset0:224 offset1:225
	v_pk_fma_f32 v[80:81], v[76:77], v[94:95], v[80:81] op_sel_hi:[1,0,1]
	v_pk_fma_f32 v[62:63], v[76:77], v[98:99], v[62:63] op_sel_hi:[1,0,1]
	ds_read_b128 v[10:13], v118 offset:12800
	global_load_dwordx4 v[216:219], v118, s[56:57]
	s_add_u32 s56, s56, s58
	s_addc_u32 s57, s57, s59
	ds_read_b128 v[46:49], v118 offset:13312
	ds_read_b128 v[58:61], v118 offset:13568
	ds_read_b128 v[54:57], v118 offset:13824
	ds_read2_b32 v[82:83], v117 offset0:64 offset1:68
	v_pk_fma_f32 v[86:87], v[198:199], v[86:87], v[80:81]
	v_pk_fma_f32 v[96:97], v[198:199], v[96:97], v[62:63]
	s_waitcnt lgkmcnt(4)
	v_pk_mul_f32 v[98:99], v[12:13], v[86:87]
	v_pk_mul_f32 v[12:13], v[12:13], v[96:97]
	v_pk_fma_f32 v[98:99], v[10:11], v[84:85], v[98:99]
	v_pk_fma_f32 v[10:11], v[10:11], v[88:89], v[12:13]
	v_add_f32_e32 v12, v98, v99
	v_add_f32_e32 v10, v10, v11
	s_waitcnt lgkmcnt(0)
	v_mov_b32_e32 v100, v83
	v_add_f32_dpp v12, v12, v12 row_ror:8 row_mask:0xf bank_mask:0xf bound_ctrl:1
	v_add_f32_dpp v10, v10, v10 row_ror:8 row_mask:0xf bank_mask:0xf bound_ctrl:1
	v_add_f32_e32 v8, v14, v15
	v_add_f32_dpp v12, v12, v12 row_ror:4 row_mask:0xf bank_mask:0xf bound_ctrl:1
	v_add_f32_dpp v10, v10, v10 row_ror:4 row_mask:0xf bank_mask:0xf bound_ctrl:1
	v_add_f32_e32 v6, v6, v7
	v_add_f32_dpp v12, v12, v12 row_ror:2 row_mask:0xf bank_mask:0xf bound_ctrl:1
	v_add_f32_dpp v10, v10, v10 row_ror:2 row_mask:0xf bank_mask:0xf bound_ctrl:1
	ds_write2st64_b32 v111, v8, v6 offset0:232 offset1:233
	v_add_f32_dpp v12, v12, v12 row_ror:1 row_mask:0xf bank_mask:0xf bound_ctrl:1
	v_add_f32_dpp v98, v10, v10 row_ror:1 row_mask:0xf bank_mask:0xf bound_ctrl:1
	v_pk_mul_f32 v[10:11], v[46:47], v[12:13] op_sel_hi:[1,0]
	v_pk_mul_f32 v[46:47], v[46:47], v[98:99] op_sel_hi:[1,0]
	v_pk_fma_f32 v[10:11], v[58:59], v[82:83], v[10:11] op_sel_hi:[1,0,1]
	v_pk_mul_f32 v[12:13], v[48:49], v[12:13] op_sel_hi:[1,0]
	v_pk_fma_f32 v[46:47], v[58:59], v[100:101], v[46:47] op_sel_hi:[1,0,1]
	s_waitcnt vmcnt(4)
	v_pk_fma_f32 v[10:11], v[200:201], v[84:85], v[10:11]
	v_pk_fma_f32 v[12:13], v[60:61], v[82:83], v[12:13] op_sel_hi:[1,0,1]
	v_pk_fma_f32 v[2:3], v[200:201], v[88:89], v[46:47]
	v_pk_mul_f32 v[46:47], v[48:49], v[98:99] op_sel_hi:[1,0]
	v_pk_fma_f32 v[12:13], v[202:203], v[86:87], v[12:13]
	v_pk_fma_f32 v[46:47], v[60:61], v[100:101], v[46:47] op_sel_hi:[1,0,1]
	ds_read_b128 v[6:9], v118 offset:14080
	global_load_dwordx4 v[220:223], v118, s[56:57]
	s_add_u32 s56, s56, s58
	s_addc_u32 s57, s57, s59
	ds_read_b128 v[34:37], v118 offset:14592
	ds_read_b128 v[50:53], v118 offset:14848
	ds_read_b128 v[66:69], v118 offset:15104
	ds_read2_b32 v[92:93], v117 offset0:96 offset1:100
	v_pk_fma_f32 v[4:5], v[202:203], v[96:97], v[46:47]
	s_waitcnt lgkmcnt(4)
	v_pk_mul_f32 v[98:99], v[8:9], v[12:13]
	v_pk_mul_f32 v[8:9], v[8:9], v[4:5]
	v_pk_fma_f32 v[98:99], v[6:7], v[10:11], v[98:99]
	v_pk_fma_f32 v[6:7], v[6:7], v[2:3], v[8:9]
	v_add_f32_e32 v8, v98, v99
	v_add_f32_e32 v6, v6, v7
	s_waitcnt lgkmcnt(0)
	v_mov_b32_e32 v102, v93
	v_add_f32_dpp v8, v8, v8 row_ror:8 row_mask:0xf bank_mask:0xf bound_ctrl:1
	v_add_f32_dpp v6, v6, v6 row_ror:8 row_mask:0xf bank_mask:0xf bound_ctrl:1
	v_pk_mul_f32 v[48:49], v[56:57], v[4:5]
	v_add_f32_dpp v8, v8, v8 row_ror:4 row_mask:0xf bank_mask:0xf bound_ctrl:1
	v_add_f32_dpp v6, v6, v6 row_ror:4 row_mask:0xf bank_mask:0xf bound_ctrl:1
	v_pk_fma_f32 v[48:49], v[54:55], v[2:3], v[48:49]
	v_add_f32_dpp v8, v8, v8 row_ror:2 row_mask:0xf bank_mask:0xf bound_ctrl:1
	v_add_f32_dpp v6, v6, v6 row_ror:2 row_mask:0xf bank_mask:0xf bound_ctrl:1
	v_add_f32_e32 v20, v22, v23
	v_add_f32_dpp v8, v8, v8 row_ror:1 row_mask:0xf bank_mask:0xf bound_ctrl:1
	v_pk_mul_f32 v[98:99], v[34:35], v[8:9] op_sel_hi:[1,0]
	v_pk_mul_f32 v[8:9], v[36:37], v[8:9] op_sel_hi:[1,0]
	v_add_f32_dpp v6, v6, v6 row_ror:1 row_mask:0xf bank_mask:0xf bound_ctrl:1
	v_pk_fma_f32 v[8:9], v[52:53], v[92:93], v[8:9] op_sel_hi:[1,0,1]
	v_pk_fma_f32 v[98:99], v[50:51], v[92:93], v[98:99] op_sel_hi:[1,0,1]
	s_waitcnt vmcnt(4)
	v_pk_fma_f32 v[92:93], v[206:207], v[12:13], v[8:9]
	v_pk_mul_f32 v[8:9], v[34:35], v[6:7] op_sel_hi:[1,0]
	v_add_f32_e32 v18, v18, v19
	v_pk_fma_f32 v[8:9], v[50:51], v[102:103], v[8:9] op_sel_hi:[1,0,1]
	ds_write2st64_b32 v111, v20, v18 offset0:240 offset1:241
	v_pk_fma_f32 v[100:101], v[204:205], v[2:3], v[8:9]
	v_pk_mul_f32 v[2:3], v[36:37], v[6:7] op_sel_hi:[1,0]
	ds_read_b128 v[38:41], v118 offset:15360
	global_load_dwordx4 v[192:195], v118, s[56:57]
	s_add_u32 s56, s56, s58
	s_addc_u32 s57, s57, s59
	ds_read_b128 v[22:25], v118 offset:15872
	ds_read_b128 v[26:29], v118 offset:16128
	ds_read_b128 v[30:33], v118 offset:16384
	ds_read2_b32 v[90:91], v117 offset0:128 offset1:132
	v_pk_fma_f32 v[2:3], v[52:53], v[102:103], v[2:3] op_sel_hi:[1,0,1]
	v_pk_fma_f32 v[98:99], v[204:205], v[10:11], v[98:99]
	v_pk_fma_f32 v[52:53], v[206:207], v[4:5], v[2:3]
	v_pk_mul_f32 v[2:3], v[68:69], v[92:93]
	v_pk_mul_f32 v[4:5], v[68:69], v[52:53]
	v_pk_fma_f32 v[2:3], v[66:67], v[98:99], v[2:3]
	v_pk_fma_f32 v[4:5], v[66:67], v[100:101], v[4:5]
	s_waitcnt lgkmcnt(4)
	v_pk_mul_f32 v[66:67], v[40:41], v[92:93]
	v_pk_mul_f32 v[40:41], v[40:41], v[52:53]
	v_pk_fma_f32 v[66:67], v[38:39], v[98:99], v[66:67]
	v_pk_fma_f32 v[38:39], v[38:39], v[100:101], v[40:41]
	v_add_f32_e32 v40, v66, v67
	v_add_f32_e32 v38, v38, v39
	s_waitcnt lgkmcnt(0)
	v_mov_b32_e32 v66, v91
	v_add_f32_dpp v40, v40, v40 row_ror:8 row_mask:0xf bank_mask:0xf bound_ctrl:1
	v_add_f32_dpp v38, v38, v38 row_ror:8 row_mask:0xf bank_mask:0xf bound_ctrl:1
	v_pk_mul_f32 v[62:63], v[44:45], v[86:87]
	v_add_f32_dpp v40, v40, v40 row_ror:4 row_mask:0xf bank_mask:0xf bound_ctrl:1
	v_add_f32_dpp v38, v38, v38 row_ror:4 row_mask:0xf bank_mask:0xf bound_ctrl:1
	v_pk_mul_f32 v[44:45], v[44:45], v[96:97]
	v_add_f32_dpp v40, v40, v40 row_ror:2 row_mask:0xf bank_mask:0xf bound_ctrl:1
	v_add_f32_dpp v38, v38, v38 row_ror:2 row_mask:0xf bank_mask:0xf bound_ctrl:1
	v_pk_fma_f32 v[62:63], v[42:43], v[84:85], v[62:63]
	v_add_f32_dpp v40, v40, v40 row_ror:1 row_mask:0xf bank_mask:0xf bound_ctrl:1
	v_add_f32_dpp v38, v38, v38 row_ror:1 row_mask:0xf bank_mask:0xf bound_ctrl:1
	v_pk_mul_f32 v[68:69], v[22:23], v[40:41] op_sel_hi:[1,0]
	v_pk_mul_f32 v[22:23], v[22:23], v[38:39] op_sel_hi:[1,0]
	v_pk_fma_f32 v[68:69], v[26:27], v[90:91], v[68:69] op_sel_hi:[1,0,1]
	v_pk_fma_f32 v[22:23], v[26:27], v[66:67], v[22:23] op_sel_hi:[1,0,1]
	s_waitcnt vmcnt(4)
	v_pk_fma_f32 v[68:69], v[208:209], v[98:99], v[68:69]
	v_pk_mul_f32 v[40:41], v[24:25], v[40:41] op_sel_hi:[1,0]
	v_pk_fma_f32 v[18:19], v[208:209], v[100:101], v[22:23]
	v_pk_mul_f32 v[22:23], v[24:25], v[38:39] op_sel_hi:[1,0]
	v_pk_fma_f32 v[42:43], v[42:43], v[88:89], v[44:45]
	v_pk_mul_f32 v[46:47], v[56:57], v[12:13]
	v_pk_fma_f32 v[40:41], v[28:29], v[90:91], v[40:41] op_sel_hi:[1,0,1]
	v_pk_fma_f32 v[22:23], v[28:29], v[66:67], v[22:23] op_sel_hi:[1,0,1]
	v_add_f32_e32 v44, v62, v63
	v_add_f32_e32 v42, v42, v43
	v_pk_fma_f32 v[46:47], v[54:55], v[10:11], v[46:47]
	v_pk_fma_f32 v[40:41], v[210:211], v[92:93], v[40:41]
	v_pk_fma_f32 v[20:21], v[210:211], v[52:53], v[22:23]
	ds_write2st64_b32 v111, v44, v42 offset0:248 offset1:249
	v_add_f32_e32 v46, v46, v47
	v_add_f32_e32 v47, v48, v49
	v_pk_mul_f32 v[22:23], v[32:33], v[40:41]
	v_pk_mul_f32 v[24:25], v[32:33], v[20:21]
	ds_read_b128 v[78:81], v118 offset:16640
	global_load_dwordx4 v[196:199], v118, s[56:57]
	s_add_u32 s56, s56, s58
	s_addc_u32 s57, s57, s59
	ds_read_b128 v[62:65], v118 offset:17152
	ds_read_b128 v[70:73], v118 offset:17408
	ds_read_b128 v[74:77], v118 offset:17664
	ds_read2_b32 v[94:95], v117 offset0:160 offset1:164
	ds_write2st64_b32 v112, v46, v47 offset0:80 offset1:81
	v_add_f32_e32 v2, v2, v3
	v_add_f32_e32 v3, v4, v5
	v_pk_fma_f32 v[22:23], v[30:31], v[68:69], v[22:23]
	v_pk_fma_f32 v[24:25], v[30:31], v[18:19], v[24:25]
	ds_read_b128 v[86:89], v118 offset:17920
	global_load_dwordx4 v[200:203], v118, s[56:57]
	s_add_u32 s56, s56, s58
	s_addc_u32 s57, s57, s59
	ds_read_b128 v[54:57], v118 offset:18432
	ds_read_b128 v[58:61], v118 offset:18688
	ds_read_b128 v[82:85], v118 offset:18944
	ds_read2_b32 v[96:97], v117 offset0:192 offset1:196
	ds_write2st64_b32 v112, v2, v3 offset0:88 offset1:89
	v_add_f32_e32 v22, v22, v23
	v_add_f32_e32 v23, v24, v25
	ds_read_b128 v[34:37], v118 offset:19200
	global_load_dwordx4 v[204:207], v118, s[56:57]
	s_add_u32 s56, s56, s58
	s_addc_u32 s57, s57, s59
	ds_read_b128 v[6:9], v118 offset:19712
	ds_read_b128 v[14:17], v118 offset:19968
	ds_read_b128 v[10:13], v118 offset:20224
	ds_read2_b32 v[50:51], v117 offset0:224 offset1:228
	ds_write2st64_b32 v112, v22, v23 offset0:96 offset1:97
	s_waitcnt lgkmcnt(12)
	v_pk_mul_f32 v[22:23], v[80:81], v[40:41]
	v_pk_mul_f32 v[24:25], v[80:81], v[20:21]
	v_pk_fma_f32 v[22:23], v[78:79], v[68:69], v[22:23]
	v_pk_fma_f32 v[24:25], v[78:79], v[18:19], v[24:25]
	v_add_f32_e32 v22, v22, v23
	v_add_f32_e32 v23, v24, v25
	v_mov_b32_e32 v26, v95
	v_add_f32_dpp v22, v22, v22 row_ror:8 row_mask:0xf bank_mask:0xf bound_ctrl:1
	v_add_f32_dpp v23, v23, v23 row_ror:8 row_mask:0xf bank_mask:0xf bound_ctrl:1
	s_waitcnt lgkmcnt(7)
	v_mov_b32_e32 v32, v97
	v_add_f32_dpp v22, v22, v22 row_ror:4 row_mask:0xf bank_mask:0xf bound_ctrl:1
	v_add_f32_dpp v23, v23, v23 row_ror:4 row_mask:0xf bank_mask:0xf bound_ctrl:1
	s_nop 0
	v_add_f32_dpp v22, v22, v22 row_ror:2 row_mask:0xf bank_mask:0xf bound_ctrl:1
	v_add_f32_dpp v23, v23, v23 row_ror:2 row_mask:0xf bank_mask:0xf bound_ctrl:1
	s_nop 0
	v_add_f32_dpp v22, v22, v22 row_ror:1 row_mask:0xf bank_mask:0xf bound_ctrl:1
	v_add_f32_dpp v24, v23, v23 row_ror:1 row_mask:0xf bank_mask:0xf bound_ctrl:1
	v_pk_mul_f32 v[28:29], v[62:63], v[22:23] op_sel_hi:[1,0]
	v_pk_mul_f32 v[22:23], v[64:65], v[22:23] op_sel_hi:[1,0]
	v_pk_mul_f32 v[30:31], v[62:63], v[24:25] op_sel_hi:[1,0]
	v_pk_mul_f32 v[24:25], v[64:65], v[24:25] op_sel_hi:[1,0]
	v_pk_fma_f32 v[22:23], v[72:73], v[94:95], v[22:23] op_sel_hi:[1,0,1]
	v_pk_fma_f32 v[24:25], v[72:73], v[26:27], v[24:25] op_sel_hi:[1,0,1]
	v_pk_fma_f32 v[28:29], v[70:71], v[94:95], v[28:29] op_sel_hi:[1,0,1]
	s_waitcnt vmcnt(6)
	v_pk_fma_f32 v[22:23], v[214:215], v[40:41], v[22:23]
	v_pk_fma_f32 v[30:31], v[70:71], v[26:27], v[30:31] op_sel_hi:[1,0,1]
	v_pk_fma_f32 v[26:27], v[214:215], v[20:21], v[24:25]
	v_pk_fma_f32 v[28:29], v[212:213], v[68:69], v[28:29]
	v_pk_fma_f32 v[18:19], v[212:213], v[18:19], v[30:31]
	v_pk_mul_f32 v[20:21], v[76:77], v[22:23]
	v_pk_mul_f32 v[24:25], v[76:77], v[26:27]
	v_pk_fma_f32 v[20:21], v[74:75], v[28:29], v[20:21]
	v_pk_fma_f32 v[24:25], v[74:75], v[18:19], v[24:25]
	v_add_f32_e32 v20, v20, v21
	v_add_f32_e32 v21, v24, v25
	ds_write2st64_b32 v112, v20, v21 offset0:104 offset1:105
	v_pk_mul_f32 v[20:21], v[88:89], v[22:23]
	v_pk_mul_f32 v[24:25], v[88:89], v[26:27]
	v_pk_fma_f32 v[20:21], v[86:87], v[28:29], v[20:21]
	v_pk_fma_f32 v[24:25], v[86:87], v[18:19], v[24:25]
	v_add_f32_e32 v20, v20, v21
	v_add_f32_e32 v21, v24, v25
	s_nop 0
	v_add_f32_dpp v20, v20, v20 row_ror:8 row_mask:0xf bank_mask:0xf bound_ctrl:1
	v_add_f32_dpp v21, v21, v21 row_ror:8 row_mask:0xf bank_mask:0xf bound_ctrl:1
	s_nop 0
	v_add_f32_dpp v20, v20, v20 row_ror:4 row_mask:0xf bank_mask:0xf bound_ctrl:1
	v_add_f32_dpp v21, v21, v21 row_ror:4 row_mask:0xf bank_mask:0xf bound_ctrl:1
	s_nop 0
	v_add_f32_dpp v20, v20, v20 row_ror:2 row_mask:0xf bank_mask:0xf bound_ctrl:1
	v_add_f32_dpp v21, v21, v21 row_ror:2 row_mask:0xf bank_mask:0xf bound_ctrl:1
	s_nop 0
	v_add_f32_dpp v20, v20, v20 row_ror:1 row_mask:0xf bank_mask:0xf bound_ctrl:1
	v_add_f32_dpp v30, v21, v21 row_ror:1 row_mask:0xf bank_mask:0xf bound_ctrl:1
	v_pk_mul_f32 v[24:25], v[54:55], v[20:21] op_sel_hi:[1,0]
	v_pk_mul_f32 v[20:21], v[56:57], v[20:21] op_sel_hi:[1,0]
	v_pk_fma_f32 v[24:25], v[58:59], v[96:97], v[24:25] op_sel_hi:[1,0,1]
	v_pk_fma_f32 v[20:21], v[60:61], v[96:97], v[20:21] op_sel_hi:[1,0,1]
	s_waitcnt vmcnt(5)
	v_pk_fma_f32 v[24:25], v[216:217], v[28:29], v[24:25]
	v_pk_fma_f32 v[22:23], v[218:219], v[22:23], v[20:21]
	v_pk_mul_f32 v[20:21], v[54:55], v[30:31] op_sel_hi:[1,0]
	s_nop 0
	v_pk_fma_f32 v[20:21], v[58:59], v[32:33], v[20:21] op_sel_hi:[1,0,1]
	s_nop 0
	v_pk_fma_f32 v[20:21], v[216:217], v[18:19], v[20:21]
	v_pk_mul_f32 v[18:19], v[56:57], v[30:31] op_sel_hi:[1,0]
	s_nop 0
	v_pk_fma_f32 v[18:19], v[60:61], v[32:33], v[18:19] op_sel_hi:[1,0,1]
	s_nop 0
	v_pk_fma_f32 v[18:19], v[218:219], v[26:27], v[18:19]
	v_pk_mul_f32 v[26:27], v[84:85], v[22:23]
	v_pk_mul_f32 v[28:29], v[84:85], v[18:19]
	v_pk_fma_f32 v[26:27], v[82:83], v[24:25], v[26:27]
	v_pk_fma_f32 v[28:29], v[82:83], v[20:21], v[28:29]
	v_add_f32_e32 v26, v26, v27
	v_add_f32_e32 v27, v28, v29
	ds_write2st64_b32 v112, v26, v27 offset0:112 offset1:113
	s_waitcnt lgkmcnt(7)
	v_pk_mul_f32 v[26:27], v[36:37], v[22:23]
	v_pk_mul_f32 v[28:29], v[36:37], v[18:19]
	v_pk_fma_f32 v[26:27], v[34:35], v[24:25], v[26:27]
	v_pk_fma_f32 v[30:31], v[34:35], v[20:21], v[28:29]
	v_add_f32_e32 v26, v26, v27
	s_nop 1
	v_add_f32_dpp v26, v26, v26 row_ror:8 row_mask:0xf bank_mask:0xf bound_ctrl:1
	s_nop 1
	v_add_f32_dpp v26, v26, v26 row_ror:4 row_mask:0xf bank_mask:0xf bound_ctrl:1
	s_nop 1
	v_add_f32_dpp v26, v26, v26 row_ror:2 row_mask:0xf bank_mask:0xf bound_ctrl:1
	s_nop 1
	v_add_f32_dpp v28, v26, v26 row_ror:1 row_mask:0xf bank_mask:0xf bound_ctrl:1
	v_add_f32_e32 v26, v30, v31
	s_waitcnt lgkmcnt(3)
	v_mov_b32_e32 v30, v51
	v_pk_mul_f32 v[32:33], v[6:7], v[28:29] op_sel_hi:[1,0]
	v_add_f32_dpp v26, v26, v26 row_ror:8 row_mask:0xf bank_mask:0xf bound_ctrl:1
	v_pk_fma_f32 v[32:33], v[14:15], v[50:51], v[32:33] op_sel_hi:[1,0,1]
	s_nop 0
	v_add_f32_dpp v26, v26, v26 row_ror:4 row_mask:0xf bank_mask:0xf bound_ctrl:1
	s_waitcnt vmcnt(4)
	v_pk_fma_f32 v[76:77], v[220:221], v[24:25], v[32:33]
	v_pk_mul_f32 v[24:25], v[8:9], v[28:29] op_sel_hi:[1,0]
	v_add_f32_dpp v26, v26, v26 row_ror:2 row_mask:0xf bank_mask:0xf bound_ctrl:1
	v_pk_fma_f32 v[24:25], v[16:17], v[50:51], v[24:25] op_sel_hi:[1,0,1]
	s_nop 0
	v_add_f32_dpp v26, v26, v26 row_ror:1 row_mask:0xf bank_mask:0xf bound_ctrl:1
	v_pk_mul_f32 v[6:7], v[6:7], v[26:27] op_sel_hi:[1,0]
	v_pk_fma_f32 v[78:79], v[222:223], v[22:23], v[24:25]
	v_pk_fma_f32 v[6:7], v[14:15], v[30:31], v[6:7] op_sel_hi:[1,0,1]
	s_nop 0
	v_pk_fma_f32 v[80:81], v[220:221], v[20:21], v[6:7]
	v_pk_mul_f32 v[2:3], v[8:9], v[26:27] op_sel_hi:[1,0]
	s_nop 0
	v_pk_fma_f32 v[2:3], v[16:17], v[30:31], v[2:3] op_sel_hi:[1,0,1]
	s_nop 0
	v_pk_fma_f32 v[92:93], v[222:223], v[18:19], v[2:3]
	v_pk_mul_f32 v[2:3], v[12:13], v[78:79]
	v_pk_mul_f32 v[4:5], v[12:13], v[92:93]
	v_pk_fma_f32 v[2:3], v[10:11], v[76:77], v[2:3]
	v_pk_fma_f32 v[4:5], v[10:11], v[80:81], v[4:5]
	v_add_f32_e32 v2, v2, v3
	v_add_f32_e32 v3, v4, v5
	ds_write2st64_b32 v112, v2, v3 offset0:120 offset1:121
	s_waitcnt lgkmcnt(0)
	s_barrier
	ds_read_b128 v[10:13], v118 offset:20480
	global_load_dwordx4 v[208:211], v118, s[56:57]
	s_add_u32 s56, s56, s58
	s_addc_u32 s57, s57, s59
	ds_read_b128 v[22:25], v118 offset:20992
	ds_read_b128 v[26:29], v118 offset:21248
	ds_read_b128 v[46:49], v118 offset:21504
	ds_read2_b32 v[94:95], v120 offset1:4
	ds_read_b128 v[50:53], v118 offset:21760
	global_load_dwordx4 v[212:215], v118, s[56:57]
	s_add_u32 s56, s56, s58
	s_addc_u32 s57, s57, s59
	ds_read_b128 v[72:75], v118 offset:22272
	ds_read_b128 v[82:85], v118 offset:22528
	ds_read_b128 v[86:89], v118 offset:22784
	ds_read2_b32 v[96:97], v120 offset0:32 offset1:36
	ds_read_b128 v[62:65], v118 offset:23040
	global_load_dwordx4 v[216:219], v118, s[56:57]
	s_add_u32 s56, s56, s58
	s_addc_u32 s57, s57, s59
	ds_read_b128 v[54:57], v118 offset:23552
	ds_read_b128 v[58:61], v118 offset:23808
	ds_read_b128 v[14:17], v118 offset:24064
	ds_read2_b32 v[66:67], v120 offset0:64 offset1:68
	ds_read_b128 v[42:45], v118 offset:24320
	global_load_dwordx4 v[220:223], v118, s[56:57]
	s_add_u32 s56, s56, s58
	s_addc_u32 s57, s57, s59
	ds_read_b128 v[30:33], v118 offset:24832
	ds_read_b128 v[34:37], v118 offset:25088
	ds_read_b128 v[2:5], v118 offset:25344
	ds_read2_b32 v[90:91], v120 offset0:96 offset1:100
	s_waitcnt lgkmcnt(12)
	v_pk_mul_f32 v[98:99], v[12:13], v[78:79]
	v_pk_mul_f32 v[12:13], v[12:13], v[92:93]
	v_pk_fma_f32 v[98:99], v[10:11], v[76:77], v[98:99]
	v_pk_fma_f32 v[10:11], v[10:11], v[80:81], v[12:13]
	v_add_f32_e32 v12, v98, v99
	v_add_f32_e32 v10, v10, v11
	v_mov_b32_e32 v98, v95
	v_add_f32_dpp v12, v12, v12 row_ror:8 row_mask:0xf bank_mask:0xf bound_ctrl:1
	v_add_f32_dpp v10, v10, v10 row_ror:8 row_mask:0xf bank_mask:0xf bound_ctrl:1
	s_nop 0
	v_add_f32_dpp v12, v12, v12 row_ror:4 row_mask:0xf bank_mask:0xf bound_ctrl:1
	v_add_f32_dpp v10, v10, v10 row_ror:4 row_mask:0xf bank_mask:0xf bound_ctrl:1
	s_nop 0
	v_add_f32_dpp v12, v12, v12 row_ror:2 row_mask:0xf bank_mask:0xf bound_ctrl:1
	v_add_f32_dpp v10, v10, v10 row_ror:2 row_mask:0xf bank_mask:0xf bound_ctrl:1
	s_nop 0
	v_add_f32_dpp v12, v12, v12 row_ror:1 row_mask:0xf bank_mask:0xf bound_ctrl:1
	v_pk_mul_f32 v[100:101], v[22:23], v[12:13] op_sel_hi:[1,0]
	v_pk_mul_f32 v[12:13], v[24:25], v[12:13] op_sel_hi:[1,0]
	v_add_f32_dpp v10, v10, v10 row_ror:1 row_mask:0xf bank_mask:0xf bound_ctrl:1
	v_pk_fma_f32 v[100:101], v[26:27], v[94:95], v[100:101] op_sel_hi:[1,0,1]
	v_pk_fma_f32 v[12:13], v[28:29], v[94:95], v[12:13] op_sel_hi:[1,0,1]
	s_waitcnt vmcnt(7)
	v_pk_fma_f32 v[76:77], v[192:193], v[76:77], v[100:101]
	v_pk_fma_f32 v[100:101], v[194:195], v[78:79], v[12:13]
	v_pk_mul_f32 v[12:13], v[22:23], v[10:11] op_sel_hi:[1,0]
	v_pk_mul_f32 v[10:11], v[24:25], v[10:11] op_sel_hi:[1,0]
	v_pk_fma_f32 v[12:13], v[26:27], v[98:99], v[12:13] op_sel_hi:[1,0,1]
	v_pk_fma_f32 v[10:11], v[28:29], v[98:99], v[10:11] op_sel_hi:[1,0,1]
	v_pk_fma_f32 v[102:103], v[192:193], v[80:81], v[12:13]
	v_pk_fma_f32 v[92:93], v[194:195], v[92:93], v[10:11]
	v_pk_mul_f32 v[10:11], v[48:49], v[100:101]
	v_pk_mul_f32 v[12:13], v[48:49], v[92:93]
	v_pk_fma_f32 v[10:11], v[46:47], v[76:77], v[10:11]
	v_pk_fma_f32 v[12:13], v[46:47], v[102:103], v[12:13]
	v_pk_mul_f32 v[46:47], v[52:53], v[100:101]
	v_pk_mul_f32 v[48:49], v[52:53], v[92:93]
	v_pk_fma_f32 v[46:47], v[50:51], v[76:77], v[46:47]
	v_pk_fma_f32 v[48:49], v[50:51], v[102:103], v[48:49]
	v_add_f32_e32 v46, v46, v47
	v_add_f32_e32 v47, v48, v49
	s_waitcnt lgkmcnt(10)
	v_mov_b32_e32 v50, v97
	v_add_f32_dpp v46, v46, v46 row_ror:8 row_mask:0xf bank_mask:0xf bound_ctrl:1
	v_add_f32_dpp v47, v47, v47 row_ror:8 row_mask:0xf bank_mask:0xf bound_ctrl:1
	v_add_f32_e32 v10, v10, v11
	v_add_f32_dpp v46, v46, v46 row_ror:4 row_mask:0xf bank_mask:0xf bound_ctrl:1
	v_add_f32_dpp v47, v47, v47 row_ror:4 row_mask:0xf bank_mask:0xf bound_ctrl:1
	v_add_f32_e32 v11, v12, v13
	v_add_f32_dpp v46, v46, v46 row_ror:2 row_mask:0xf bank_mask:0xf bound_ctrl:1
	v_add_f32_dpp v47, v47, v47 row_ror:2 row_mask:0xf bank_mask:0xf bound_ctrl:1
	ds_write2st64_b32 v113, v10, v11 offset1:1
	v_add_f32_dpp v46, v46, v46 row_ror:1 row_mask:0xf bank_mask:0xf bound_ctrl:1
	v_add_f32_dpp v48, v47, v47 row_ror:1 row_mask:0xf bank_mask:0xf bound_ctrl:1
	v_pk_mul_f32 v[52:53], v[72:73], v[46:47] op_sel_hi:[1,0]
	v_pk_mul_f32 v[46:47], v[74:75], v[46:47] op_sel_hi:[1,0]
	v_pk_fma_f32 v[52:53], v[82:83], v[96:97], v[52:53] op_sel_hi:[1,0,1]
	v_pk_fma_f32 v[46:47], v[84:85], v[96:97], v[46:47] op_sel_hi:[1,0,1]
	s_waitcnt vmcnt(6)
	v_pk_fma_f32 v[98:99], v[196:197], v[76:77], v[52:53]
	v_pk_fma_f32 v[100:101], v[198:199], v[100:101], v[46:47]
	v_pk_mul_f32 v[46:47], v[72:73], v[48:49] op_sel_hi:[1,0]
	ds_read_b128 v[78:81], v118 offset:25600
	global_load_dwordx4 v[192:195], v118, s[56:57]
	s_add_u32 s56, s56, s58
	s_addc_u32 s57, s57, s59
	ds_read_b128 v[22:25], v118 offset:26112
	ds_read_b128 v[26:29], v118 offset:26368
	ds_read_b128 v[10:13], v118 offset:26624
	ds_read2_b32 v[94:95], v120 offset0:128 offset1:132
	v_pk_fma_f32 v[46:47], v[82:83], v[50:51], v[46:47] op_sel_hi:[1,0,1]
	s_nop 0
	v_pk_fma_f32 v[68:69], v[196:197], v[102:103], v[46:47]
	v_pk_mul_f32 v[46:47], v[74:75], v[48:49] op_sel_hi:[1,0]
	s_nop 0
	v_pk_fma_f32 v[46:47], v[84:85], v[50:51], v[46:47] op_sel_hi:[1,0,1]
	s_waitcnt lgkmcnt(12)
	v_pk_mul_f32 v[84:85], v[64:65], v[100:101]
	v_pk_fma_f32 v[82:83], v[198:199], v[92:93], v[46:47]
	v_pk_fma_f32 v[84:85], v[62:63], v[98:99], v[84:85]
	v_pk_mul_f32 v[64:65], v[64:65], v[82:83]
	v_pk_mul_f32 v[46:47], v[88:89], v[100:101]
	v_pk_fma_f32 v[62:63], v[62:63], v[68:69], v[64:65]
	v_add_f32_e32 v64, v84, v85
	v_add_f32_e32 v62, v62, v63
	s_waitcnt lgkmcnt(11)
	v_mov_b32_e32 v84, v67
	v_add_f32_dpp v64, v64, v64 row_ror:8 row_mask:0xf bank_mask:0xf bound_ctrl:1
	v_add_f32_dpp v62, v62, v62 row_ror:8 row_mask:0xf bank_mask:0xf bound_ctrl:1
	v_pk_mul_f32 v[48:49], v[88:89], v[82:83]
	v_add_f32_dpp v64, v64, v64 row_ror:4 row_mask:0xf bank_mask:0xf bound_ctrl:1
	v_add_f32_dpp v62, v62, v62 row_ror:4 row_mask:0xf bank_mask:0xf bound_ctrl:1
	v_pk_fma_f32 v[46:47], v[86:87], v[98:99], v[46:47]
	v_add_f32_dpp v64, v64, v64 row_ror:2 row_mask:0xf bank_mask:0xf bound_ctrl:1
	v_add_f32_dpp v62, v62, v62 row_ror:2 row_mask:0xf bank_mask:0xf bound_ctrl:1
	v_pk_fma_f32 v[48:49], v[86:87], v[68:69], v[48:49]
	v_add_f32_dpp v64, v64, v64 row_ror:1 row_mask:0xf bank_mask:0xf bound_ctrl:1
	v_add_f32_dpp v62, v62, v62 row_ror:1 row_mask:0xf bank_mask:0xf bound_ctrl:1
	v_pk_mul_f32 v[92:93], v[54:55], v[64:65] op_sel_hi:[1,0]
	v_pk_mul_f32 v[54:55], v[54:55], v[62:63] op_sel_hi:[1,0]
	v_pk_fma_f32 v[92:93], v[58:59], v[66:67], v[92:93] op_sel_hi:[1,0,1]
	v_pk_fma_f32 v[54:55], v[58:59], v[84:85], v[54:55] op_sel_hi:[1,0,1]
	s_waitcnt vmcnt(6)
	v_pk_fma_f32 v[92:93], v[200:201], v[98:99], v[92:93]
	v_pk_mul_f32 v[64:65], v[56:57], v[64:65] op_sel_hi:[1,0]
	v_pk_fma_f32 v[58:59], v[200:201], v[68:69], v[54:55]
	v_pk_mul_f32 v[38:39], v[56:57], v[62:63] op_sel_hi:[1,0]
	v_pk_fma_f32 v[64:65], v[60:61], v[66:67], v[64:65] op_sel_hi:[1,0,1]
	v_pk_fma_f32 v[38:39], v[60:61], v[84:85], v[38:39] op_sel_hi:[1,0,1]
	v_pk_fma_f32 v[64:65], v[202:203], v[100:101], v[64:65]
	v_pk_fma_f32 v[60:61], v[202:203], v[82:83], v[38:39]
	s_waitcnt lgkmcnt(10)
	v_pk_mul_f32 v[62:63], v[44:45], v[64:65]
	v_pk_mul_f32 v[44:45], v[44:45], v[60:61]
	v_pk_fma_f32 v[62:63], v[42:43], v[92:93], v[62:63]
	v_pk_fma_f32 v[42:43], v[42:43], v[58:59], v[44:45]
	v_add_f32_e32 v44, v62, v63
	v_add_f32_e32 v42, v42, v43
	s_waitcnt lgkmcnt(6)
	v_mov_b32_e32 v62, v91
	v_add_f32_dpp v44, v44, v44 row_ror:8 row_mask:0xf bank_mask:0xf bound_ctrl:1
	v_add_f32_dpp v42, v42, v42 row_ror:8 row_mask:0xf bank_mask:0xf bound_ctrl:1
	v_pk_mul_f32 v[38:39], v[16:17], v[64:65]
	v_add_f32_dpp v44, v44, v44 row_ror:4 row_mask:0xf bank_mask:0xf bound_ctrl:1
	v_add_f32_dpp v42, v42, v42 row_ror:4 row_mask:0xf bank_mask:0xf bound_ctrl:1
	v_pk_mul_f32 v[16:17], v[16:17], v[60:61]
	v_add_f32_dpp v44, v44, v44 row_ror:2 row_mask:0xf bank_mask:0xf bound_ctrl:1
	v_add_f32_dpp v42, v42, v42 row_ror:2 row_mask:0xf bank_mask:0xf bound_ctrl:1
	v_add_f32_e32 v46, v46, v47
	v_add_f32_dpp v44, v44, v44 row_ror:1 row_mask:0xf bank_mask:0xf bound_ctrl:1
	v_add_f32_dpp v42, v42, v42 row_ror:1 row_mask:0xf bank_mask:0xf bound_ctrl:1
	v_pk_mul_f32 v[100:101], v[30:31], v[44:45] op_sel_hi:[1,0]
	v_pk_mul_f32 v[30:31], v[30:31], v[42:43] op_sel_hi:[1,0]
	v_pk_fma_f32 v[100:101], v[34:35], v[90:91], v[100:101] op_sel_hi:[1,0,1]
	v_pk_fma_f32 v[30:31], v[34:35], v[62:63], v[30:31] op_sel_hi:[1,0,1]
	s_waitcnt vmcnt(5)
	v_pk_fma_f32 v[100:101], v[204:205], v[92:93], v[100:101]
	v_pk_mul_f32 v[44:45], v[32:33], v[44:45] op_sel_hi:[1,0]
	v_pk_fma_f32 v[30:31], v[204:205], v[58:59], v[30:31]
	v_pk_mul_f32 v[6:7], v[32:33], v[42:43] op_sel_hi:[1,0]
	v_pk_fma_f32 v[44:45], v[36:37], v[90:91], v[44:45] op_sel_hi:[1,0,1]
	v_pk_fma_f32 v[6:7], v[36:37], v[62:63], v[6:7] op_sel_hi:[1,0,1]
	v_pk_fma_f32 v[90:91], v[206:207], v[64:65], v[44:45]
	v_pk_fma_f32 v[32:33], v[206:207], v[60:61], v[6:7]
	s_waitcnt lgkmcnt(4)
	v_pk_mul_f32 v[34:35], v[80:81], v[90:91]
	v_pk_mul_f32 v[36:37], v[80:81], v[32:33]
	v_pk_fma_f32 v[34:35], v[78:79], v[100:101], v[34:35]
	v_pk_fma_f32 v[36:37], v[78:79], v[30:31], v[36:37]
	v_add_f32_e32 v34, v34, v35
	v_add_f32_e32 v35, v36, v37
	s_waitcnt lgkmcnt(0)
	v_mov_b32_e32 v78, v95
	v_add_f32_dpp v34, v34, v34 row_ror:8 row_mask:0xf bank_mask:0xf bound_ctrl:1
	v_add_f32_dpp v35, v35, v35 row_ror:8 row_mask:0xf bank_mask:0xf bound_ctrl:1
	v_pk_mul_f32 v[6:7], v[4:5], v[90:91]
	v_add_f32_dpp v34, v34, v34 row_ror:4 row_mask:0xf bank_mask:0xf bound_ctrl:1
	v_add_f32_dpp v35, v35, v35 row_ror:4 row_mask:0xf bank_mask:0xf bound_ctrl:1
	v_pk_fma_f32 v[6:7], v[2:3], v[100:101], v[6:7]
	v_add_f32_dpp v34, v34, v34 row_ror:2 row_mask:0xf bank_mask:0xf bound_ctrl:1
	v_add_f32_dpp v35, v35, v35 row_ror:2 row_mask:0xf bank_mask:0xf bound_ctrl:1
	v_add_f32_e32 v47, v48, v49
	v_add_f32_dpp v34, v34, v34 row_ror:1 row_mask:0xf bank_mask:0xf bound_ctrl:1
	v_add_f32_dpp v36, v35, v35 row_ror:1 row_mask:0xf bank_mask:0xf bound_ctrl:1
	v_pk_mul_f32 v[80:81], v[22:23], v[34:35] op_sel_hi:[1,0]
	v_pk_mul_f32 v[22:23], v[22:23], v[36:37] op_sel_hi:[1,0]
	v_pk_fma_f32 v[80:81], v[26:27], v[94:95], v[80:81] op_sel_hi:[1,0,1]
	v_pk_fma_f32 v[22:23], v[26:27], v[78:79], v[22:23] op_sel_hi:[1,0,1]
	s_waitcnt vmcnt(4)
	v_pk_fma_f32 v[80:81], v[208:209], v[100:101], v[80:81]
	v_pk_mul_f32 v[34:35], v[24:25], v[34:35] op_sel_hi:[1,0]
	v_pk_fma_f32 v[100:101], v[208:209], v[30:31], v[22:23]
	v_pk_mul_f32 v[18:19], v[24:25], v[36:37] op_sel_hi:[1,0]
	v_pk_fma_f32 v[34:35], v[28:29], v[94:95], v[34:35] op_sel_hi:[1,0,1]
	v_pk_fma_f32 v[18:19], v[28:29], v[78:79], v[18:19] op_sel_hi:[1,0,1]
	v_pk_fma_f32 v[38:39], v[14:15], v[92:93], v[38:39]
	v_pk_fma_f32 v[14:15], v[14:15], v[58:59], v[16:17]
	v_pk_mul_f32 v[4:5], v[4:5], v[32:33]
	v_pk_fma_f32 v[94:95], v[210:211], v[90:91], v[34:35]
	v_pk_fma_f32 v[78:79], v[210:211], v[32:33], v[18:19]
	ds_write2st64_b32 v113, v46, v47 offset0:8 offset1:9
	v_add_f32_e32 v16, v38, v39
	v_add_f32_e32 v14, v14, v15
	v_pk_fma_f32 v[2:3], v[2:3], v[30:31], v[4:5]
	v_pk_mul_f32 v[18:19], v[12:13], v[94:95]
	v_pk_mul_f32 v[12:13], v[12:13], v[78:79]
	ds_read_b128 v[86:89], v118 offset:26880
	global_load_dwordx4 v[196:199], v118, s[56:57]
	s_add_u32 s56, s56, s58
	s_addc_u32 s57, s57, s59
	ds_read_b128 v[70:73], v118 offset:27392
	ds_read_b128 v[74:77], v118 offset:27648
	ds_read_b128 v[46:49], v118 offset:27904
	ds_read2_b32 v[96:97], v120 offset0:160 offset1:164
	ds_write2st64_b32 v113, v16, v14 offset0:16 offset1:17
	v_add_f32_e32 v4, v6, v7
	v_add_f32_e32 v2, v2, v3
	v_pk_fma_f32 v[18:19], v[10:11], v[80:81], v[18:19]
	v_pk_fma_f32 v[10:11], v[10:11], v[100:101], v[12:13]
	ds_read_b128 v[82:85], v118 offset:28160
	global_load_dwordx4 v[200:203], v118, s[56:57]
	s_add_u32 s56, s56, s58
	s_addc_u32 s57, s57, s59
	ds_read_b128 v[54:57], v118 offset:28672
	ds_read_b128 v[66:69], v118 offset:28928
	ds_read_b128 v[14:17], v118 offset:29184
	ds_read2_b32 v[98:99], v120 offset0:192 offset1:196
	ds_write2st64_b32 v113, v4, v2 offset0:24 offset1:25
	v_add_f32_e32 v12, v18, v19
	v_add_f32_e32 v10, v10, v11
	ds_read_b128 v[62:65], v118 offset:29440
	global_load_dwordx4 v[204:207], v118, s[56:57]
	s_add_u32 s56, s56, s58
	s_addc_u32 s57, s57, s59
	ds_read_b128 v[42:45], v118 offset:29952
	ds_read_b128 v[58:61], v118 offset:30208
	ds_read_b128 v[2:5], v118 offset:30464
	ds_read2_b32 v[92:93], v120 offset0:224 offset1:228
	ds_write2st64_b32 v113, v12, v10 offset0:32 offset1:33
	s_waitcnt lgkmcnt(12)
	v_pk_mul_f32 v[10:11], v[88:89], v[94:95]
	v_pk_mul_f32 v[12:13], v[88:89], v[78:79]
	v_pk_fma_f32 v[10:11], v[86:87], v[80:81], v[10:11]
	v_pk_fma_f32 v[12:13], v[86:87], v[100:101], v[12:13]
	v_add_f32_e32 v10, v10, v11
	v_add_f32_e32 v11, v12, v13
	v_mov_b32_e32 v86, v97
	v_add_f32_dpp v10, v10, v10 row_ror:8 row_mask:0xf bank_mask:0xf bound_ctrl:1
	v_add_f32_dpp v11, v11, v11 row_ror:8 row_mask:0xf bank_mask:0xf bound_ctrl:1
	ds_read_b128 v[34:37], v118 offset:30720
	global_load_dwordx4 v[208:211], v118, s[56:57]
	s_add_u32 s56, s56, s58
	s_addc_u32 s57, s57, s59
	ds_read_b128 v[26:29], v118 offset:31232
	ds_read_b128 v[30:33], v118 offset:31488
	ds_read_b128 v[18:21], v118 offset:31744
	ds_read2_b32 v[90:91], v114 offset1:4
	v_add_f32_dpp v10, v10, v10 row_ror:4 row_mask:0xf bank_mask:0xf bound_ctrl:1
	v_add_f32_dpp v11, v11, v11 row_ror:4 row_mask:0xf bank_mask:0xf bound_ctrl:1
	s_nop 0
	v_add_f32_dpp v10, v10, v10 row_ror:2 row_mask:0xf bank_mask:0xf bound_ctrl:1
	v_add_f32_dpp v11, v11, v11 row_ror:2 row_mask:0xf bank_mask:0xf bound_ctrl:1
	s_nop 0
	v_add_f32_dpp v10, v10, v10 row_ror:1 row_mask:0xf bank_mask:0xf bound_ctrl:1
	v_add_f32_dpp v12, v11, v11 row_ror:1 row_mask:0xf bank_mask:0xf bound_ctrl:1
	v_pk_mul_f32 v[88:89], v[70:71], v[10:11] op_sel_hi:[1,0]
	v_pk_mul_f32 v[10:11], v[72:73], v[10:11] op_sel_hi:[1,0]
	v_pk_mul_f32 v[70:71], v[70:71], v[12:13] op_sel_hi:[1,0]
	v_pk_fma_f32 v[10:11], v[76:77], v[96:97], v[10:11] op_sel_hi:[1,0,1]
	v_pk_mul_f32 v[12:13], v[72:73], v[12:13] op_sel_hi:[1,0]
	v_pk_fma_f32 v[88:89], v[74:75], v[96:97], v[88:89] op_sel_hi:[1,0,1]
	s_waitcnt vmcnt(7)
	v_pk_fma_f32 v[10:11], v[214:215], v[94:95], v[10:11]
	v_pk_fma_f32 v[12:13], v[76:77], v[86:87], v[12:13] op_sel_hi:[1,0,1]
	v_pk_fma_f32 v[88:89], v[212:213], v[80:81], v[88:89]
	v_pk_fma_f32 v[70:71], v[74:75], v[86:87], v[70:71] op_sel_hi:[1,0,1]
	v_pk_fma_f32 v[12:13], v[214:215], v[78:79], v[12:13]
	s_waitcnt lgkmcnt(12)
	v_pk_mul_f32 v[96:97], v[84:85], v[10:11]
	v_pk_fma_f32 v[94:95], v[212:213], v[100:101], v[70:71]
	v_pk_fma_f32 v[96:97], v[82:83], v[88:89], v[96:97]
	v_pk_mul_f32 v[84:85], v[84:85], v[12:13]
	v_pk_mul_f32 v[50:51], v[48:49], v[10:11]
	v_pk_fma_f32 v[82:83], v[82:83], v[94:95], v[84:85]
	v_add_f32_e32 v84, v96, v97
	v_add_f32_e32 v82, v82, v83
	v_mov_b32_e32 v96, v99
	v_add_f32_dpp v84, v84, v84 row_ror:8 row_mask:0xf bank_mask:0xf bound_ctrl:1
	v_add_f32_dpp v82, v82, v82 row_ror:8 row_mask:0xf bank_mask:0xf bound_ctrl:1
	v_pk_mul_f32 v[48:49], v[48:49], v[12:13]
	v_add_f32_dpp v84, v84, v84 row_ror:4 row_mask:0xf bank_mask:0xf bound_ctrl:1
	v_add_f32_dpp v82, v82, v82 row_ror:4 row_mask:0xf bank_mask:0xf bound_ctrl:1
	v_pk_fma_f32 v[50:51], v[46:47], v[88:89], v[50:51]
	v_add_f32_dpp v84, v84, v84 row_ror:2 row_mask:0xf bank_mask:0xf bound_ctrl:1
	v_add_f32_dpp v82, v82, v82 row_ror:2 row_mask:0xf bank_mask:0xf bound_ctrl:1
	v_pk_fma_f32 v[46:47], v[46:47], v[94:95], v[48:49]
	v_add_f32_dpp v84, v84, v84 row_ror:1 row_mask:0xf bank_mask:0xf bound_ctrl:1
	v_pk_mul_f32 v[100:101], v[54:55], v[84:85] op_sel_hi:[1,0]
	v_pk_mul_f32 v[84:85], v[56:57], v[84:85] op_sel_hi:[1,0]
	v_add_f32_dpp v82, v82, v82 row_ror:1 row_mask:0xf bank_mask:0xf bound_ctrl:1
	v_pk_fma_f32 v[84:85], v[68:69], v[98:99], v[84:85] op_sel_hi:[1,0,1]
	v_pk_fma_f32 v[100:101], v[66:67], v[98:99], v[100:101] op_sel_hi:[1,0,1]
	s_waitcnt vmcnt(6)
	v_pk_fma_f32 v[98:99], v[218:219], v[10:11], v[84:85]
	v_pk_mul_f32 v[10:11], v[54:55], v[82:83] op_sel_hi:[1,0]
	v_pk_fma_f32 v[88:89], v[216:217], v[88:89], v[100:101]
	v_pk_fma_f32 v[10:11], v[66:67], v[96:97], v[10:11] op_sel_hi:[1,0,1]
	s_waitcnt lgkmcnt(10)
	v_pk_mul_f32 v[84:85], v[64:65], v[98:99]
	v_pk_fma_f32 v[94:95], v[216:217], v[94:95], v[10:11]
	v_pk_mul_f32 v[10:11], v[56:57], v[82:83] op_sel_hi:[1,0]
	v_pk_fma_f32 v[84:85], v[62:63], v[88:89], v[84:85]
	v_pk_fma_f32 v[10:11], v[68:69], v[96:97], v[10:11] op_sel_hi:[1,0,1]
	s_waitcnt lgkmcnt(6)
	v_mov_b32_e32 v100, v93
	v_pk_fma_f32 v[96:97], v[218:219], v[12:13], v[10:11]
	v_pk_mul_f32 v[10:11], v[16:17], v[98:99]
	v_pk_mul_f32 v[64:65], v[64:65], v[96:97]
	v_pk_mul_f32 v[12:13], v[16:17], v[96:97]
	v_pk_fma_f32 v[62:63], v[62:63], v[94:95], v[64:65]
	v_add_f32_e32 v64, v84, v85
	v_add_f32_e32 v62, v62, v63
	v_pk_fma_f32 v[12:13], v[14:15], v[94:95], v[12:13]
	v_add_f32_dpp v64, v64, v64 row_ror:8 row_mask:0xf bank_mask:0xf bound_ctrl:1
	v_add_f32_dpp v62, v62, v62 row_ror:8 row_mask:0xf bank_mask:0xf bound_ctrl:1
	v_pk_fma_f32 v[10:11], v[14:15], v[88:89], v[10:11]
	v_add_f32_dpp v64, v64, v64 row_ror:4 row_mask:0xf bank_mask:0xf bound_ctrl:1
	v_add_f32_dpp v62, v62, v62 row_ror:4 row_mask:0xf bank_mask:0xf bound_ctrl:1
	v_add_f32_e32 v48, v50, v51
	v_add_f32_dpp v64, v64, v64 row_ror:2 row_mask:0xf bank_mask:0xf bound_ctrl:1
	v_add_f32_dpp v62, v62, v62 row_ror:2 row_mask:0xf bank_mask:0xf bound_ctrl:1
	v_add_f32_e32 v46, v46, v47
	v_add_f32_dpp v64, v64, v64 row_ror:1 row_mask:0xf bank_mask:0xf bound_ctrl:1
	v_add_f32_dpp v62, v62, v62 row_ror:1 row_mask:0xf bank_mask:0xf bound_ctrl:1
	v_pk_mul_f32 v[84:85], v[42:43], v[64:65] op_sel_hi:[1,0]
	v_pk_mul_f32 v[42:43], v[42:43], v[62:63] op_sel_hi:[1,0]
	v_pk_fma_f32 v[84:85], v[58:59], v[92:93], v[84:85] op_sel_hi:[1,0,1]
	v_pk_fma_f32 v[42:43], v[58:59], v[100:101], v[42:43] op_sel_hi:[1,0,1]
	s_waitcnt vmcnt(5)
	v_pk_fma_f32 v[84:85], v[220:221], v[88:89], v[84:85]
	v_pk_mul_f32 v[64:65], v[44:45], v[64:65] op_sel_hi:[1,0]
	v_pk_fma_f32 v[94:95], v[220:221], v[94:95], v[42:43]
	v_pk_mul_f32 v[6:7], v[44:45], v[62:63] op_sel_hi:[1,0]
	v_pk_fma_f32 v[64:65], v[60:61], v[92:93], v[64:65] op_sel_hi:[1,0,1]
	v_pk_fma_f32 v[6:7], v[60:61], v[100:101], v[6:7] op_sel_hi:[1,0,1]
	v_pk_fma_f32 v[88:89], v[222:223], v[98:99], v[64:65]
	v_pk_fma_f32 v[96:97], v[222:223], v[96:97], v[6:7]
	s_waitcnt lgkmcnt(4)
	v_pk_mul_f32 v[98:99], v[36:37], v[88:89]
	v_pk_mul_f32 v[36:37], v[36:37], v[96:97]
	v_pk_fma_f32 v[98:99], v[34:35], v[84:85], v[98:99]
	v_pk_fma_f32 v[34:35], v[34:35], v[94:95], v[36:37]
	v_add_f32_e32 v36, v98, v99
	v_add_f32_e32 v34, v34, v35
	s_waitcnt lgkmcnt(0)
	v_mov_b32_e32 v98, v91
	v_add_f32_dpp v36, v36, v36 row_ror:8 row_mask:0xf bank_mask:0xf bound_ctrl:1
	v_add_f32_dpp v34, v34, v34 row_ror:8 row_mask:0xf bank_mask:0xf bound_ctrl:1
	v_pk_mul_f32 v[6:7], v[4:5], v[88:89]
	v_add_f32_dpp v36, v36, v36 row_ror:4 row_mask:0xf bank_mask:0xf bound_ctrl:1
	v_add_f32_dpp v34, v34, v34 row_ror:4 row_mask:0xf bank_mask:0xf bound_ctrl:1
	v_pk_mul_f32 v[4:5], v[4:5], v[96:97]
	v_add_f32_dpp v36, v36, v36 row_ror:2 row_mask:0xf bank_mask:0xf bound_ctrl:1
	v_add_f32_dpp v34, v34, v34 row_ror:2 row_mask:0xf bank_mask:0xf bound_ctrl:1
	v_pk_fma_f32 v[6:7], v[2:3], v[84:85], v[6:7]
	v_add_f32_dpp v36, v36, v36 row_ror:1 row_mask:0xf bank_mask:0xf bound_ctrl:1
	v_add_f32_dpp v34, v34, v34 row_ror:1 row_mask:0xf bank_mask:0xf bound_ctrl:1
	v_pk_mul_f32 v[100:101], v[26:27], v[36:37] op_sel_hi:[1,0]
	v_pk_mul_f32 v[26:27], v[26:27], v[34:35] op_sel_hi:[1,0]
	v_pk_fma_f32 v[100:101], v[30:31], v[90:91], v[100:101] op_sel_hi:[1,0,1]
	v_pk_fma_f32 v[26:27], v[30:31], v[98:99], v[26:27] op_sel_hi:[1,0,1]
	v_pk_fma_f32 v[2:3], v[2:3], v[94:95], v[4:5]
	s_waitcnt vmcnt(4)
	v_pk_fma_f32 v[84:85], v[192:193], v[84:85], v[100:101]
	v_pk_mul_f32 v[36:37], v[28:29], v[36:37] op_sel_hi:[1,0]
	v_pk_fma_f32 v[94:95], v[192:193], v[94:95], v[26:27]
	v_pk_mul_f32 v[22:23], v[28:29], v[34:35] op_sel_hi:[1,0]
	ds_write2st64_b32 v113, v48, v46 offset0:40 offset1:41
	v_pk_fma_f32 v[36:37], v[32:33], v[90:91], v[36:37] op_sel_hi:[1,0,1]
	v_pk_fma_f32 v[22:23], v[32:33], v[98:99], v[22:23] op_sel_hi:[1,0,1]
	ds_read_b128 v[78:81], v118 offset:32000
	global_load_dwordx4 v[212:215], v118, s[56:57]
	s_add_u32 s56, s56, s58
	s_addc_u32 s57, s57, s59
	ds_read_b128 v[70:73], v118 offset:32512
	ds_read_b128 v[74:77], v118 offset:32768
	ds_read_b128 v[46:49], v118 offset:33024
	ds_read2_b32 v[86:87], v114 offset0:32 offset1:36
	v_pk_fma_f32 v[88:89], v[194:195], v[88:89], v[36:37]
	v_pk_fma_f32 v[96:97], v[194:195], v[96:97], v[22:23]
	s_waitcnt lgkmcnt(4)
	v_pk_mul_f32 v[98:99], v[80:81], v[88:89]
	v_pk_mul_f32 v[80:81], v[80:81], v[96:97]
	v_pk_fma_f32 v[98:99], v[78:79], v[84:85], v[98:99]
	v_pk_fma_f32 v[78:79], v[78:79], v[94:95], v[80:81]
	v_add_f32_e32 v80, v98, v99
	v_add_f32_e32 v78, v78, v79
	s_waitcnt lgkmcnt(0)
	v_mov_b32_e32 v98, v87
	v_add_f32_dpp v80, v80, v80 row_ror:8 row_mask:0xf bank_mask:0xf bound_ctrl:1
	v_add_f32_dpp v78, v78, v78 row_ror:8 row_mask:0xf bank_mask:0xf bound_ctrl:1
	v_pk_mul_f32 v[22:23], v[20:21], v[88:89]
	v_add_f32_dpp v80, v80, v80 row_ror:4 row_mask:0xf bank_mask:0xf bound_ctrl:1
	v_add_f32_dpp v78, v78, v78 row_ror:4 row_mask:0xf bank_mask:0xf bound_ctrl:1
	v_add_f32_e32 v10, v10, v11
	v_add_f32_dpp v80, v80, v80 row_ror:2 row_mask:0xf bank_mask:0xf bound_ctrl:1
	v_add_f32_dpp v78, v78, v78 row_ror:2 row_mask:0xf bank_mask:0xf bound_ctrl:1
	v_add_f32_e32 v11, v12, v13
	v_add_f32_dpp v80, v80, v80 row_ror:1 row_mask:0xf bank_mask:0xf bound_ctrl:1
	v_add_f32_dpp v78, v78, v78 row_ror:1 row_mask:0xf bank_mask:0xf bound_ctrl:1
	v_pk_mul_f32 v[100:101], v[70:71], v[80:81] op_sel_hi:[1,0]
	v_pk_mul_f32 v[80:81], v[72:73], v[80:81] op_sel_hi:[1,0]
	v_pk_mul_f32 v[70:71], v[70:71], v[78:79] op_sel_hi:[1,0]
	v_pk_fma_f32 v[100:101], v[74:75], v[86:87], v[100:101] op_sel_hi:[1,0,1]
	v_pk_fma_f32 v[80:81], v[76:77], v[86:87], v[80:81] op_sel_hi:[1,0,1]
	v_pk_fma_f32 v[70:71], v[74:75], v[98:99], v[70:71] op_sel_hi:[1,0,1]
	v_pk_fma_f32 v[22:23], v[18:19], v[84:85], v[22:23]
	s_waitcnt vmcnt(4)
	v_pk_fma_f32 v[84:85], v[196:197], v[84:85], v[100:101]
	v_pk_fma_f32 v[86:87], v[198:199], v[88:89], v[80:81]
	v_pk_fma_f32 v[88:89], v[196:197], v[94:95], v[70:71]
	v_pk_mul_f32 v[50:51], v[72:73], v[78:79] op_sel_hi:[1,0]
	ds_write2st64_b32 v113, v10, v11 offset0:48 offset1:49
	v_pk_fma_f32 v[50:51], v[76:77], v[98:99], v[50:51] op_sel_hi:[1,0,1]
	ds_read_b128 v[14:17], v118 offset:33280
	global_load_dwordx4 v[216:219], v118, s[56:57]
	s_add_u32 s56, s56, s58
	s_addc_u32 s57, s57, s59
	ds_read_b128 v[38:41], v118 offset:33792
	ds_read_b128 v[54:57], v118 offset:34048
	ds_read_b128 v[66:69], v118 offset:34304
	ds_read2_b32 v[82:83], v114 offset0:64 offset1:68
	v_pk_mul_f32 v[20:21], v[20:21], v[96:97]
	v_pk_fma_f32 v[96:97], v[198:199], v[96:97], v[50:51]
	s_waitcnt lgkmcnt(4)
	v_pk_mul_f32 v[98:99], v[16:17], v[86:87]
	v_pk_mul_f32 v[16:17], v[16:17], v[96:97]
	v_pk_fma_f32 v[98:99], v[14:15], v[84:85], v[98:99]
	v_pk_fma_f32 v[14:15], v[14:15], v[88:89], v[16:17]
	v_add_f32_e32 v16, v98, v99
	v_add_f32_e32 v14, v14, v15
	s_waitcnt lgkmcnt(0)
	v_mov_b32_e32 v100, v83
	v_add_f32_dpp v16, v16, v16 row_ror:8 row_mask:0xf bank_mask:0xf bound_ctrl:1
	v_add_f32_dpp v14, v14, v14 row_ror:8 row_mask:0xf bank_mask:0xf bound_ctrl:1
	v_add_f32_e32 v4, v6, v7
	v_add_f32_dpp v16, v16, v16 row_ror:4 row_mask:0xf bank_mask:0xf bound_ctrl:1
	v_add_f32_dpp v14, v14, v14 row_ror:4 row_mask:0xf bank_mask:0xf bound_ctrl:1
	v_add_f32_e32 v2, v2, v3
	v_add_f32_dpp v16, v16, v16 row_ror:2 row_mask:0xf bank_mask:0xf bound_ctrl:1
	v_add_f32_dpp v14, v14, v14 row_ror:2 row_mask:0xf bank_mask:0xf bound_ctrl:1
	ds_write2st64_b32 v113, v4, v2 offset0:56 offset1:57
	v_add_f32_dpp v16, v16, v16 row_ror:1 row_mask:0xf bank_mask:0xf bound_ctrl:1
	v_add_f32_dpp v98, v14, v14 row_ror:1 row_mask:0xf bank_mask:0xf bound_ctrl:1
	v_pk_mul_f32 v[14:15], v[38:39], v[16:17] op_sel_hi:[1,0]
	v_pk_mul_f32 v[38:39], v[38:39], v[98:99] op_sel_hi:[1,0]
	v_pk_fma_f32 v[14:15], v[54:55], v[82:83], v[14:15] op_sel_hi:[1,0,1]
	v_pk_mul_f32 v[16:17], v[40:41], v[16:17] op_sel_hi:[1,0]
	v_pk_fma_f32 v[38:39], v[54:55], v[100:101], v[38:39] op_sel_hi:[1,0,1]
	s_waitcnt vmcnt(4)
	v_pk_fma_f32 v[14:15], v[200:201], v[84:85], v[14:15]
	v_pk_fma_f32 v[16:17], v[56:57], v[82:83], v[16:17] op_sel_hi:[1,0,1]
	v_pk_fma_f32 v[10:11], v[200:201], v[88:89], v[38:39]
	v_pk_mul_f32 v[38:39], v[40:41], v[98:99] op_sel_hi:[1,0]
	v_pk_fma_f32 v[16:17], v[202:203], v[86:87], v[16:17]
	v_pk_fma_f32 v[38:39], v[56:57], v[100:101], v[38:39] op_sel_hi:[1,0,1]
	ds_read_b128 v[6:9], v118 offset:34560
	global_load_dwordx4 v[220:223], v118, s[56:57]
	s_add_u32 s56, s56, s58
	s_addc_u32 s57, s57, s59
	ds_read_b128 v[42:45], v118 offset:35072
	ds_read_b128 v[58:61], v118 offset:35328
	ds_read_b128 v[62:65], v118 offset:35584
	ds_read2_b32 v[92:93], v114 offset0:96 offset1:100
	v_pk_fma_f32 v[12:13], v[202:203], v[96:97], v[38:39]
	s_waitcnt lgkmcnt(4)
	v_pk_mul_f32 v[98:99], v[8:9], v[16:17]
	v_pk_mul_f32 v[8:9], v[8:9], v[12:13]
	v_pk_fma_f32 v[98:99], v[6:7], v[14:15], v[98:99]
	v_pk_fma_f32 v[6:7], v[6:7], v[10:11], v[8:9]
	v_add_f32_e32 v8, v98, v99
	v_add_f32_e32 v6, v6, v7
	s_waitcnt lgkmcnt(0)
	v_mov_b32_e32 v102, v93
	v_add_f32_dpp v8, v8, v8 row_ror:8 row_mask:0xf bank_mask:0xf bound_ctrl:1
	v_add_f32_dpp v6, v6, v6 row_ror:8 row_mask:0xf bank_mask:0xf bound_ctrl:1
	v_pk_fma_f32 v[18:19], v[18:19], v[94:95], v[20:21]
	v_add_f32_dpp v8, v8, v8 row_ror:4 row_mask:0xf bank_mask:0xf bound_ctrl:1
	v_add_f32_dpp v6, v6, v6 row_ror:4 row_mask:0xf bank_mask:0xf bound_ctrl:1
	v_add_f32_e32 v20, v22, v23
	v_add_f32_dpp v8, v8, v8 row_ror:2 row_mask:0xf bank_mask:0xf bound_ctrl:1
	v_add_f32_dpp v6, v6, v6 row_ror:2 row_mask:0xf bank_mask:0xf bound_ctrl:1
	v_add_f32_e32 v18, v18, v19
	v_add_f32_dpp v8, v8, v8 row_ror:1 row_mask:0xf bank_mask:0xf bound_ctrl:1
	v_pk_mul_f32 v[98:99], v[42:43], v[8:9] op_sel_hi:[1,0]
	v_pk_mul_f32 v[8:9], v[44:45], v[8:9] op_sel_hi:[1,0]
	v_add_f32_dpp v6, v6, v6 row_ror:1 row_mask:0xf bank_mask:0xf bound_ctrl:1
	v_pk_fma_f32 v[8:9], v[60:61], v[92:93], v[8:9] op_sel_hi:[1,0,1]
	v_pk_fma_f32 v[98:99], v[58:59], v[92:93], v[98:99] op_sel_hi:[1,0,1]
	s_waitcnt vmcnt(4)
	v_pk_fma_f32 v[92:93], v[206:207], v[16:17], v[8:9]
	v_pk_mul_f32 v[8:9], v[42:43], v[6:7] op_sel_hi:[1,0]
	v_pk_fma_f32 v[98:99], v[204:205], v[14:15], v[98:99]
	v_pk_fma_f32 v[8:9], v[58:59], v[102:103], v[8:9] op_sel_hi:[1,0,1]
	ds_write2st64_b32 v113, v20, v18 offset0:64 offset1:65
	v_pk_fma_f32 v[100:101], v[204:205], v[10:11], v[8:9]
	v_pk_mul_f32 v[2:3], v[44:45], v[6:7] op_sel_hi:[1,0]
	ds_read_b128 v[34:37], v118 offset:35840
	global_load_dwordx4 v[192:195], v118, s[56:57]
	s_add_u32 s56, s56, s58
	s_addc_u32 s57, s57, s59
	ds_read_b128 v[22:25], v118 offset:36352
	ds_read_b128 v[26:29], v118 offset:36608
	ds_read_b128 v[30:33], v118 offset:36864
	ds_read2_b32 v[90:91], v114 offset0:128 offset1:132
	v_pk_fma_f32 v[2:3], v[60:61], v[102:103], v[2:3] op_sel_hi:[1,0,1]
	v_pk_mul_f32 v[50:51], v[48:49], v[86:87]
	v_pk_fma_f32 v[60:61], v[206:207], v[12:13], v[2:3]
	v_pk_mul_f32 v[2:3], v[64:65], v[92:93]
	v_pk_mul_f32 v[4:5], v[64:65], v[60:61]
	v_pk_fma_f32 v[2:3], v[62:63], v[98:99], v[2:3]
	v_pk_fma_f32 v[4:5], v[62:63], v[100:101], v[4:5]
	s_waitcnt lgkmcnt(4)
	v_pk_mul_f32 v[62:63], v[36:37], v[92:93]
	v_pk_mul_f32 v[36:37], v[36:37], v[60:61]
	v_pk_fma_f32 v[62:63], v[34:35], v[98:99], v[62:63]
	v_pk_fma_f32 v[34:35], v[34:35], v[100:101], v[36:37]
	v_add_f32_e32 v36, v62, v63
	v_add_f32_e32 v34, v34, v35
	s_waitcnt lgkmcnt(0)
	v_mov_b32_e32 v62, v91
	v_add_f32_dpp v36, v36, v36 row_ror:8 row_mask:0xf bank_mask:0xf bound_ctrl:1
	v_add_f32_dpp v34, v34, v34 row_ror:8 row_mask:0xf bank_mask:0xf bound_ctrl:1
	v_pk_mul_f32 v[48:49], v[48:49], v[96:97]
	v_add_f32_dpp v36, v36, v36 row_ror:4 row_mask:0xf bank_mask:0xf bound_ctrl:1
	v_add_f32_dpp v34, v34, v34 row_ror:4 row_mask:0xf bank_mask:0xf bound_ctrl:1
	v_pk_fma_f32 v[50:51], v[46:47], v[84:85], v[50:51]
	v_add_f32_dpp v36, v36, v36 row_ror:2 row_mask:0xf bank_mask:0xf bound_ctrl:1
	v_add_f32_dpp v34, v34, v34 row_ror:2 row_mask:0xf bank_mask:0xf bound_ctrl:1
	v_pk_fma_f32 v[46:47], v[46:47], v[88:89], v[48:49]
	v_add_f32_dpp v36, v36, v36 row_ror:1 row_mask:0xf bank_mask:0xf bound_ctrl:1
	v_add_f32_dpp v34, v34, v34 row_ror:1 row_mask:0xf bank_mask:0xf bound_ctrl:1
	v_pk_mul_f32 v[64:65], v[22:23], v[36:37] op_sel_hi:[1,0]
	v_pk_mul_f32 v[22:23], v[22:23], v[34:35] op_sel_hi:[1,0]
	v_pk_fma_f32 v[64:65], v[26:27], v[90:91], v[64:65] op_sel_hi:[1,0,1]
	v_pk_fma_f32 v[22:23], v[26:27], v[62:63], v[22:23] op_sel_hi:[1,0,1]
	s_waitcnt vmcnt(4)
	v_pk_fma_f32 v[64:65], v[208:209], v[98:99], v[64:65]
	v_pk_mul_f32 v[36:37], v[24:25], v[36:37] op_sel_hi:[1,0]
	v_pk_fma_f32 v[18:19], v[208:209], v[100:101], v[22:23]
	v_pk_mul_f32 v[22:23], v[24:25], v[34:35] op_sel_hi:[1,0]
	v_pk_mul_f32 v[38:39], v[68:69], v[16:17]
	v_pk_mul_f32 v[40:41], v[68:69], v[12:13]
	v_pk_fma_f32 v[36:37], v[28:29], v[90:91], v[36:37] op_sel_hi:[1,0,1]
	v_pk_fma_f32 v[22:23], v[28:29], v[62:63], v[22:23] op_sel_hi:[1,0,1]
	v_add_f32_e32 v48, v50, v51
	v_add_f32_e32 v46, v46, v47
	v_pk_fma_f32 v[38:39], v[66:67], v[14:15], v[38:39]
	v_pk_fma_f32 v[40:41], v[66:67], v[10:11], v[40:41]
	v_pk_fma_f32 v[36:37], v[210:211], v[92:93], v[36:37]
	v_pk_fma_f32 v[20:21], v[210:211], v[60:61], v[22:23]
	ds_write2st64_b32 v113, v48, v46 offset0:72 offset1:73
	v_add_f32_e32 v38, v38, v39
	v_add_f32_e32 v39, v40, v41
	v_pk_mul_f32 v[22:23], v[32:33], v[36:37]
	v_pk_mul_f32 v[24:25], v[32:33], v[20:21]
	ds_read_b128 v[78:81], v118 offset:37120
	global_load_dwordx4 v[196:199], v118, s[56:57]
	s_add_u32 s56, s56, s58
	s_addc_u32 s57, s57, s59
	ds_read_b128 v[50:53], v118 offset:37632
	ds_read_b128 v[70:73], v118 offset:37888
	ds_read_b128 v[74:77], v118 offset:38144
	ds_read2_b32 v[94:95], v114 offset0:160 offset1:164
	ds_write2st64_b32 v113, v38, v39 offset0:80 offset1:81
	v_add_f32_e32 v2, v2, v3
	v_add_f32_e32 v3, v4, v5
	v_pk_fma_f32 v[22:23], v[30:31], v[64:65], v[22:23]
	v_pk_fma_f32 v[24:25], v[30:31], v[18:19], v[24:25]
	ds_read_b128 v[86:89], v118 offset:38400
	global_load_dwordx4 v[200:203], v118, s[56:57]
	s_add_u32 s56, s56, s58
	s_addc_u32 s57, s57, s59
	ds_read_b128 v[54:57], v118 offset:38912
	ds_read_b128 v[66:69], v118 offset:39168
	ds_read_b128 v[82:85], v118 offset:39424
	ds_read2_b32 v[96:97], v114 offset0:192 offset1:196
	ds_write2st64_b32 v113, v2, v3 offset0:88 offset1:89
	v_add_f32_e32 v22, v22, v23
	v_add_f32_e32 v23, v24, v25
	ds_read_b128 v[42:45], v118 offset:39680
	global_load_dwordx4 v[204:207], v118, s[56:57]
	s_add_u32 s56, s56, s58
	s_addc_u32 s57, s57, s59
	ds_read_b128 v[10:13], v118 offset:40192
	ds_read_b128 v[6:9], v118 offset:40448
	ds_read_b128 v[14:17], v118 offset:40704
	ds_read2_b32 v[58:59], v114 offset0:224 offset1:228
	ds_write2st64_b32 v113, v22, v23 offset0:96 offset1:97
	s_waitcnt lgkmcnt(12)
	v_pk_mul_f32 v[22:23], v[80:81], v[36:37]
	v_pk_mul_f32 v[24:25], v[80:81], v[20:21]
	v_pk_fma_f32 v[22:23], v[78:79], v[64:65], v[22:23]
	v_pk_fma_f32 v[24:25], v[78:79], v[18:19], v[24:25]
	v_add_f32_e32 v22, v22, v23
	v_add_f32_e32 v23, v24, v25
	v_mov_b32_e32 v26, v95
	v_add_f32_dpp v22, v22, v22 row_ror:8 row_mask:0xf bank_mask:0xf bound_ctrl:1
	v_add_f32_dpp v23, v23, v23 row_ror:8 row_mask:0xf bank_mask:0xf bound_ctrl:1
	s_waitcnt lgkmcnt(7)
	v_mov_b32_e32 v32, v97
	v_add_f32_dpp v22, v22, v22 row_ror:4 row_mask:0xf bank_mask:0xf bound_ctrl:1
	v_add_f32_dpp v23, v23, v23 row_ror:4 row_mask:0xf bank_mask:0xf bound_ctrl:1
	s_nop 0
	v_add_f32_dpp v22, v22, v22 row_ror:2 row_mask:0xf bank_mask:0xf bound_ctrl:1
	v_add_f32_dpp v23, v23, v23 row_ror:2 row_mask:0xf bank_mask:0xf bound_ctrl:1
	s_nop 0
	v_add_f32_dpp v22, v22, v22 row_ror:1 row_mask:0xf bank_mask:0xf bound_ctrl:1
	v_add_f32_dpp v24, v23, v23 row_ror:1 row_mask:0xf bank_mask:0xf bound_ctrl:1
	v_pk_mul_f32 v[28:29], v[50:51], v[22:23] op_sel_hi:[1,0]
	v_pk_mul_f32 v[22:23], v[52:53], v[22:23] op_sel_hi:[1,0]
	v_pk_mul_f32 v[30:31], v[50:51], v[24:25] op_sel_hi:[1,0]
	v_pk_mul_f32 v[24:25], v[52:53], v[24:25] op_sel_hi:[1,0]
	v_pk_fma_f32 v[22:23], v[72:73], v[94:95], v[22:23] op_sel_hi:[1,0,1]
	v_pk_fma_f32 v[24:25], v[72:73], v[26:27], v[24:25] op_sel_hi:[1,0,1]
	v_pk_fma_f32 v[28:29], v[70:71], v[94:95], v[28:29] op_sel_hi:[1,0,1]
	s_waitcnt vmcnt(6)
	v_pk_fma_f32 v[22:23], v[214:215], v[36:37], v[22:23]
	v_pk_fma_f32 v[30:31], v[70:71], v[26:27], v[30:31] op_sel_hi:[1,0,1]
	v_pk_fma_f32 v[26:27], v[214:215], v[20:21], v[24:25]
	v_pk_fma_f32 v[28:29], v[212:213], v[64:65], v[28:29]
	v_pk_fma_f32 v[18:19], v[212:213], v[18:19], v[30:31]
	v_pk_mul_f32 v[20:21], v[76:77], v[22:23]
	v_pk_mul_f32 v[24:25], v[76:77], v[26:27]
	v_pk_fma_f32 v[20:21], v[74:75], v[28:29], v[20:21]
	v_pk_fma_f32 v[24:25], v[74:75], v[18:19], v[24:25]
	v_add_f32_e32 v20, v20, v21
	v_add_f32_e32 v21, v24, v25
	ds_write2st64_b32 v113, v20, v21 offset0:104 offset1:105
	v_pk_mul_f32 v[20:21], v[88:89], v[22:23]
	v_pk_mul_f32 v[24:25], v[88:89], v[26:27]
	v_pk_fma_f32 v[20:21], v[86:87], v[28:29], v[20:21]
	v_pk_fma_f32 v[24:25], v[86:87], v[18:19], v[24:25]
	v_add_f32_e32 v20, v20, v21
	v_add_f32_e32 v21, v24, v25
	s_nop 0
	v_add_f32_dpp v20, v20, v20 row_ror:8 row_mask:0xf bank_mask:0xf bound_ctrl:1
	v_add_f32_dpp v21, v21, v21 row_ror:8 row_mask:0xf bank_mask:0xf bound_ctrl:1
	s_nop 0
	v_add_f32_dpp v20, v20, v20 row_ror:4 row_mask:0xf bank_mask:0xf bound_ctrl:1
	v_add_f32_dpp v21, v21, v21 row_ror:4 row_mask:0xf bank_mask:0xf bound_ctrl:1
	s_nop 0
	v_add_f32_dpp v20, v20, v20 row_ror:2 row_mask:0xf bank_mask:0xf bound_ctrl:1
	v_add_f32_dpp v21, v21, v21 row_ror:2 row_mask:0xf bank_mask:0xf bound_ctrl:1
	s_nop 0
	v_add_f32_dpp v20, v20, v20 row_ror:1 row_mask:0xf bank_mask:0xf bound_ctrl:1
	v_add_f32_dpp v30, v21, v21 row_ror:1 row_mask:0xf bank_mask:0xf bound_ctrl:1
	v_pk_mul_f32 v[24:25], v[54:55], v[20:21] op_sel_hi:[1,0]
	v_pk_mul_f32 v[20:21], v[56:57], v[20:21] op_sel_hi:[1,0]
	v_pk_fma_f32 v[24:25], v[66:67], v[96:97], v[24:25] op_sel_hi:[1,0,1]
	v_pk_fma_f32 v[20:21], v[68:69], v[96:97], v[20:21] op_sel_hi:[1,0,1]
	s_waitcnt vmcnt(5)
	v_pk_fma_f32 v[24:25], v[216:217], v[28:29], v[24:25]
	v_pk_fma_f32 v[22:23], v[218:219], v[22:23], v[20:21]
	v_pk_mul_f32 v[20:21], v[54:55], v[30:31] op_sel_hi:[1,0]
	s_nop 0
	v_pk_fma_f32 v[20:21], v[66:67], v[32:33], v[20:21] op_sel_hi:[1,0,1]
	s_nop 0
	v_pk_fma_f32 v[20:21], v[216:217], v[18:19], v[20:21]
	v_pk_mul_f32 v[18:19], v[56:57], v[30:31] op_sel_hi:[1,0]
	s_nop 0
	v_pk_fma_f32 v[18:19], v[68:69], v[32:33], v[18:19] op_sel_hi:[1,0,1]
	s_nop 0
	v_pk_fma_f32 v[18:19], v[218:219], v[26:27], v[18:19]
	v_pk_mul_f32 v[26:27], v[84:85], v[22:23]
	v_pk_mul_f32 v[28:29], v[84:85], v[18:19]
	v_pk_fma_f32 v[26:27], v[82:83], v[24:25], v[26:27]
	v_pk_fma_f32 v[28:29], v[82:83], v[20:21], v[28:29]
	v_add_f32_e32 v26, v26, v27
	v_add_f32_e32 v27, v28, v29
	ds_write2st64_b32 v113, v26, v27 offset0:112 offset1:113
	s_waitcnt lgkmcnt(7)
	v_pk_mul_f32 v[26:27], v[44:45], v[22:23]
	v_pk_mul_f32 v[28:29], v[44:45], v[18:19]
	v_pk_fma_f32 v[26:27], v[42:43], v[24:25], v[26:27]
	v_pk_fma_f32 v[30:31], v[42:43], v[20:21], v[28:29]
	v_add_f32_e32 v26, v26, v27
	s_nop 1
	v_add_f32_dpp v26, v26, v26 row_ror:8 row_mask:0xf bank_mask:0xf bound_ctrl:1
	s_nop 1
	v_add_f32_dpp v26, v26, v26 row_ror:4 row_mask:0xf bank_mask:0xf bound_ctrl:1
	s_nop 1
	v_add_f32_dpp v26, v26, v26 row_ror:2 row_mask:0xf bank_mask:0xf bound_ctrl:1
	s_nop 1
	v_add_f32_dpp v28, v26, v26 row_ror:1 row_mask:0xf bank_mask:0xf bound_ctrl:1
	v_add_f32_e32 v26, v30, v31
	s_waitcnt lgkmcnt(3)
	v_mov_b32_e32 v30, v59
	v_pk_mul_f32 v[32:33], v[10:11], v[28:29] op_sel_hi:[1,0]
	v_add_f32_dpp v26, v26, v26 row_ror:8 row_mask:0xf bank_mask:0xf bound_ctrl:1
	v_pk_fma_f32 v[32:33], v[6:7], v[58:59], v[32:33] op_sel_hi:[1,0,1]
	v_pk_mul_f32 v[28:29], v[12:13], v[28:29] op_sel_hi:[1,0]
	v_add_f32_dpp v26, v26, v26 row_ror:4 row_mask:0xf bank_mask:0xf bound_ctrl:1
	s_waitcnt vmcnt(4)
	v_pk_fma_f32 v[24:25], v[220:221], v[24:25], v[32:33]
	v_pk_fma_f32 v[28:29], v[8:9], v[58:59], v[28:29] op_sel_hi:[1,0,1]
	v_add_f32_dpp v26, v26, v26 row_ror:2 row_mask:0xf bank_mask:0xf bound_ctrl:1
	v_pk_fma_f32 v[22:23], v[222:223], v[22:23], v[28:29]
	s_nop 0
	v_add_f32_dpp v26, v26, v26 row_ror:1 row_mask:0xf bank_mask:0xf bound_ctrl:1
	v_pk_mul_f32 v[10:11], v[10:11], v[26:27] op_sel_hi:[1,0]
	s_nop 0
	v_pk_fma_f32 v[6:7], v[6:7], v[30:31], v[10:11] op_sel_hi:[1,0,1]
	s_nop 0
	v_pk_fma_f32 v[6:7], v[220:221], v[20:21], v[6:7]
	v_pk_mul_f32 v[2:3], v[12:13], v[26:27] op_sel_hi:[1,0]
	s_nop 0
	v_pk_fma_f32 v[2:3], v[8:9], v[30:31], v[2:3] op_sel_hi:[1,0,1]
	s_nop 0
	v_pk_fma_f32 v[8:9], v[222:223], v[18:19], v[2:3]
	v_pk_mul_f32 v[2:3], v[16:17], v[22:23]
	v_pk_mul_f32 v[4:5], v[16:17], v[8:9]
	v_pk_fma_f32 v[2:3], v[14:15], v[24:25], v[2:3]
	v_pk_fma_f32 v[4:5], v[14:15], v[6:7], v[4:5]
	v_add_f32_e32 v2, v2, v3
	v_add_f32_e32 v3, v4, v5
	ds_write2st64_b32 v113, v2, v3 offset0:120 offset1:121
	s_waitcnt lgkmcnt(0)
	s_barrier
	s_cmpk_gt_u32 s4, 0x1fb
	s_cbranch_scc0 .LBB0_833
